# NSA near-tile bias gathers (cmp pass A/B + selected branch, 20 chains): 16 masked ds_read_b32 issued back-to-back, one lgkmcnt(0), then 16 fmacs, instead of read+wait+fmac per element
# speedup vs baseline: 1.1280x; 1.0113x over previous
; template <int MODE, int TM> ...
;     ...
; #pragma unroll
;     for (int kt = 0; kt < 4; ++kt) {
;       S[t][kt] = f32x4{0.f, 0.f, 0.f, 0.f};
; #pragma unroll
;       for (int ks = 0; ks < 2; ++ks) {
;         h16x8 Kf = *(const h16x8*)(Ks + (kt * 16 + col) * KP + ks * 32 + q4 * 8);
;         S[t][kt] = __builtin_amdgcn_mfma_f32_16x16x32_f16(Kf, Q[ks], S[t][kt], 0, 0, 0);
;       }
;     }
;   }
;   __builtin_amdgcn_s_setprio(0);
;   const float* bt = biasT + hd * 800;
;   float addc[2] = {0.f, 0.f}, sclc[2] = {1.f, 1.f};
; #pragma unroll
;   for (int t = 0; t < 2; ++t) {
;     if (!(TM & (1 << t))) continue;
;     const int kbase = kbase0 + 64 * t;
;     if (far[t]) {
;       const bool ok = (MODE == M_SEL) ? selbit[t] : true;
;       addc[t] = ok ? bt[799] : -1e30f;
;       sclc[t] = SCL2;
;     } else {
;       addc[t] = 0.f;
;       sclc[t] = 1.f;
;       const int kx0 = kbase + q4 * 4;
;       const int d0 = (DK == 16) ? tq - 31 - 16 * kx0 : tq - kx0;
; #pragma unroll
;       for (int kt = 0; kt < 4; ++kt)
; #pragma unroll
;         for (int j = 0; j < 4; ++j) {
;           const int dist = d0 - DK * (kt * 16 + j);
;           const int kx = kx0 + kt * 16 + j;
;           bool valid = dist >= 0;
;           if (MODE == M_WIN) valid = valid && dist < 512 && kx >= 0;
;           if (MODE == M_SEL) valid = valid && selbit[t];
;           if (DK == 16) valid = valid && kx < NCMP;
;           const int dc = dist < 0 ? 0 : (dist > 799 ? 799 : dist);
;           S[t][kt][j] = valid ? S[t][kt][j] * SCL2 + bt[dc] : -1e30f;
;         }
.LBB0_775:
	s_lshl_b32 s3, s56, 1
	s_lshl_b32 s57, s56, 7
	s_lshl_b32 s42, s56, 11
	s_cmp_ge_i32 s42, s31
	s_cselect_b64 s[42:43], -1, 0
	s_or_b32 s3, s3, 1
	s_cmp_ge_u32 s3, s28
	s_setprio 1
	ds_read_b128 v[32:35], v155 offset:12800
	ds_read_b128 v[28:31], v155 offset:12864
	s_mov_b64 s[50:51], -1
	s_cbranch_scc0 .LBB0_814
	s_waitcnt lgkmcnt(1)
	v_mfma_f32_16x16x32_f16 v[36:39], v[32:35], v[4:7], 0
	ds_read_b128 v[40:43], v155 offset:15360
	ds_read_b128 v[52:55], v155 offset:17920
	s_waitcnt lgkmcnt(2)
	v_mfma_f32_16x16x32_f16 v[48:51], v[28:31], v[8:11], v[36:39]
	s_nop 3
	ds_read_b128 v[36:39], v155 offset:15424
	s_waitcnt lgkmcnt(2)
	v_mfma_f32_16x16x32_f16 v[40:43], v[40:43], v[4:7], 0
	s_waitcnt lgkmcnt(0)
	v_mfma_f32_16x16x32_f16 v[44:47], v[36:39], v[8:11], v[40:43]
	ds_read_b128 v[36:39], v155 offset:17984
	v_mfma_f32_16x16x32_f16 v[40:43], v[52:55], v[4:7], 0
	ds_read_b128 v[52:55], v155 offset:20480
	s_waitcnt lgkmcnt(1)
	v_mfma_f32_16x16x32_f16 v[40:43], v[36:39], v[8:11], v[40:43]
	ds_read_b128 v[36:39], v155 offset:20544
	s_waitcnt lgkmcnt(1)
	v_mfma_f32_16x16x32_f16 v[52:55], v[52:55], v[4:7], 0
	s_waitcnt lgkmcnt(0)
	v_mfma_f32_16x16x32_f16 v[36:39], v[36:39], v[8:11], v[52:55]
	s_setprio 0
	s_and_b64 vcc, exec, s[42:43]
	s_cbranch_vccz .LBB0_810
	v_or_b32_e32 v0, s57, v154
	v_lshlrev_b32_e32 v0, 4, v0
	s_nop 0
	v_sub_u32_e32 v54, v124, v0
	v_cmp_lt_i32_e32 vcc, -1, v54
	v_mov_b32_e32 v53, 0xf149f2ca
	v_mov_b32_e32 v52, 0xf149f2ca
	s_and_saveexec_b64 s[50:51], vcc
	s_cbranch_execz .LBB0_779
	v_min_u32_e32 v52, 0x31f, v54
	v_lshl_add_u32 v52, v52, 2, v157
	ds_read_b32 v52, v52
.LBB0_779:
	s_or_b64 exec, exec, s[50:51]
	v_or_b32_e32 v54, 16, v0
	v_sub_u32_e32 v54, v124, v54
	v_cmp_lt_i32_e32 vcc, -1, v54
	s_and_saveexec_b64 s[50:51], vcc
	s_cbranch_execz .LBB0_781
	v_min_u32_e32 v53, 0x31f, v54
	v_lshl_add_u32 v53, v53, 2, v157
	ds_read_b32 v53, v53
.LBB0_781:
	s_or_b64 exec, exec, s[50:51]
	v_or_b32_e32 v54, 32, v0
	v_sub_u32_e32 v56, v124, v54
	v_cmp_lt_i32_e32 vcc, -1, v56
	v_mov_b32_e32 v55, 0xf149f2ca
	v_mov_b32_e32 v54, 0xf149f2ca
	s_and_saveexec_b64 s[50:51], vcc
	s_cbranch_execz .LBB0_783
	v_min_u32_e32 v54, 0x31f, v56
	v_lshl_add_u32 v54, v54, 2, v157
	ds_read_b32 v54, v54
.LBB0_783:
	s_or_b64 exec, exec, s[50:51]
	v_or_b32_e32 v56, 48, v0
	v_sub_u32_e32 v56, v124, v56
	v_cmp_lt_i32_e32 vcc, -1, v56
	s_and_saveexec_b64 s[50:51], vcc
	s_cbranch_execz .LBB0_785
	v_min_u32_e32 v55, 0x31f, v56
	v_lshl_add_u32 v55, v55, 2, v157
	ds_read_b32 v55, v55
.LBB0_785:
	s_or_b64 exec, exec, s[50:51]
	v_or_b32_e32 v56, 0x100, v0
	v_sub_u32_e32 v58, v124, v56
	v_cmp_lt_i32_e32 vcc, -1, v58
	v_mov_b32_e32 v57, 0xf149f2ca
	v_mov_b32_e32 v56, 0xf149f2ca
	s_and_saveexec_b64 s[50:51], vcc
	s_cbranch_execz .LBB0_787
	v_min_u32_e32 v56, 0x31f, v58
	v_lshl_add_u32 v56, v56, 2, v157
	ds_read_b32 v56, v56
.LBB0_787:
	s_or_b64 exec, exec, s[50:51]
	v_or_b32_e32 v58, 0x110, v0
	v_sub_u32_e32 v58, v124, v58
	v_cmp_lt_i32_e32 vcc, -1, v58
	s_and_saveexec_b64 s[50:51], vcc
	s_cbranch_execz .LBB0_789
	v_min_u32_e32 v57, 0x31f, v58
	v_lshl_add_u32 v57, v57, 2, v157
	ds_read_b32 v57, v57
.LBB0_789:
	s_or_b64 exec, exec, s[50:51]
	v_or_b32_e32 v58, 0x120, v0
	v_sub_u32_e32 v60, v124, v58
	v_cmp_lt_i32_e32 vcc, -1, v60
	v_mov_b32_e32 v59, 0xf149f2ca
	v_mov_b32_e32 v58, 0xf149f2ca
	s_and_saveexec_b64 s[50:51], vcc
	s_cbranch_execz .LBB0_791
	v_min_u32_e32 v58, 0x31f, v60
	v_lshl_add_u32 v58, v58, 2, v157
	ds_read_b32 v58, v58
.LBB0_791:
	s_or_b64 exec, exec, s[50:51]
	v_or_b32_e32 v60, 0x130, v0
	v_sub_u32_e32 v60, v124, v60
	v_cmp_lt_i32_e32 vcc, -1, v60
	s_and_saveexec_b64 s[50:51], vcc
	s_cbranch_execz .LBB0_793
	v_min_u32_e32 v59, 0x31f, v60
	v_lshl_add_u32 v59, v59, 2, v157
	ds_read_b32 v59, v59
.LBB0_793:
	s_or_b64 exec, exec, s[50:51]
	v_or_b32_e32 v60, 0x200, v0
	v_sub_u32_e32 v62, v124, v60
	v_cmp_lt_i32_e32 vcc, -1, v62
	v_mov_b32_e32 v61, 0xf149f2ca
	v_mov_b32_e32 v60, 0xf149f2ca
	s_and_saveexec_b64 s[50:51], vcc
	s_cbranch_execz .LBB0_795
	v_min_u32_e32 v60, 0x31f, v62
	v_lshl_add_u32 v60, v60, 2, v157
	ds_read_b32 v60, v60
.LBB0_795:
	s_or_b64 exec, exec, s[50:51]
	v_or_b32_e32 v62, 0x210, v0
	v_sub_u32_e32 v62, v124, v62
	v_cmp_lt_i32_e32 vcc, -1, v62
	s_and_saveexec_b64 s[50:51], vcc
	s_cbranch_execz .LBB0_797
	v_min_u32_e32 v61, 0x31f, v62
	v_lshl_add_u32 v61, v61, 2, v157
	ds_read_b32 v61, v61
.LBB0_797:
	s_or_b64 exec, exec, s[50:51]
	v_or_b32_e32 v62, 0x220, v0
	v_sub_u32_e32 v64, v124, v62
	v_cmp_lt_i32_e32 vcc, -1, v64
	v_mov_b32_e32 v63, 0xf149f2ca
	v_mov_b32_e32 v62, 0xf149f2ca
	s_and_saveexec_b64 s[50:51], vcc
	s_cbranch_execz .LBB0_799
	v_min_u32_e32 v62, 0x31f, v64
	v_lshl_add_u32 v62, v62, 2, v157
	ds_read_b32 v62, v62
.LBB0_799:
	s_or_b64 exec, exec, s[50:51]
	v_or_b32_e32 v64, 0x230, v0
	v_sub_u32_e32 v64, v124, v64
	v_cmp_lt_i32_e32 vcc, -1, v64
	s_and_saveexec_b64 s[50:51], vcc
	s_cbranch_execz .LBB0_801
	v_min_u32_e32 v63, 0x31f, v64
	v_lshl_add_u32 v63, v63, 2, v157
	ds_read_b32 v63, v63
.LBB0_801:
	s_or_b64 exec, exec, s[50:51]
	v_or_b32_e32 v64, 0x300, v0
	v_sub_u32_e32 v66, v124, v64
	v_cmp_lt_i32_e32 vcc, -1, v66
	v_mov_b32_e32 v65, 0xf149f2ca
	v_mov_b32_e32 v64, 0xf149f2ca
	s_and_saveexec_b64 s[50:51], vcc
	s_cbranch_execz .LBB0_803
	v_min_u32_e32 v64, 0x31f, v66
	v_lshl_add_u32 v64, v64, 2, v157
	ds_read_b32 v64, v64
.LBB0_803:
	s_or_b64 exec, exec, s[50:51]
	v_or_b32_e32 v66, 0x310, v0
	v_sub_u32_e32 v66, v124, v66
	v_cmp_lt_i32_e32 vcc, -1, v66
	s_and_saveexec_b64 s[50:51], vcc
	s_cbranch_execz .LBB0_805
	v_min_u32_e32 v65, 0x31f, v66
	v_lshl_add_u32 v65, v65, 2, v157
	ds_read_b32 v65, v65
.LBB0_805:
	s_or_b64 exec, exec, s[50:51]
	v_or_b32_e32 v66, 0x320, v0
	v_sub_u32_e32 v68, v124, v66
	v_cmp_lt_i32_e32 vcc, -1, v68
	v_mov_b32_e32 v67, 0xf149f2ca
	v_mov_b32_e32 v66, 0xf149f2ca
	s_and_saveexec_b64 s[50:51], vcc
	s_cbranch_execz .LBB0_807
	v_min_u32_e32 v66, 0x31f, v68
	v_lshl_add_u32 v66, v66, 2, v157
	ds_read_b32 v66, v66
.LBB0_807:
	s_or_b64 exec, exec, s[50:51]
	v_or_b32_e32 v0, 0x330, v0
	v_sub_u32_e32 v0, v124, v0
	v_cmp_lt_i32_e32 vcc, -1, v0
	s_and_saveexec_b64 s[50:51], vcc
	s_cbranch_execz .LBB0_809
	v_min_u32_e32 v0, 0x31f, v0
	v_lshl_add_u32 v0, v0, 2, v157
	ds_read_b32 v67, v0
.LBB0_809:
	s_or_b64 exec, exec, s[50:51]
	s_waitcnt lgkmcnt(0)
	v_fmac_f32_e32 v52, 0x3e38aa3b, v48
	v_fmac_f32_e32 v53, 0x3e38aa3b, v49
	v_fmac_f32_e32 v54, 0x3e38aa3b, v50
	v_fmac_f32_e32 v55, 0x3e38aa3b, v51
	v_fmac_f32_e32 v56, 0x3e38aa3b, v44
	v_fmac_f32_e32 v57, 0x3e38aa3b, v45
	v_fmac_f32_e32 v58, 0x3e38aa3b, v46
	v_fmac_f32_e32 v59, 0x3e38aa3b, v47
	v_fmac_f32_e32 v60, 0x3e38aa3b, v40
	v_fmac_f32_e32 v61, 0x3e38aa3b, v41
	v_fmac_f32_e32 v62, 0x3e38aa3b, v42
	v_fmac_f32_e32 v63, 0x3e38aa3b, v43
	v_fmac_f32_e32 v64, 0x3e38aa3b, v36
	v_fmac_f32_e32 v65, 0x3e38aa3b, v37
	v_fmac_f32_e32 v66, 0x3e38aa3b, v38
	v_fmac_f32_e32 v67, 0x3e38aa3b, v39
	s_mov_b64 s[50:51], 0

; template <int MODE, int TM> ...
;     ...
; #pragma unroll
;     for (int kt = 0; kt < 4; ++kt) {
;       S[t][kt] = f32x4{0.f, 0.f, 0.f, 0.f};
; #pragma unroll
;       for (int ks = 0; ks < 2; ++ks) {
;         h16x8 Kf = *(const h16x8*)(Ks + (kt * 16 + col) * KP + ks * 32 + q4 * 8);
;         S[t][kt] = __builtin_amdgcn_mfma_f32_16x16x32_f16(Kf, Q[ks], S[t][kt], 0, 0, 0);
;       }
;     }
;   }
;   __builtin_amdgcn_s_setprio(0);
;   const float* bt = biasT + hd * 800;
;   float addc[2] = {0.f, 0.f}, sclc[2] = {1.f, 1.f};
; #pragma unroll
;   for (int t = 0; t < 2; ++t) {
;     if (!(TM & (1 << t))) continue;
;     const int kbase = kbase0 + 64 * t;
;     if (far[t]) {
;       const bool ok = (MODE == M_SEL) ? selbit[t] : true;
;       addc[t] = ok ? bt[799] : -1e30f;
;       sclc[t] = SCL2;
;     } else {
;       addc[t] = 0.f;
;       sclc[t] = 1.f;
;       const int kx0 = kbase + q4 * 4;
;       const int d0 = (DK == 16) ? tq - 31 - 16 * kx0 : tq - kx0;
; #pragma unroll
;       for (int kt = 0; kt < 4; ++kt)
; #pragma unroll
;         for (int j = 0; j < 4; ++j) {
;           const int dist = d0 - DK * (kt * 16 + j);
;           const int kx = kx0 + kt * 16 + j;
;           bool valid = dist >= 0;
;           if (MODE == M_WIN) valid = valid && dist < 512 && kx >= 0;
;           if (MODE == M_SEL) valid = valid && selbit[t];
;           if (DK == 16) valid = valid && kx < NCMP;
;           const int dc = dist < 0 ? 0 : (dist > 799 ? 799 : dist);
;           S[t][kt][j] = valid ? S[t][kt][j] * SCL2 + bt[dc] : -1e30f;
;         }
.LBB0_814:
	s_and_b64 vcc, exec, s[50:51]
	s_cbranch_vccz .LBB0_888
	s_waitcnt lgkmcnt(1)
	v_mfma_f32_16x16x32_f16 v[32:35], v[32:35], v[4:7], 0
	ds_read_b128 v[36:39], v155 offset:15360
	ds_read_b128 v[44:47], v155 offset:17920
	ds_read_b128 v[48:51], v155 offset:33280
	s_waitcnt lgkmcnt(3)
	v_mfma_f32_16x16x32_f16 v[40:43], v[28:31], v[8:11], v[32:35]
	ds_read_b128 v[28:31], v155 offset:15424
	ds_read_b128 v[52:55], v155 offset:35840
	ds_read_b128 v[56:59], v155 offset:38400
	ds_read_b128 v[60:63], v155 offset:40960
	s_waitcnt lgkmcnt(6)
	v_mfma_f32_16x16x32_f16 v[32:35], v[36:39], v[4:7], 0
	s_waitcnt lgkmcnt(3)
	v_mfma_f32_16x16x32_f16 v[36:39], v[28:31], v[8:11], v[32:35]
	ds_read_b128 v[28:31], v155 offset:17984
	v_mfma_f32_16x16x32_f16 v[32:35], v[44:47], v[4:7], 0
	ds_read_b128 v[44:47], v155 offset:20480
	s_waitcnt lgkmcnt(1)
	v_mfma_f32_16x16x32_f16 v[32:35], v[28:31], v[8:11], v[32:35]
	ds_read_b128 v[28:31], v155 offset:20544
	s_waitcnt lgkmcnt(1)
	v_mfma_f32_16x16x32_f16 v[44:47], v[44:47], v[4:7], 0
	s_waitcnt lgkmcnt(0)
	v_mfma_f32_16x16x32_f16 v[28:31], v[28:31], v[8:11], v[44:47]
	s_nop 5
	ds_read_b128 v[44:47], v155 offset:33344
	v_mfma_f32_16x16x32_f16 v[48:51], v[48:51], v[4:7], 0
	s_waitcnt lgkmcnt(0)
	v_mfma_f32_16x16x32_f16 v[44:47], v[44:47], v[8:11], v[48:51]
	s_nop 5
	ds_read_b128 v[48:51], v155 offset:35904
	v_mfma_f32_16x16x32_f16 v[52:55], v[52:55], v[4:7], 0
	s_waitcnt lgkmcnt(0)
	v_mfma_f32_16x16x32_f16 v[48:51], v[48:51], v[8:11], v[52:55]
	s_nop 5
	ds_read_b128 v[52:55], v155 offset:38464
	v_mfma_f32_16x16x32_f16 v[56:59], v[56:59], v[4:7], 0
	s_waitcnt lgkmcnt(0)
	v_mfma_f32_16x16x32_f16 v[52:55], v[52:55], v[8:11], v[56:59]
	s_nop 5
	ds_read_b128 v[56:59], v155 offset:41024
	v_mfma_f32_16x16x32_f16 v[60:63], v[60:63], v[4:7], 0
	s_waitcnt lgkmcnt(0)
	v_mfma_f32_16x16x32_f16 v[56:59], v[56:59], v[8:11], v[60:63]
	s_setprio 0
	v_or_b32_e32 v0, s57, v154
	s_mov_b64 s[50:51], -1
	s_and_b64 vcc, exec, s[42:43]
	v_lshlrev_b32_e32 v77, 4, v0
	s_cbranch_vccz .LBB0_849
	v_sub_u32_e32 v0, v124, v77
	v_cmp_lt_i32_e32 vcc, -1, v0
	v_mov_b32_e32 v61, 0xf149f2ca
	v_mov_b32_e32 v60, 0xf149f2ca
	s_and_saveexec_b64 s[42:43], vcc
	s_cbranch_execz .LBB0_818
	v_min_u32_e32 v0, 0x31f, v0
	v_lshl_add_u32 v0, v0, 2, v157
	ds_read_b32 v60, v0
.LBB0_818:
	s_or_b64 exec, exec, s[42:43]
	v_or_b32_e32 v0, 16, v77
	v_sub_u32_e32 v0, v124, v0
	v_cmp_lt_i32_e32 vcc, -1, v0
	s_and_saveexec_b64 s[42:43], vcc
	s_cbranch_execz .LBB0_820
	v_min_u32_e32 v0, 0x31f, v0
	v_lshl_add_u32 v0, v0, 2, v157
	ds_read_b32 v61, v0
.LBB0_820:
	s_or_b64 exec, exec, s[42:43]
	v_or_b32_e32 v0, 32, v77
	v_sub_u32_e32 v0, v124, v0
	v_cmp_lt_i32_e32 vcc, -1, v0
	v_mov_b32_e32 v63, 0xf149f2ca
	v_mov_b32_e32 v62, 0xf149f2ca
	s_and_saveexec_b64 s[42:43], vcc
	s_cbranch_execz .LBB0_822
	v_min_u32_e32 v0, 0x31f, v0
	v_lshl_add_u32 v0, v0, 2, v157
	ds_read_b32 v62, v0
.LBB0_822:
	s_or_b64 exec, exec, s[42:43]
	v_or_b32_e32 v0, 48, v77
	v_sub_u32_e32 v0, v124, v0
	v_cmp_lt_i32_e32 vcc, -1, v0
	s_and_saveexec_b64 s[42:43], vcc
	s_cbranch_execz .LBB0_824
	v_min_u32_e32 v0, 0x31f, v0
	v_lshl_add_u32 v0, v0, 2, v157
	ds_read_b32 v63, v0
.LBB0_824:
	s_or_b64 exec, exec, s[42:43]
	v_or_b32_e32 v0, 0x100, v77
	v_sub_u32_e32 v0, v124, v0
	v_cmp_lt_i32_e32 vcc, -1, v0
	v_mov_b32_e32 v65, 0xf149f2ca
	v_mov_b32_e32 v64, 0xf149f2ca
	s_and_saveexec_b64 s[42:43], vcc
	s_cbranch_execz .LBB0_826
	v_min_u32_e32 v0, 0x31f, v0
	v_lshl_add_u32 v0, v0, 2, v157
	ds_read_b32 v64, v0
.LBB0_826:
	s_or_b64 exec, exec, s[42:43]
	v_or_b32_e32 v0, 0x110, v77
	v_sub_u32_e32 v0, v124, v0
	v_cmp_lt_i32_e32 vcc, -1, v0
	s_and_saveexec_b64 s[42:43], vcc
	s_cbranch_execz .LBB0_828
	v_min_u32_e32 v0, 0x31f, v0
	v_lshl_add_u32 v0, v0, 2, v157
	ds_read_b32 v65, v0
; template <int MODE, int TM> ...
;     ...
;       const int kx0 = kbase + q4 * 4;
;       const int d0 = (DK == 16) ? tq - 31 - 16 * kx0 : tq - kx0;
; #pragma unroll
;       for (int kt = 0; kt < 4; ++kt)
; #pragma unroll
;         for (int j = 0; j < 4; ++j) {
;           const int dist = d0 - DK * (kt * 16 + j);
;           const int kx = kx0 + kt * 16 + j;
;           bool valid = dist >= 0;
;           if (MODE == M_WIN) valid = valid && dist < 512 && kx >= 0;
;           if (MODE == M_SEL) valid = valid && selbit[t];
;           if (DK == 16) valid = valid && kx < NCMP;
;           const int dc = dist < 0 ? 0 : (dist > 799 ? 799 : dist);
;           S[t][kt][j] = valid ? S[t][kt][j] * SCL2 + bt[dc] : -1e30f;
;         }
.LBB0_828:
	s_or_b64 exec, exec, s[42:43]
	v_or_b32_e32 v0, 0x120, v77
	v_sub_u32_e32 v0, v124, v0
	v_cmp_lt_i32_e32 vcc, -1, v0
	v_mov_b32_e32 v67, 0xf149f2ca
	v_mov_b32_e32 v66, 0xf149f2ca
	s_and_saveexec_b64 s[42:43], vcc
	s_cbranch_execz .LBB0_830
	v_min_u32_e32 v0, 0x31f, v0
	v_lshl_add_u32 v0, v0, 2, v157
	ds_read_b32 v66, v0
.LBB0_830:
	s_or_b64 exec, exec, s[42:43]
	v_or_b32_e32 v0, 0x130, v77
	v_sub_u32_e32 v0, v124, v0
	v_cmp_lt_i32_e32 vcc, -1, v0
	s_and_saveexec_b64 s[42:43], vcc
	s_cbranch_execz .LBB0_832
	v_min_u32_e32 v0, 0x31f, v0
	v_lshl_add_u32 v0, v0, 2, v157
	ds_read_b32 v67, v0
.LBB0_832:
	s_or_b64 exec, exec, s[42:43]
	v_or_b32_e32 v0, 0x200, v77
	v_sub_u32_e32 v0, v124, v0
	v_cmp_lt_i32_e32 vcc, -1, v0
	v_mov_b32_e32 v69, 0xf149f2ca
	v_mov_b32_e32 v68, 0xf149f2ca
	s_and_saveexec_b64 s[42:43], vcc
	s_cbranch_execz .LBB0_834
	v_min_u32_e32 v0, 0x31f, v0
	v_lshl_add_u32 v0, v0, 2, v157
	ds_read_b32 v68, v0
.LBB0_834:
	s_or_b64 exec, exec, s[42:43]
	v_or_b32_e32 v0, 0x210, v77
	v_sub_u32_e32 v0, v124, v0
	v_cmp_lt_i32_e32 vcc, -1, v0
	s_and_saveexec_b64 s[42:43], vcc
	s_cbranch_execz .LBB0_836
	v_min_u32_e32 v0, 0x31f, v0
	v_lshl_add_u32 v0, v0, 2, v157
	ds_read_b32 v69, v0
.LBB0_836:
	s_or_b64 exec, exec, s[42:43]
	v_or_b32_e32 v0, 0x220, v77
	v_sub_u32_e32 v0, v124, v0
	v_cmp_lt_i32_e32 vcc, -1, v0
	v_mov_b32_e32 v71, 0xf149f2ca
	v_mov_b32_e32 v70, 0xf149f2ca
	s_and_saveexec_b64 s[42:43], vcc
	s_cbranch_execz .LBB0_838
	v_min_u32_e32 v0, 0x31f, v0
	v_lshl_add_u32 v0, v0, 2, v157
	ds_read_b32 v70, v0
.LBB0_838:
	s_or_b64 exec, exec, s[42:43]
	v_or_b32_e32 v0, 0x230, v77
	v_sub_u32_e32 v0, v124, v0
	v_cmp_lt_i32_e32 vcc, -1, v0
	s_and_saveexec_b64 s[42:43], vcc
	s_cbranch_execz .LBB0_840
	v_min_u32_e32 v0, 0x31f, v0
	v_lshl_add_u32 v0, v0, 2, v157
	ds_read_b32 v71, v0
.LBB0_840:
	s_or_b64 exec, exec, s[42:43]
	v_or_b32_e32 v0, 0x300, v77
	v_sub_u32_e32 v0, v124, v0
	v_cmp_lt_i32_e32 vcc, -1, v0
	v_mov_b32_e32 v73, 0xf149f2ca
	v_mov_b32_e32 v72, 0xf149f2ca
	s_and_saveexec_b64 s[42:43], vcc
	s_cbranch_execz .LBB0_842
	v_min_u32_e32 v0, 0x31f, v0
	v_lshl_add_u32 v0, v0, 2, v157
	ds_read_b32 v72, v0
.LBB0_842:
	s_or_b64 exec, exec, s[42:43]
	v_or_b32_e32 v0, 0x310, v77
	v_sub_u32_e32 v0, v124, v0
	v_cmp_lt_i32_e32 vcc, -1, v0
	s_and_saveexec_b64 s[42:43], vcc
	s_cbranch_execz .LBB0_844
	v_min_u32_e32 v0, 0x31f, v0
	v_lshl_add_u32 v0, v0, 2, v157
	ds_read_b32 v73, v0
.LBB0_844:
	s_or_b64 exec, exec, s[42:43]
	v_or_b32_e32 v0, 0x320, v77
	v_sub_u32_e32 v0, v124, v0
	v_cmp_lt_i32_e32 vcc, -1, v0
	v_mov_b32_e32 v75, 0xf149f2ca
	v_mov_b32_e32 v74, 0xf149f2ca
	s_and_saveexec_b64 s[42:43], vcc
	s_cbranch_execz .LBB0_846
	v_min_u32_e32 v0, 0x31f, v0
	v_lshl_add_u32 v0, v0, 2, v157
	ds_read_b32 v74, v0
.LBB0_846:
	s_or_b64 exec, exec, s[42:43]
	v_or_b32_e32 v0, 0x330, v77
	v_sub_u32_e32 v0, v124, v0
	v_cmp_lt_i32_e32 vcc, -1, v0
	s_and_saveexec_b64 s[42:43], vcc
	s_cbranch_execz .LBB0_848
	v_min_u32_e32 v0, 0x31f, v0
	v_lshl_add_u32 v0, v0, 2, v157
	ds_read_b32 v75, v0
.LBB0_848:
	s_or_b64 exec, exec, s[42:43]
	s_waitcnt lgkmcnt(0)
	v_fmac_f32_e32 v60, 0x3e38aa3b, v40
	v_fmac_f32_e32 v61, 0x3e38aa3b, v41
	v_fmac_f32_e32 v62, 0x3e38aa3b, v42
	v_fmac_f32_e32 v63, 0x3e38aa3b, v43
	v_fmac_f32_e32 v64, 0x3e38aa3b, v36
	v_fmac_f32_e32 v65, 0x3e38aa3b, v37
	v_fmac_f32_e32 v66, 0x3e38aa3b, v38
	v_fmac_f32_e32 v67, 0x3e38aa3b, v39
	v_fmac_f32_e32 v68, 0x3e38aa3b, v32
	v_fmac_f32_e32 v69, 0x3e38aa3b, v33
	v_fmac_f32_e32 v70, 0x3e38aa3b, v34
	v_fmac_f32_e32 v71, 0x3e38aa3b, v35
	v_fmac_f32_e32 v72, 0x3e38aa3b, v28
	v_fmac_f32_e32 v73, 0x3e38aa3b, v29
	v_fmac_f32_e32 v74, 0x3e38aa3b, v30
	v_fmac_f32_e32 v75, 0x3e38aa3b, v31
	s_mov_b64 s[50:51], 0

; template <int MODE, int TM> ...
;     ...
;       const int kx0 = kbase + q4 * 4;
;       const int d0 = (DK == 16) ? tq - 31 - 16 * kx0 : tq - kx0;
; #pragma unroll
;       for (int kt = 0; kt < 4; ++kt)
; #pragma unroll
;         for (int j = 0; j < 4; ++j) {
;           const int dist = d0 - DK * (kt * 16 + j);
;           const int kx = kx0 + kt * 16 + j;
;           bool valid = dist >= 0;
;           if (MODE == M_WIN) valid = valid && dist < 512 && kx >= 0;
;           if (MODE == M_SEL) valid = valid && selbit[t];
;           if (DK == 16) valid = valid && kx < NCMP;
;           const int dc = dist < 0 ? 0 : (dist > 799 ? 799 : dist);
;           S[t][kt][j] = valid ? S[t][kt][j] * SCL2 + bt[dc] : -1e30f;
;         }
.LBB0_852:
	v_or_b32_e32 v60, 0x400, v77
	v_sub_u32_e32 v62, v124, v60
	v_cmp_lt_i32_e32 vcc, -1, v62
	v_mov_b32_e32 v61, 0xf149f2ca
	v_mov_b32_e32 v60, 0xf149f2ca
	s_and_saveexec_b64 s[42:43], vcc
	s_cbranch_execz .LBB0_854
	v_min_u32_e32 v60, 0x31f, v62
	v_lshl_add_u32 v60, v60, 2, v157
	ds_read_b32 v60, v60
.LBB0_854:
	s_or_b64 exec, exec, s[42:43]
	v_or_b32_e32 v62, 0x410, v77
	v_sub_u32_e32 v62, v124, v62
	v_cmp_lt_i32_e32 vcc, -1, v62
	s_and_saveexec_b64 s[42:43], vcc
	s_cbranch_execz .LBB0_856
	v_min_u32_e32 v61, 0x31f, v62
	v_lshl_add_u32 v61, v61, 2, v157
	ds_read_b32 v61, v61
.LBB0_856:
	s_or_b64 exec, exec, s[42:43]
	v_or_b32_e32 v62, 0x420, v77
	v_sub_u32_e32 v64, v124, v62
	v_cmp_lt_i32_e32 vcc, -1, v64
	v_mov_b32_e32 v63, 0xf149f2ca
	v_mov_b32_e32 v62, 0xf149f2ca
	s_and_saveexec_b64 s[42:43], vcc
	s_cbranch_execz .LBB0_858
	v_min_u32_e32 v62, 0x31f, v64
	v_lshl_add_u32 v62, v62, 2, v157
	ds_read_b32 v62, v62
.LBB0_858:
	s_or_b64 exec, exec, s[42:43]
	v_or_b32_e32 v64, 0x430, v77
	v_sub_u32_e32 v64, v124, v64
	v_cmp_lt_i32_e32 vcc, -1, v64
	s_and_saveexec_b64 s[42:43], vcc
	s_cbranch_execz .LBB0_860
	v_min_u32_e32 v63, 0x31f, v64
	v_lshl_add_u32 v63, v63, 2, v157
	ds_read_b32 v63, v63
.LBB0_860:
	s_or_b64 exec, exec, s[42:43]
	v_or_b32_e32 v64, 0x500, v77
	v_sub_u32_e32 v66, v124, v64
	v_cmp_lt_i32_e32 vcc, -1, v66
	v_mov_b32_e32 v65, 0xf149f2ca
	v_mov_b32_e32 v64, 0xf149f2ca
	s_and_saveexec_b64 s[42:43], vcc
	s_cbranch_execz .LBB0_862
	v_min_u32_e32 v64, 0x31f, v66
	v_lshl_add_u32 v64, v64, 2, v157
	ds_read_b32 v64, v64
.LBB0_862:
	s_or_b64 exec, exec, s[42:43]
	v_or_b32_e32 v66, 0x510, v77
	v_sub_u32_e32 v66, v124, v66
	v_cmp_lt_i32_e32 vcc, -1, v66
	s_and_saveexec_b64 s[42:43], vcc
	s_cbranch_execz .LBB0_864
	v_min_u32_e32 v65, 0x31f, v66
	v_lshl_add_u32 v65, v65, 2, v157
	ds_read_b32 v65, v65
.LBB0_864:
	s_or_b64 exec, exec, s[42:43]
	v_or_b32_e32 v66, 0x520, v77
	v_sub_u32_e32 v68, v124, v66
	v_cmp_lt_i32_e32 vcc, -1, v68
	v_mov_b32_e32 v67, 0xf149f2ca
	v_mov_b32_e32 v66, 0xf149f2ca
	s_and_saveexec_b64 s[42:43], vcc
	s_cbranch_execz .LBB0_866
	v_min_u32_e32 v66, 0x31f, v68
	v_lshl_add_u32 v66, v66, 2, v157
	ds_read_b32 v66, v66
.LBB0_866:
	s_or_b64 exec, exec, s[42:43]
	v_or_b32_e32 v68, 0x530, v77
	v_sub_u32_e32 v68, v124, v68
	v_cmp_lt_i32_e32 vcc, -1, v68
	s_and_saveexec_b64 s[42:43], vcc
	s_cbranch_execz .LBB0_868
	v_min_u32_e32 v67, 0x31f, v68
	v_lshl_add_u32 v67, v67, 2, v157
	ds_read_b32 v67, v67
.LBB0_868:
	s_or_b64 exec, exec, s[42:43]
	v_or_b32_e32 v68, 0x600, v77
	v_sub_u32_e32 v70, v124, v68
	v_cmp_lt_i32_e32 vcc, -1, v70
	v_mov_b32_e32 v69, 0xf149f2ca
	v_mov_b32_e32 v68, 0xf149f2ca
	s_and_saveexec_b64 s[42:43], vcc
	s_cbranch_execz .LBB0_870
	v_min_u32_e32 v68, 0x31f, v70
	v_lshl_add_u32 v68, v68, 2, v157
	ds_read_b32 v68, v68
.LBB0_870:
	s_or_b64 exec, exec, s[42:43]
	v_or_b32_e32 v70, 0x610, v77
	v_sub_u32_e32 v70, v124, v70
	v_cmp_lt_i32_e32 vcc, -1, v70
	s_and_saveexec_b64 s[42:43], vcc
	s_cbranch_execz .LBB0_872
	v_min_u32_e32 v69, 0x31f, v70
	v_lshl_add_u32 v69, v69, 2, v157
	ds_read_b32 v69, v69
.LBB0_872:
	s_or_b64 exec, exec, s[42:43]
	v_or_b32_e32 v70, 0x620, v77
	v_sub_u32_e32 v72, v124, v70
	v_cmp_lt_i32_e32 vcc, -1, v72
	v_mov_b32_e32 v71, 0xf149f2ca
	v_mov_b32_e32 v70, 0xf149f2ca
	s_and_saveexec_b64 s[42:43], vcc
	s_cbranch_execz .LBB0_874
	v_min_u32_e32 v70, 0x31f, v72
	v_lshl_add_u32 v70, v70, 2, v157
	ds_read_b32 v70, v70
.LBB0_874:
	s_or_b64 exec, exec, s[42:43]
	v_or_b32_e32 v72, 0x630, v77
	v_sub_u32_e32 v72, v124, v72
	v_cmp_lt_i32_e32 vcc, -1, v72
	s_and_saveexec_b64 s[42:43], vcc
	s_cbranch_execz .LBB0_876
	v_min_u32_e32 v71, 0x31f, v72
	v_lshl_add_u32 v71, v71, 2, v157
	ds_read_b32 v71, v71
.LBB0_876:
	s_or_b64 exec, exec, s[42:43]
	v_or_b32_e32 v72, 0x700, v77
	v_sub_u32_e32 v74, v124, v72
	v_cmp_lt_i32_e32 vcc, -1, v74
	v_mov_b32_e32 v73, 0xf149f2ca
	v_mov_b32_e32 v72, 0xf149f2ca
	s_and_saveexec_b64 s[42:43], vcc
	s_cbranch_execz .LBB0_878
	v_min_u32_e32 v72, 0x31f, v74
	v_lshl_add_u32 v72, v72, 2, v157
	ds_read_b32 v72, v72
.LBB0_878:
	s_or_b64 exec, exec, s[42:43]
	v_or_b32_e32 v74, 0x710, v77
	v_sub_u32_e32 v74, v124, v74
	v_cmp_lt_i32_e32 vcc, -1, v74
	s_and_saveexec_b64 s[42:43], vcc
	s_cbranch_execz .LBB0_880
	v_min_u32_e32 v73, 0x31f, v74
	v_lshl_add_u32 v73, v73, 2, v157
	ds_read_b32 v73, v73
.LBB0_880:
	s_or_b64 exec, exec, s[42:43]
	v_or_b32_e32 v74, 0x720, v77
	v_sub_u32_e32 v78, v124, v74
	v_cmp_lt_i32_e32 vcc, -1, v78
	v_mov_b32_e32 v75, 0xf149f2ca
	v_mov_b32_e32 v74, 0xf149f2ca
	s_and_saveexec_b64 s[42:43], vcc
	s_cbranch_execz .LBB0_882
	v_min_u32_e32 v74, 0x31f, v78
	v_lshl_add_u32 v74, v74, 2, v157
	ds_read_b32 v74, v74
.LBB0_882:
	s_or_b64 exec, exec, s[42:43]
	v_or_b32_e32 v77, 0x730, v77
	v_sub_u32_e32 v77, v124, v77
	v_cmp_lt_i32_e32 vcc, -1, v77
	s_and_saveexec_b64 s[42:43], vcc
	s_cbranch_execz .LBB0_884
	v_min_u32_e32 v75, 0x31f, v77
	v_lshl_add_u32 v75, v75, 2, v157
	ds_read_b32 v75, v75
.LBB0_884:
	s_or_b64 exec, exec, s[42:43]
	s_waitcnt lgkmcnt(0)
	v_fmac_f32_e32 v60, 0x3e38aa3b, v44
	v_fmac_f32_e32 v61, 0x3e38aa3b, v45
	v_fmac_f32_e32 v62, 0x3e38aa3b, v46
	v_fmac_f32_e32 v63, 0x3e38aa3b, v47
	v_fmac_f32_e32 v64, 0x3e38aa3b, v48
	v_fmac_f32_e32 v65, 0x3e38aa3b, v49
	v_fmac_f32_e32 v66, 0x3e38aa3b, v50
	v_fmac_f32_e32 v67, 0x3e38aa3b, v51
	v_fmac_f32_e32 v68, 0x3e38aa3b, v52
	v_fmac_f32_e32 v69, 0x3e38aa3b, v53
	v_fmac_f32_e32 v70, 0x3e38aa3b, v54
	v_fmac_f32_e32 v71, 0x3e38aa3b, v55
	v_fmac_f32_e32 v72, 0x3e38aa3b, v56
	v_fmac_f32_e32 v73, 0x3e38aa3b, v57
	v_fmac_f32_e32 v74, 0x3e38aa3b, v58
	v_fmac_f32_e32 v75, 0x3e38aa3b, v59
	s_mov_b64 s[42:43], 0
	s_waitcnt lgkmcnt(0)
	v_mov_b64_e32 v[78:79], v[0:1]

; template <int MODE, int TM> ...
;     ...
;   for (int t = 0; t < 2; ++t) {
;     if (!(TM & (1 << t))) continue;
;     const h16* Ks = t ? Ks1 : Ks0;
; #pragma unroll
;     for (int kt = 0; kt < 4; ++kt) {
;       S[t][kt] = f32x4{0.f, 0.f, 0.f, 0.f};
; #pragma unroll
;       for (int ks = 0; ks < 2; ++ks) {
;         h16x8 Kf = *(const h16x8*)(Ks + (kt * 16 + col) * KP + ks * 32 + q4 * 8);
;         S[t][kt] = __builtin_amdgcn_mfma_f32_16x16x32_f16(Kf, Q[ks], S[t][kt], 0, 0, 0);
;       }
;     }
;   }
;   __builtin_amdgcn_s_setprio(0);
;   const float* bt = biasT + hd * 800;
;   float addc[2] = {0.f, 0.f}, sclc[2] = {1.f, 1.f};
; #pragma unroll
;   for (int t = 0; t < 2; ++t) {
;     if (!(TM & (1 << t))) continue;
;     const int kbase = kbase0 + 64 * t;
;     if (far[t]) {
;       const bool ok = (MODE == M_SEL) ? selbit[t] : true;
;       addc[t] = ok ? bt[799] : -1e30f;
;       sclc[t] = SCL2;
;     } else {
;       addc[t] = 0.f;
;       sclc[t] = 1.f;
;       const int kx0 = kbase + q4 * 4;
;       const int d0 = (DK == 16) ? tq - 31 - 16 * kx0 : tq - kx0;
; #pragma unroll
;       for (int kt = 0; kt < 4; ++kt)
; #pragma unroll
;         for (int j = 0; j < 4; ++j) {
;           const int dist = d0 - DK * (kt * 16 + j);
;           const int kx = kx0 + kt * 16 + j;
;           bool valid = dist >= 0;
;           if (MODE == M_WIN) valid = valid && dist < 512 && kx >= 0;
;           if (MODE == M_SEL) valid = valid && selbit[t];
;           if (DK == 16) valid = valid && kx < NCMP;
;           const int dc = dist < 0 ? 0 : (dist > 799 ? 799 : dist);
;           S[t][kt][j] = valid ? S[t][kt][j] * SCL2 + bt[dc] : -1e30f;
;         }
.LBB0_891:
	s_lshl_b32 s0, s2, 1
	s_lshl_b32 s3, s2, 7
	s_lshl_b32 s1, s2, 11
	s_cmp_ge_i32 s1, s31
	s_cselect_b64 s[42:43], -1, 0
	s_or_b32 s2, s0, 1
	s_cmp_lt_u32 s2, s28
	s_setprio 1
	ds_read_b128 v[32:35], v155 offset:53760
	ds_read_b128 v[28:31], v155 offset:53824
	v_cndmask_b32_e64 v0, 0, 1, s[42:43]
	s_mov_b64 s[0:1], -1
	v_cmp_ne_u32_e64 s[42:43], 1, v0
	s_cbranch_scc1 .LBB0_931
	s_waitcnt lgkmcnt(1)
	v_mfma_f32_16x16x32_f16 v[36:39], v[32:35], v[4:7], 0
	ds_read_b128 v[44:47], v155 offset:56320
	ds_read_b128 v[48:51], v155 offset:58880
	ds_read_b128 v[52:55], v155 offset:61440
	s_waitcnt lgkmcnt(3)
	v_mfma_f32_16x16x32_f16 v[40:43], v[28:31], v[8:11], v[36:39]
	s_nop 2
	ds_read_b128 v[36:39], v155 offset:56384
	s_waitcnt lgkmcnt(3)
	v_mfma_f32_16x16x32_f16 v[44:47], v[44:47], v[4:7], 0
	s_waitcnt lgkmcnt(0)
	v_mfma_f32_16x16x32_f16 v[44:47], v[36:39], v[8:11], v[44:47]
	ds_read_b128 v[36:39], v155 offset:58944
	v_mfma_f32_16x16x32_f16 v[48:51], v[48:51], v[4:7], 0
	s_waitcnt lgkmcnt(0)
	v_mfma_f32_16x16x32_f16 v[48:51], v[36:39], v[8:11], v[48:51]
	ds_read_b128 v[36:39], v155 offset:61504
	v_mfma_f32_16x16x32_f16 v[52:55], v[52:55], v[4:7], 0
	s_waitcnt lgkmcnt(0)
	v_mfma_f32_16x16x32_f16 v[52:55], v[36:39], v[8:11], v[52:55]
	s_setprio 0
	s_and_b64 vcc, exec, s[42:43]
	s_cbranch_vccnz .LBB0_926
	v_or_b32_e32 v0, s3, v154
	v_lshlrev_b32_e32 v0, 4, v0
	v_sub_u32_e32 v3, v124, v0
	v_cmp_lt_i32_e32 vcc, -1, v3
	v_mov_b32_e32 v37, 0xf149f2ca
	v_mov_b32_e32 v36, 0xf149f2ca
	s_and_saveexec_b64 s[0:1], vcc
	s_cbranch_execz .LBB0_895
	v_min_u32_e32 v3, 0x31f, v3
	v_lshl_add_u32 v3, v3, 2, v157
	ds_read_b32 v36, v3
.LBB0_895:
	s_or_b64 exec, exec, s[0:1]
	v_or_b32_e32 v3, 16, v0
	v_sub_u32_e32 v3, v124, v3
	v_cmp_lt_i32_e32 vcc, -1, v3
	s_and_saveexec_b64 s[0:1], vcc
	s_cbranch_execz .LBB0_897
	v_min_u32_e32 v3, 0x31f, v3
	v_lshl_add_u32 v3, v3, 2, v157
	ds_read_b32 v37, v3
.LBB0_897:
	s_or_b64 exec, exec, s[0:1]
	v_or_b32_e32 v3, 32, v0
	v_sub_u32_e32 v3, v124, v3
	v_cmp_lt_i32_e32 vcc, -1, v3
	v_mov_b32_e32 v39, 0xf149f2ca
	v_mov_b32_e32 v38, 0xf149f2ca
	s_and_saveexec_b64 s[0:1], vcc
	s_cbranch_execz .LBB0_899
	v_min_u32_e32 v3, 0x31f, v3
	v_lshl_add_u32 v3, v3, 2, v157
	ds_read_b32 v38, v3
.LBB0_899:
	s_or_b64 exec, exec, s[0:1]
	v_or_b32_e32 v3, 48, v0
	v_sub_u32_e32 v3, v124, v3
	v_cmp_lt_i32_e32 vcc, -1, v3
	s_and_saveexec_b64 s[0:1], vcc
	s_cbranch_execz .LBB0_901
	v_min_u32_e32 v3, 0x31f, v3
	v_lshl_add_u32 v3, v3, 2, v157
	ds_read_b32 v39, v3
.LBB0_901:
	s_or_b64 exec, exec, s[0:1]
	v_or_b32_e32 v3, 0x100, v0
	v_sub_u32_e32 v3, v124, v3
	v_cmp_lt_i32_e32 vcc, -1, v3
	v_mov_b32_e32 v57, 0xf149f2ca
	v_mov_b32_e32 v56, 0xf149f2ca
	s_and_saveexec_b64 s[0:1], vcc
	s_cbranch_execz .LBB0_903
	v_min_u32_e32 v3, 0x31f, v3
	v_lshl_add_u32 v3, v3, 2, v157
	ds_read_b32 v56, v3
.LBB0_903:
	s_or_b64 exec, exec, s[0:1]
	v_or_b32_e32 v3, 0x110, v0
	v_sub_u32_e32 v3, v124, v3
	v_cmp_lt_i32_e32 vcc, -1, v3
	s_and_saveexec_b64 s[0:1], vcc
	s_cbranch_execz .LBB0_905
	v_min_u32_e32 v3, 0x31f, v3
	v_lshl_add_u32 v3, v3, 2, v157
	ds_read_b32 v57, v3
.LBB0_905:
	s_or_b64 exec, exec, s[0:1]
	v_or_b32_e32 v3, 0x120, v0
	v_sub_u32_e32 v3, v124, v3
	v_cmp_lt_i32_e32 vcc, -1, v3
	v_mov_b32_e32 v59, 0xf149f2ca
	v_mov_b32_e32 v58, 0xf149f2ca
	s_and_saveexec_b64 s[0:1], vcc
	s_cbranch_execz .LBB0_907
	v_min_u32_e32 v3, 0x31f, v3
	v_lshl_add_u32 v3, v3, 2, v157
	ds_read_b32 v58, v3
.LBB0_907:
	s_or_b64 exec, exec, s[0:1]
	v_or_b32_e32 v3, 0x130, v0
	v_sub_u32_e32 v3, v124, v3
	v_cmp_lt_i32_e32 vcc, -1, v3
	s_and_saveexec_b64 s[0:1], vcc
	s_cbranch_execz .LBB0_909
	v_min_u32_e32 v3, 0x31f, v3
	v_lshl_add_u32 v3, v3, 2, v157
	ds_read_b32 v59, v3
.LBB0_909:
	s_or_b64 exec, exec, s[0:1]
	v_or_b32_e32 v3, 0x200, v0
	v_sub_u32_e32 v3, v124, v3
	v_cmp_lt_i32_e32 vcc, -1, v3
	v_mov_b32_e32 v61, 0xf149f2ca
	v_mov_b32_e32 v60, 0xf149f2ca
	s_and_saveexec_b64 s[0:1], vcc
	s_cbranch_execz .LBB0_911
	v_min_u32_e32 v3, 0x31f, v3
	v_lshl_add_u32 v3, v3, 2, v157
	ds_read_b32 v60, v3
.LBB0_911:
	s_or_b64 exec, exec, s[0:1]
	v_or_b32_e32 v3, 0x210, v0
	v_sub_u32_e32 v3, v124, v3
	v_cmp_lt_i32_e32 vcc, -1, v3
	s_and_saveexec_b64 s[0:1], vcc
	s_cbranch_execz .LBB0_913
	v_min_u32_e32 v3, 0x31f, v3
	v_lshl_add_u32 v3, v3, 2, v157
	ds_read_b32 v61, v3
.LBB0_913:
	s_or_b64 exec, exec, s[0:1]
	v_or_b32_e32 v3, 0x220, v0
	v_sub_u32_e32 v3, v124, v3
	v_cmp_lt_i32_e32 vcc, -1, v3
	v_mov_b32_e32 v63, 0xf149f2ca
	v_mov_b32_e32 v62, 0xf149f2ca
	s_and_saveexec_b64 s[0:1], vcc
	s_cbranch_execz .LBB0_915
	v_min_u32_e32 v3, 0x31f, v3
	v_lshl_add_u32 v3, v3, 2, v157
	ds_read_b32 v62, v3
.LBB0_915:
	s_or_b64 exec, exec, s[0:1]
	v_or_b32_e32 v3, 0x230, v0
	v_sub_u32_e32 v3, v124, v3
	v_cmp_lt_i32_e32 vcc, -1, v3
	s_and_saveexec_b64 s[0:1], vcc
	s_cbranch_execz .LBB0_917
	v_min_u32_e32 v3, 0x31f, v3
	v_lshl_add_u32 v3, v3, 2, v157
	ds_read_b32 v63, v3
.LBB0_917:
	s_or_b64 exec, exec, s[0:1]
	v_or_b32_e32 v3, 0x300, v0
	v_sub_u32_e32 v3, v124, v3
	v_cmp_lt_i32_e32 vcc, -1, v3
	v_mov_b32_e32 v65, 0xf149f2ca
	v_mov_b32_e32 v64, 0xf149f2ca
	s_and_saveexec_b64 s[0:1], vcc
	s_cbranch_execz .LBB0_919
	v_min_u32_e32 v3, 0x31f, v3
	v_lshl_add_u32 v3, v3, 2, v157
	ds_read_b32 v64, v3
.LBB0_919:
	s_or_b64 exec, exec, s[0:1]
	v_or_b32_e32 v3, 0x310, v0
	v_sub_u32_e32 v3, v124, v3
	v_cmp_lt_i32_e32 vcc, -1, v3
	s_and_saveexec_b64 s[0:1], vcc
	s_cbranch_execz .LBB0_921
	v_min_u32_e32 v3, 0x31f, v3
	v_lshl_add_u32 v3, v3, 2, v157
	ds_read_b32 v65, v3
.LBB0_921:
	s_or_b64 exec, exec, s[0:1]
	v_or_b32_e32 v3, 0x320, v0
	v_sub_u32_e32 v3, v124, v3
	v_cmp_lt_i32_e32 vcc, -1, v3
	v_mov_b32_e32 v67, 0xf149f2ca
	v_mov_b32_e32 v66, 0xf149f2ca
	s_and_saveexec_b64 s[0:1], vcc
	s_cbranch_execz .LBB0_923
	v_min_u32_e32 v3, 0x31f, v3
	v_lshl_add_u32 v3, v3, 2, v157
	ds_read_b32 v66, v3
.LBB0_923:
	s_or_b64 exec, exec, s[0:1]
	v_or_b32_e32 v0, 0x330, v0
	v_sub_u32_e32 v0, v124, v0
	v_cmp_lt_i32_e32 vcc, -1, v0
	s_and_saveexec_b64 s[0:1], vcc
	s_cbranch_execz .LBB0_925
	v_min_u32_e32 v0, 0x31f, v0
	v_lshl_add_u32 v0, v0, 2, v157
	ds_read_b32 v67, v0
.LBB0_925:
	s_or_b64 exec, exec, s[0:1]
	s_waitcnt lgkmcnt(0)
	v_fmac_f32_e32 v36, 0x3e38aa3b, v40
	v_fmac_f32_e32 v37, 0x3e38aa3b, v41
	v_fmac_f32_e32 v38, 0x3e38aa3b, v42
	v_fmac_f32_e32 v39, 0x3e38aa3b, v43
	v_fmac_f32_e32 v56, 0x3e38aa3b, v44
	v_fmac_f32_e32 v57, 0x3e38aa3b, v45
	v_fmac_f32_e32 v58, 0x3e38aa3b, v46
	v_fmac_f32_e32 v59, 0x3e38aa3b, v47
	v_fmac_f32_e32 v60, 0x3e38aa3b, v48
	v_fmac_f32_e32 v61, 0x3e38aa3b, v49
	v_fmac_f32_e32 v62, 0x3e38aa3b, v50
	v_fmac_f32_e32 v63, 0x3e38aa3b, v51
	v_fmac_f32_e32 v64, 0x3e38aa3b, v52
	v_fmac_f32_e32 v65, 0x3e38aa3b, v53
	v_fmac_f32_e32 v66, 0x3e38aa3b, v54
	v_fmac_f32_e32 v67, 0x3e38aa3b, v55
	s_mov_b64 s[0:1], 0

; template <int MODE, int TM> ...
;     ...
;   for (int t = 0; t < 2; ++t) {
;     if (!(TM & (1 << t))) continue;
;     const h16* Ks = t ? Ks1 : Ks0;
; #pragma unroll
;     for (int kt = 0; kt < 4; ++kt) {
;       S[t][kt] = f32x4{0.f, 0.f, 0.f, 0.f};
; #pragma unroll
;       for (int ks = 0; ks < 2; ++ks) {
;         h16x8 Kf = *(const h16x8*)(Ks + (kt * 16 + col) * KP + ks * 32 + q4 * 8);
;         S[t][kt] = __builtin_amdgcn_mfma_f32_16x16x32_f16(Kf, Q[ks], S[t][kt], 0, 0, 0);
;       }
;     }
;   }
;   __builtin_amdgcn_s_setprio(0);
;   const float* bt = biasT + hd * 800;
;   float addc[2] = {0.f, 0.f}, sclc[2] = {1.f, 1.f};
; #pragma unroll
;   for (int t = 0; t < 2; ++t) {
;     if (!(TM & (1 << t))) continue;
;     const int kbase = kbase0 + 64 * t;
;     if (far[t]) {
;       const bool ok = (MODE == M_SEL) ? selbit[t] : true;
;       addc[t] = ok ? bt[799] : -1e30f;
;       sclc[t] = SCL2;
;     } else {
;       addc[t] = 0.f;
;       sclc[t] = 1.f;
;       const int kx0 = kbase + q4 * 4;
;       const int d0 = (DK == 16) ? tq - 31 - 16 * kx0 : tq - kx0;
; #pragma unroll
;       for (int kt = 0; kt < 4; ++kt)
; #pragma unroll
;         for (int j = 0; j < 4; ++j) {
;           const int dist = d0 - DK * (kt * 16 + j);
;           const int kx = kx0 + kt * 16 + j;
;           bool valid = dist >= 0;
;           if (MODE == M_WIN) valid = valid && dist < 512 && kx >= 0;
;           if (MODE == M_SEL) valid = valid && selbit[t];
;           if (DK == 16) valid = valid && kx < NCMP;
;           const int dc = dist < 0 ? 0 : (dist > 799 ? 799 : dist);
;           S[t][kt][j] = valid ? S[t][kt][j] * SCL2 + bt[dc] : -1e30f;
;         }
.LBB0_931:
	s_and_b64 vcc, exec, s[0:1]
	s_cbranch_vccz .LBB0_766
	s_waitcnt lgkmcnt(1)
	v_mfma_f32_16x16x32_f16 v[32:35], v[32:35], v[4:7], 0
	ds_read_b128 v[36:39], v155 offset:56320
	ds_read_b128 v[40:43], v202 offset:5120
	ds_read_b128 v[44:47], v202 offset:7680
	s_waitcnt lgkmcnt(3)
	v_mfma_f32_16x16x32_f16 v[60:63], v[28:31], v[8:11], v[32:35]
	ds_read_b128 v[28:31], v155 offset:56384
	s_waitcnt lgkmcnt(3)
	v_mfma_f32_16x16x32_f16 v[32:35], v[36:39], v[4:7], 0
	ds_read_b128 v[36:39], v155 offset:58880
	s_waitcnt lgkmcnt(1)
	v_mfma_f32_16x16x32_f16 v[64:67], v[28:31], v[8:11], v[32:35]
	ds_read_b128 v[28:31], v155 offset:58944
	s_waitcnt lgkmcnt(1)
	v_mfma_f32_16x16x32_f16 v[32:35], v[36:39], v[4:7], 0
	ds_read_b128 v[36:39], v155 offset:61440
	s_waitcnt lgkmcnt(1)
	v_mfma_f32_16x16x32_f16 v[68:71], v[28:31], v[8:11], v[32:35]
	ds_read_b128 v[28:31], v155 offset:61504
	s_waitcnt lgkmcnt(1)
	v_mfma_f32_16x16x32_f16 v[32:35], v[36:39], v[4:7], 0
	ds_read_b128 v[36:39], v202
	s_waitcnt lgkmcnt(1)
	v_mfma_f32_16x16x32_f16 v[72:75], v[28:31], v[8:11], v[32:35]
	ds_read_b128 v[28:31], v202 offset:64
	s_waitcnt lgkmcnt(1)
	v_mfma_f32_16x16x32_f16 v[32:35], v[36:39], v[4:7], 0
	ds_read_b128 v[36:39], v202 offset:2560
	s_waitcnt lgkmcnt(1)
	v_mfma_f32_16x16x32_f16 v[32:35], v[28:31], v[8:11], v[32:35]
	ds_read_b128 v[28:31], v202 offset:2624
	s_waitcnt lgkmcnt(1)
	v_mfma_f32_16x16x32_f16 v[36:39], v[36:39], v[4:7], 0
	s_waitcnt lgkmcnt(0)
	v_mfma_f32_16x16x32_f16 v[36:39], v[28:31], v[8:11], v[36:39]
	ds_read_b128 v[28:31], v202 offset:5184
	v_mfma_f32_16x16x32_f16 v[40:43], v[40:43], v[4:7], 0
	s_waitcnt lgkmcnt(0)
	v_mfma_f32_16x16x32_f16 v[40:43], v[28:31], v[8:11], v[40:43]
	ds_read_b128 v[28:31], v202 offset:7744
	v_mfma_f32_16x16x32_f16 v[44:47], v[44:47], v[4:7], 0
	s_waitcnt lgkmcnt(0)
	v_mfma_f32_16x16x32_f16 v[44:47], v[28:31], v[8:11], v[44:47]
	s_setprio 0
	v_or_b32_e32 v3, s3, v154
	s_mov_b64 s[0:1], -1
	s_and_b64 vcc, exec, s[42:43]
	v_lshlrev_b32_e32 v81, 4, v3
	s_cbranch_vccnz .LBB0_966
	v_sub_u32_e32 v0, v124, v81
	v_cmp_lt_i32_e32 vcc, -1, v0
	v_mov_b32_e32 v29, 0xf149f2ca
	v_mov_b32_e32 v28, 0xf149f2ca
	s_and_saveexec_b64 s[0:1], vcc
	s_cbranch_execz .LBB0_935
	v_min_u32_e32 v0, 0x31f, v0
	v_lshl_add_u32 v0, v0, 2, v157
	ds_read_b32 v28, v0
.LBB0_935:
	s_or_b64 exec, exec, s[0:1]
	v_or_b32_e32 v0, 16, v81
	v_sub_u32_e32 v0, v124, v0
	v_cmp_lt_i32_e32 vcc, -1, v0
	s_and_saveexec_b64 s[0:1], vcc
	s_cbranch_execz .LBB0_937
	v_min_u32_e32 v0, 0x31f, v0
	v_lshl_add_u32 v0, v0, 2, v157
	ds_read_b32 v29, v0
.LBB0_937:
	s_or_b64 exec, exec, s[0:1]
	v_or_b32_e32 v0, 32, v81
	v_sub_u32_e32 v0, v124, v0
	v_cmp_lt_i32_e32 vcc, -1, v0
	v_mov_b32_e32 v31, 0xf149f2ca
	v_mov_b32_e32 v30, 0xf149f2ca
	s_and_saveexec_b64 s[0:1], vcc
	s_cbranch_execz .LBB0_939
	v_min_u32_e32 v0, 0x31f, v0
	v_lshl_add_u32 v0, v0, 2, v157
	ds_read_b32 v30, v0
.LBB0_939:
	s_or_b64 exec, exec, s[0:1]
	v_or_b32_e32 v0, 48, v81
	v_sub_u32_e32 v0, v124, v0
	v_cmp_lt_i32_e32 vcc, -1, v0
	s_and_saveexec_b64 s[0:1], vcc
	s_cbranch_execz .LBB0_941
	v_min_u32_e32 v0, 0x31f, v0
	v_lshl_add_u32 v0, v0, 2, v157
	ds_read_b32 v31, v0
.LBB0_941:
	s_or_b64 exec, exec, s[0:1]
	v_or_b32_e32 v0, 0x100, v81
	v_sub_u32_e32 v0, v124, v0
	v_cmp_lt_i32_e32 vcc, -1, v0
	v_mov_b32_e32 v49, 0xf149f2ca
	v_mov_b32_e32 v48, 0xf149f2ca
	s_and_saveexec_b64 s[0:1], vcc
	s_cbranch_execz .LBB0_943
	v_min_u32_e32 v0, 0x31f, v0
	v_lshl_add_u32 v0, v0, 2, v157
	ds_read_b32 v48, v0
.LBB0_943:
	s_or_b64 exec, exec, s[0:1]
	v_or_b32_e32 v0, 0x110, v81
	v_sub_u32_e32 v0, v124, v0
	v_cmp_lt_i32_e32 vcc, -1, v0
	s_and_saveexec_b64 s[0:1], vcc
	s_cbranch_execz .LBB0_945
	v_min_u32_e32 v0, 0x31f, v0
	v_lshl_add_u32 v0, v0, 2, v157
	ds_read_b32 v49, v0
; template <int MODE, int TM> ...
;     ...
;       const int kx0 = kbase + q4 * 4;
;       const int d0 = (DK == 16) ? tq - 31 - 16 * kx0 : tq - kx0;
; #pragma unroll
;       for (int kt = 0; kt < 4; ++kt)
; #pragma unroll
;         for (int j = 0; j < 4; ++j) {
;           const int dist = d0 - DK * (kt * 16 + j);
;           const int kx = kx0 + kt * 16 + j;
;           bool valid = dist >= 0;
;           if (MODE == M_WIN) valid = valid && dist < 512 && kx >= 0;
;           if (MODE == M_SEL) valid = valid && selbit[t];
;           if (DK == 16) valid = valid && kx < NCMP;
;           const int dc = dist < 0 ? 0 : (dist > 799 ? 799 : dist);
;           S[t][kt][j] = valid ? S[t][kt][j] * SCL2 + bt[dc] : -1e30f;
;         }
.LBB0_945:
	s_or_b64 exec, exec, s[0:1]
	v_or_b32_e32 v0, 0x120, v81
	v_sub_u32_e32 v0, v124, v0
	v_cmp_lt_i32_e32 vcc, -1, v0
	v_mov_b32_e32 v51, 0xf149f2ca
	v_mov_b32_e32 v50, 0xf149f2ca
	s_and_saveexec_b64 s[0:1], vcc
	s_cbranch_execz .LBB0_947
	v_min_u32_e32 v0, 0x31f, v0
	v_lshl_add_u32 v0, v0, 2, v157
	ds_read_b32 v50, v0
.LBB0_947:
	s_or_b64 exec, exec, s[0:1]
	v_or_b32_e32 v0, 0x130, v81
	v_sub_u32_e32 v0, v124, v0
	v_cmp_lt_i32_e32 vcc, -1, v0
	s_and_saveexec_b64 s[0:1], vcc
	s_cbranch_execz .LBB0_949
	v_min_u32_e32 v0, 0x31f, v0
	v_lshl_add_u32 v0, v0, 2, v157
	ds_read_b32 v51, v0
.LBB0_949:
	s_or_b64 exec, exec, s[0:1]
	v_or_b32_e32 v0, 0x200, v81
	v_sub_u32_e32 v0, v124, v0
	v_cmp_lt_i32_e32 vcc, -1, v0
	v_mov_b32_e32 v53, 0xf149f2ca
	v_mov_b32_e32 v52, 0xf149f2ca
	s_and_saveexec_b64 s[0:1], vcc
	s_cbranch_execz .LBB0_951
	v_min_u32_e32 v0, 0x31f, v0
	v_lshl_add_u32 v0, v0, 2, v157
	ds_read_b32 v52, v0
.LBB0_951:
	s_or_b64 exec, exec, s[0:1]
	v_or_b32_e32 v0, 0x210, v81
	v_sub_u32_e32 v0, v124, v0
	v_cmp_lt_i32_e32 vcc, -1, v0
	s_and_saveexec_b64 s[0:1], vcc
	s_cbranch_execz .LBB0_953
	v_min_u32_e32 v0, 0x31f, v0
	v_lshl_add_u32 v0, v0, 2, v157
	ds_read_b32 v53, v0
.LBB0_953:
	s_or_b64 exec, exec, s[0:1]
	v_or_b32_e32 v0, 0x220, v81
	v_sub_u32_e32 v0, v124, v0
	v_cmp_lt_i32_e32 vcc, -1, v0
	v_mov_b32_e32 v55, 0xf149f2ca
	v_mov_b32_e32 v54, 0xf149f2ca
	s_and_saveexec_b64 s[0:1], vcc
	s_cbranch_execz .LBB0_955
	v_min_u32_e32 v0, 0x31f, v0
	v_lshl_add_u32 v0, v0, 2, v157
	ds_read_b32 v54, v0
.LBB0_955:
	s_or_b64 exec, exec, s[0:1]
	v_or_b32_e32 v0, 0x230, v81
	v_sub_u32_e32 v0, v124, v0
	v_cmp_lt_i32_e32 vcc, -1, v0
	s_and_saveexec_b64 s[0:1], vcc
	s_cbranch_execz .LBB0_957
	v_min_u32_e32 v0, 0x31f, v0
	v_lshl_add_u32 v0, v0, 2, v157
	ds_read_b32 v55, v0
.LBB0_957:
	s_or_b64 exec, exec, s[0:1]
	v_or_b32_e32 v0, 0x300, v81
	v_sub_u32_e32 v0, v124, v0
	v_cmp_lt_i32_e32 vcc, -1, v0
	v_mov_b32_e32 v57, 0xf149f2ca
	v_mov_b32_e32 v56, 0xf149f2ca
	s_and_saveexec_b64 s[0:1], vcc
	s_cbranch_execz .LBB0_959
	v_min_u32_e32 v0, 0x31f, v0
	v_lshl_add_u32 v0, v0, 2, v157
	ds_read_b32 v56, v0
.LBB0_959:
	s_or_b64 exec, exec, s[0:1]
	v_or_b32_e32 v0, 0x310, v81
	v_sub_u32_e32 v0, v124, v0
	v_cmp_lt_i32_e32 vcc, -1, v0
	s_and_saveexec_b64 s[0:1], vcc
	s_cbranch_execz .LBB0_961
	v_min_u32_e32 v0, 0x31f, v0
	v_lshl_add_u32 v0, v0, 2, v157
	ds_read_b32 v57, v0
.LBB0_961:
	s_or_b64 exec, exec, s[0:1]
	v_or_b32_e32 v0, 0x320, v81
	v_sub_u32_e32 v0, v124, v0
	v_cmp_lt_i32_e32 vcc, -1, v0
	v_mov_b32_e32 v59, 0xf149f2ca
	v_mov_b32_e32 v58, 0xf149f2ca
	s_and_saveexec_b64 s[0:1], vcc
	s_cbranch_execz .LBB0_963
	v_min_u32_e32 v0, 0x31f, v0
	v_lshl_add_u32 v0, v0, 2, v157
	ds_read_b32 v58, v0
.LBB0_963:
	s_or_b64 exec, exec, s[0:1]
	v_or_b32_e32 v0, 0x330, v81
	v_sub_u32_e32 v0, v124, v0
	v_cmp_lt_i32_e32 vcc, -1, v0
	s_and_saveexec_b64 s[0:1], vcc
	s_cbranch_execz .LBB0_965
	v_min_u32_e32 v0, 0x31f, v0
	v_lshl_add_u32 v0, v0, 2, v157
	ds_read_b32 v59, v0
.LBB0_965:
	s_or_b64 exec, exec, s[0:1]
	s_waitcnt lgkmcnt(0)
	v_fmac_f32_e32 v28, 0x3e38aa3b, v60
	v_fmac_f32_e32 v29, 0x3e38aa3b, v61
	v_fmac_f32_e32 v30, 0x3e38aa3b, v62
	v_fmac_f32_e32 v31, 0x3e38aa3b, v63
	v_fmac_f32_e32 v48, 0x3e38aa3b, v64
	v_fmac_f32_e32 v49, 0x3e38aa3b, v65
	v_fmac_f32_e32 v50, 0x3e38aa3b, v66
	v_fmac_f32_e32 v51, 0x3e38aa3b, v67
	v_fmac_f32_e32 v52, 0x3e38aa3b, v68
	v_fmac_f32_e32 v53, 0x3e38aa3b, v69
	v_fmac_f32_e32 v54, 0x3e38aa3b, v70
	v_fmac_f32_e32 v55, 0x3e38aa3b, v71
	v_fmac_f32_e32 v56, 0x3e38aa3b, v72
	v_fmac_f32_e32 v57, 0x3e38aa3b, v73
	v_fmac_f32_e32 v58, 0x3e38aa3b, v74
	v_fmac_f32_e32 v59, 0x3e38aa3b, v75
	s_mov_b64 s[0:1], 0

; template <int MODE, int TM> ...
;     ...
;       const int kx0 = kbase + q4 * 4;
;       const int d0 = (DK == 16) ? tq - 31 - 16 * kx0 : tq - kx0;
; #pragma unroll
;       for (int kt = 0; kt < 4; ++kt)
; #pragma unroll
;         for (int j = 0; j < 4; ++j) {
;           const int dist = d0 - DK * (kt * 16 + j);
;           const int kx = kx0 + kt * 16 + j;
;           bool valid = dist >= 0;
;           if (MODE == M_WIN) valid = valid && dist < 512 && kx >= 0;
;           if (MODE == M_SEL) valid = valid && selbit[t];
;           if (DK == 16) valid = valid && kx < NCMP;
;           const int dc = dist < 0 ? 0 : (dist > 799 ? 799 : dist);
;           S[t][kt][j] = valid ? S[t][kt][j] * SCL2 + bt[dc] : -1e30f;
;         }
.LBB0_969:
	v_or_b32_e32 v60, 0x400, v81
	v_sub_u32_e32 v62, v124, v60
	v_cmp_lt_i32_e32 vcc, -1, v62
	v_mov_b32_e32 v61, 0xf149f2ca
	v_mov_b32_e32 v60, 0xf149f2ca
	s_and_saveexec_b64 s[0:1], vcc
	s_cbranch_execz .LBB0_971
	v_min_u32_e32 v60, 0x31f, v62
	v_lshl_add_u32 v60, v60, 2, v157
	ds_read_b32 v60, v60
.LBB0_971:
	s_or_b64 exec, exec, s[0:1]
	v_or_b32_e32 v62, 0x410, v81
	v_sub_u32_e32 v62, v124, v62
	v_cmp_lt_i32_e32 vcc, -1, v62
	s_and_saveexec_b64 s[0:1], vcc
	s_cbranch_execz .LBB0_973
	v_min_u32_e32 v61, 0x31f, v62
	v_lshl_add_u32 v61, v61, 2, v157
	ds_read_b32 v61, v61
.LBB0_973:
	s_or_b64 exec, exec, s[0:1]
	v_or_b32_e32 v62, 0x420, v81
	v_sub_u32_e32 v64, v124, v62
	v_cmp_lt_i32_e32 vcc, -1, v64
	v_mov_b32_e32 v63, 0xf149f2ca
	v_mov_b32_e32 v62, 0xf149f2ca
	s_and_saveexec_b64 s[0:1], vcc
	s_cbranch_execz .LBB0_975
	v_min_u32_e32 v62, 0x31f, v64
	v_lshl_add_u32 v62, v62, 2, v157
	ds_read_b32 v62, v62
.LBB0_975:
	s_or_b64 exec, exec, s[0:1]
	v_or_b32_e32 v64, 0x430, v81
	v_sub_u32_e32 v64, v124, v64
	v_cmp_lt_i32_e32 vcc, -1, v64
	s_and_saveexec_b64 s[0:1], vcc
	s_cbranch_execz .LBB0_977
	v_min_u32_e32 v63, 0x31f, v64
	v_lshl_add_u32 v63, v63, 2, v157
	ds_read_b32 v63, v63
.LBB0_977:
	s_or_b64 exec, exec, s[0:1]
	v_or_b32_e32 v64, 0x500, v81
	v_sub_u32_e32 v66, v124, v64
	v_cmp_lt_i32_e32 vcc, -1, v66
	v_mov_b32_e32 v65, 0xf149f2ca
	v_mov_b32_e32 v64, 0xf149f2ca
	s_and_saveexec_b64 s[0:1], vcc
	s_cbranch_execz .LBB0_979
	v_min_u32_e32 v64, 0x31f, v66
	v_lshl_add_u32 v64, v64, 2, v157
	ds_read_b32 v64, v64
.LBB0_979:
	s_or_b64 exec, exec, s[0:1]
	v_or_b32_e32 v66, 0x510, v81
	v_sub_u32_e32 v66, v124, v66
	v_cmp_lt_i32_e32 vcc, -1, v66
	s_and_saveexec_b64 s[0:1], vcc
	s_cbranch_execz .LBB0_981
	v_min_u32_e32 v65, 0x31f, v66
	v_lshl_add_u32 v65, v65, 2, v157
	ds_read_b32 v65, v65
.LBB0_981:
	s_or_b64 exec, exec, s[0:1]
	v_or_b32_e32 v66, 0x520, v81
	v_sub_u32_e32 v68, v124, v66
	v_cmp_lt_i32_e32 vcc, -1, v68
	v_mov_b32_e32 v67, 0xf149f2ca
	v_mov_b32_e32 v66, 0xf149f2ca
	s_and_saveexec_b64 s[0:1], vcc
	s_cbranch_execz .LBB0_983
	v_min_u32_e32 v66, 0x31f, v68
	v_lshl_add_u32 v66, v66, 2, v157
	ds_read_b32 v66, v66
.LBB0_983:
	s_or_b64 exec, exec, s[0:1]
	v_or_b32_e32 v68, 0x530, v81
	v_sub_u32_e32 v68, v124, v68
	v_cmp_lt_i32_e32 vcc, -1, v68
	s_and_saveexec_b64 s[0:1], vcc
	s_cbranch_execz .LBB0_985
	v_min_u32_e32 v67, 0x31f, v68
	v_lshl_add_u32 v67, v67, 2, v157
	ds_read_b32 v67, v67
.LBB0_985:
	s_or_b64 exec, exec, s[0:1]
	v_or_b32_e32 v68, 0x600, v81
	v_sub_u32_e32 v70, v124, v68
	v_cmp_lt_i32_e32 vcc, -1, v70
	v_mov_b32_e32 v69, 0xf149f2ca
	v_mov_b32_e32 v68, 0xf149f2ca
	s_and_saveexec_b64 s[0:1], vcc
	s_cbranch_execz .LBB0_987
	v_min_u32_e32 v68, 0x31f, v70
	v_lshl_add_u32 v68, v68, 2, v157
	ds_read_b32 v68, v68
.LBB0_987:
	s_or_b64 exec, exec, s[0:1]
	v_or_b32_e32 v70, 0x610, v81
	v_sub_u32_e32 v70, v124, v70
	v_cmp_lt_i32_e32 vcc, -1, v70
	s_and_saveexec_b64 s[0:1], vcc
	s_cbranch_execz .LBB0_989
	v_min_u32_e32 v69, 0x31f, v70
	v_lshl_add_u32 v69, v69, 2, v157
	ds_read_b32 v69, v69
.LBB0_989:
	s_or_b64 exec, exec, s[0:1]
	v_or_b32_e32 v70, 0x620, v81
	v_sub_u32_e32 v72, v124, v70
	v_cmp_lt_i32_e32 vcc, -1, v72
	v_mov_b32_e32 v71, 0xf149f2ca
	v_mov_b32_e32 v70, 0xf149f2ca
	s_and_saveexec_b64 s[0:1], vcc
	s_cbranch_execz .LBB0_991
	v_min_u32_e32 v70, 0x31f, v72
	v_lshl_add_u32 v70, v70, 2, v157
	ds_read_b32 v70, v70
.LBB0_991:
	s_or_b64 exec, exec, s[0:1]
	v_or_b32_e32 v72, 0x630, v81
	v_sub_u32_e32 v72, v124, v72
	v_cmp_lt_i32_e32 vcc, -1, v72
	s_and_saveexec_b64 s[0:1], vcc
	s_cbranch_execz .LBB0_993
	v_min_u32_e32 v71, 0x31f, v72
	v_lshl_add_u32 v71, v71, 2, v157
	ds_read_b32 v71, v71
.LBB0_993:
	s_or_b64 exec, exec, s[0:1]
	v_or_b32_e32 v72, 0x700, v81
	v_sub_u32_e32 v74, v124, v72
	v_cmp_lt_i32_e32 vcc, -1, v74
	v_mov_b32_e32 v73, 0xf149f2ca
	v_mov_b32_e32 v72, 0xf149f2ca
	s_and_saveexec_b64 s[0:1], vcc
	s_cbranch_execz .LBB0_995
	v_min_u32_e32 v72, 0x31f, v74
	v_lshl_add_u32 v72, v72, 2, v157
	ds_read_b32 v72, v72
.LBB0_995:
	s_or_b64 exec, exec, s[0:1]
	v_or_b32_e32 v74, 0x710, v81
	v_sub_u32_e32 v74, v124, v74
	v_cmp_lt_i32_e32 vcc, -1, v74
	s_and_saveexec_b64 s[0:1], vcc
	s_cbranch_execz .LBB0_997
	v_min_u32_e32 v73, 0x31f, v74
	v_lshl_add_u32 v73, v73, 2, v157
	ds_read_b32 v73, v73
.LBB0_997:
	s_or_b64 exec, exec, s[0:1]
	v_or_b32_e32 v74, 0x720, v81
	v_sub_u32_e32 v78, v124, v74
	v_cmp_lt_i32_e32 vcc, -1, v78
	v_mov_b32_e32 v75, 0xf149f2ca
	v_mov_b32_e32 v74, 0xf149f2ca
	s_and_saveexec_b64 s[0:1], vcc
	s_cbranch_execz .LBB0_999
	v_min_u32_e32 v74, 0x31f, v78
	v_lshl_add_u32 v74, v74, 2, v157
	ds_read_b32 v74, v74
.LBB0_999:
	s_or_b64 exec, exec, s[0:1]
	v_or_b32_e32 v78, 0x73, v3
	v_lshlrev_b32_e32 v3, 4, v78
	v_sub_u32_e32 v3, v124, v3
	v_cmp_lt_i32_e32 vcc, -1, v3
	v_cmp_gt_u32_e64 s[0:1], s60, v78
	s_and_b64 s[42:43], s[0:1], vcc
	s_and_saveexec_b64 s[0:1], s[42:43]
	s_cbranch_execz .LBB0_1001
	v_min_u32_e32 v3, 0x31f, v3
	v_lshl_add_u32 v3, v3, 2, v157
	ds_read_b32 v75, v3
.LBB0_1001:
	s_or_b64 exec, exec, s[0:1]
	s_waitcnt lgkmcnt(0)
	v_fmac_f32_e32 v60, 0x3e38aa3b, v32
	v_fmac_f32_e32 v61, 0x3e38aa3b, v33
	v_fmac_f32_e32 v62, 0x3e38aa3b, v34
	v_fmac_f32_e32 v63, 0x3e38aa3b, v35
	v_fmac_f32_e32 v64, 0x3e38aa3b, v36
	v_fmac_f32_e32 v65, 0x3e38aa3b, v37
	v_fmac_f32_e32 v66, 0x3e38aa3b, v38
	v_fmac_f32_e32 v67, 0x3e38aa3b, v39
	v_fmac_f32_e32 v68, 0x3e38aa3b, v40
	v_fmac_f32_e32 v69, 0x3e38aa3b, v41
	v_fmac_f32_e32 v70, 0x3e38aa3b, v42
	v_fmac_f32_e32 v71, 0x3e38aa3b, v43
	v_fmac_f32_e32 v72, 0x3e38aa3b, v44
	v_fmac_f32_e32 v73, 0x3e38aa3b, v45
	v_fmac_f32_e32 v74, 0x3e38aa3b, v46
	v_fmac_f32_e32 v75, 0x3e38aa3b, v47
	s_mov_b64 s[0:1], 0
	s_waitcnt lgkmcnt(0)
	v_mov_b64_e32 v[78:79], v[0:1]

; template <int MODE, int TM> ...
;     ...
;   for (int t = 0; t < 2; ++t) {
;     if (!(TM & (1 << t))) continue;
;     const h16* Ks = t ? Ks1 : Ks0;
; #pragma unroll
;     for (int kt = 0; kt < 4; ++kt) {
;       S[t][kt] = f32x4{0.f, 0.f, 0.f, 0.f};
; #pragma unroll
;       for (int ks = 0; ks < 2; ++ks) {
;         h16x8 Kf = *(const h16x8*)(Ks + (kt * 16 + col) * KP + ks * 32 + q4 * 8);
;         S[t][kt] = __builtin_amdgcn_mfma_f32_16x16x32_f16(Kf, Q[ks], S[t][kt], 0, 0, 0);
;       }
;     }
;   }
;   __builtin_amdgcn_s_setprio(0);
;   const float* bt = biasT + hd * 800;
;   float addc[2] = {0.f, 0.f}, sclc[2] = {1.f, 1.f};
; #pragma unroll
;   for (int t = 0; t < 2; ++t) {
;     if (!(TM & (1 << t))) continue;
;     const int kbase = kbase0 + 64 * t;
;     if (far[t]) {
;       const bool ok = (MODE == M_SEL) ? selbit[t] : true;
;       addc[t] = ok ? bt[799] : -1e30f;
;       sclc[t] = SCL2;
;     } else {
;       addc[t] = 0.f;
;       sclc[t] = 1.f;
;       const int kx0 = kbase + q4 * 4;
;       const int d0 = (DK == 16) ? tq - 31 - 16 * kx0 : tq - kx0;
; #pragma unroll
;       for (int kt = 0; kt < 4; ++kt)
; #pragma unroll
;         for (int j = 0; j < 4; ++j) {
;           const int dist = d0 - DK * (kt * 16 + j);
;           const int kx = kx0 + kt * 16 + j;
;           bool valid = dist >= 0;
;           if (MODE == M_WIN) valid = valid && dist < 512 && kx >= 0;
;           if (MODE == M_SEL) valid = valid && selbit[t];
;           if (DK == 16) valid = valid && kx < NCMP;
;           const int dc = dist < 0 ? 0 : (dist > 799 ? 799 : dist);
;           S[t][kt][j] = valid ? S[t][kt][j] * SCL2 + bt[dc] : -1e30f;
;         }
.LBB0_1047:
	s_lshl_b32 s2, s48, 1
	s_lshl_b32 s3, s48, 7
	s_lshl_b32 s42, s48, 11
	s_cmp_ge_i32 s42, s31
	s_cselect_b64 s[44:45], -1, 0
	s_or_b32 s2, s2, 1
	s_cmp_lt_u32 s2, s28
	s_cselect_b64 s[42:43], -1, 0
	s_cmp_ge_u32 s2, s28
	s_setprio 1
	ds_read_b128 v[80:83], v155 offset:12800
	ds_read_b128 v[76:79], v155 offset:12864
	s_mov_b64 s[46:47], -1
	s_cbranch_scc0 .LBB0_1086
	s_waitcnt lgkmcnt(1)
	v_mfma_f32_16x16x32_f16 v[60:63], v[80:83], v[4:7], 0
	ds_read_b128 v[64:67], v155 offset:15360
	ds_read_b128 v[84:87], v155 offset:17920
	s_waitcnt lgkmcnt(2)
	v_mfma_f32_16x16x32_f16 v[68:71], v[76:79], v[8:11], v[60:63]
	s_nop 3
	ds_read_b128 v[60:63], v155 offset:15424
	s_waitcnt lgkmcnt(2)
	v_mfma_f32_16x16x32_f16 v[64:67], v[64:67], v[4:7], 0
	s_waitcnt lgkmcnt(0)
	v_mfma_f32_16x16x32_f16 v[72:75], v[60:63], v[8:11], v[64:67]
	ds_read_b128 v[60:63], v155 offset:17984
	v_mfma_f32_16x16x32_f16 v[64:67], v[84:87], v[4:7], 0
	ds_read_b128 v[84:87], v155 offset:20480
	s_waitcnt lgkmcnt(1)
	v_mfma_f32_16x16x32_f16 v[64:67], v[60:63], v[8:11], v[64:67]
	ds_read_b128 v[60:63], v155 offset:20544
	s_waitcnt lgkmcnt(1)
	v_mfma_f32_16x16x32_f16 v[84:87], v[84:87], v[4:7], 0
	s_waitcnt lgkmcnt(0)
	v_mfma_f32_16x16x32_f16 v[60:63], v[60:63], v[8:11], v[84:87]
	s_setprio 0
	s_and_b64 vcc, exec, s[44:45]
	s_cbranch_vccz .LBB0_1082
	v_or_b32_e32 v0, s3, v154
	v_lshlrev_b32_e32 v0, 4, v0
	v_sub_u32_e32 v2, v124, v0
	v_cmp_lt_i32_e32 vcc, -1, v2
	v_mov_b32_e32 v85, 0xf149f2ca
	v_mov_b32_e32 v84, 0xf149f2ca
	s_and_saveexec_b64 s[46:47], vcc
	s_cbranch_execz .LBB0_1051
	v_min_u32_e32 v2, 0x31f, v2
	v_lshl_add_u32 v2, v2, 2, v157
	ds_read_b32 v84, v2
.LBB0_1051:
	s_or_b64 exec, exec, s[46:47]
	v_or_b32_e32 v2, 16, v0
	v_sub_u32_e32 v2, v124, v2
	v_cmp_lt_i32_e32 vcc, -1, v2
	s_and_saveexec_b64 s[46:47], vcc
	s_cbranch_execz .LBB0_1053
	v_min_u32_e32 v2, 0x31f, v2
	v_lshl_add_u32 v2, v2, 2, v157
	ds_read_b32 v85, v2
.LBB0_1053:
	s_or_b64 exec, exec, s[46:47]
	v_or_b32_e32 v2, 32, v0
	v_sub_u32_e32 v2, v124, v2
	v_cmp_lt_i32_e32 vcc, -1, v2
	v_mov_b32_e32 v87, 0xf149f2ca
	v_mov_b32_e32 v86, 0xf149f2ca
	s_and_saveexec_b64 s[46:47], vcc
	s_cbranch_execz .LBB0_1055
	v_min_u32_e32 v2, 0x31f, v2
	v_lshl_add_u32 v2, v2, 2, v157
	ds_read_b32 v86, v2
.LBB0_1055:
	s_or_b64 exec, exec, s[46:47]
	v_or_b32_e32 v2, 48, v0
	v_sub_u32_e32 v2, v124, v2
	v_cmp_lt_i32_e32 vcc, -1, v2
	s_and_saveexec_b64 s[46:47], vcc
	s_cbranch_execz .LBB0_1057
	v_min_u32_e32 v2, 0x31f, v2
	v_lshl_add_u32 v2, v2, 2, v157
	ds_read_b32 v87, v2
.LBB0_1057:
	s_or_b64 exec, exec, s[46:47]
	v_or_b32_e32 v2, 0x100, v0
	v_sub_u32_e32 v2, v124, v2
	v_cmp_lt_i32_e32 vcc, -1, v2
	v_mov_b32_e32 v89, 0xf149f2ca
	v_mov_b32_e32 v88, 0xf149f2ca
	s_and_saveexec_b64 s[46:47], vcc
	s_cbranch_execz .LBB0_1059
	v_min_u32_e32 v2, 0x31f, v2
	v_lshl_add_u32 v2, v2, 2, v157
	ds_read_b32 v88, v2
.LBB0_1059:
	s_or_b64 exec, exec, s[46:47]
	v_or_b32_e32 v2, 0x110, v0
	v_sub_u32_e32 v2, v124, v2
	v_cmp_lt_i32_e32 vcc, -1, v2
	s_and_saveexec_b64 s[46:47], vcc
	s_cbranch_execz .LBB0_1061
	v_min_u32_e32 v2, 0x31f, v2
	v_lshl_add_u32 v2, v2, 2, v157
	ds_read_b32 v89, v2
.LBB0_1061:
	s_or_b64 exec, exec, s[46:47]
	v_or_b32_e32 v2, 0x120, v0
	v_sub_u32_e32 v2, v124, v2
	v_cmp_lt_i32_e32 vcc, -1, v2
	v_mov_b32_e32 v91, 0xf149f2ca
	v_mov_b32_e32 v90, 0xf149f2ca
	s_and_saveexec_b64 s[46:47], vcc
	s_cbranch_execz .LBB0_1063
	v_min_u32_e32 v2, 0x31f, v2
	v_lshl_add_u32 v2, v2, 2, v157
	ds_read_b32 v90, v2
.LBB0_1063:
	s_or_b64 exec, exec, s[46:47]
	v_or_b32_e32 v2, 0x130, v0
	v_sub_u32_e32 v2, v124, v2
	v_cmp_lt_i32_e32 vcc, -1, v2
	s_and_saveexec_b64 s[46:47], vcc
	s_cbranch_execz .LBB0_1065
	v_min_u32_e32 v2, 0x31f, v2
	v_lshl_add_u32 v2, v2, 2, v157
	ds_read_b32 v91, v2
.LBB0_1065:
	s_or_b64 exec, exec, s[46:47]
	v_or_b32_e32 v2, 0x200, v0
	v_sub_u32_e32 v2, v124, v2
	v_cmp_lt_i32_e32 vcc, -1, v2
	v_mov_b32_e32 v93, 0xf149f2ca
	v_mov_b32_e32 v92, 0xf149f2ca
	s_and_saveexec_b64 s[46:47], vcc
	s_cbranch_execz .LBB0_1067
	v_min_u32_e32 v2, 0x31f, v2
	v_lshl_add_u32 v2, v2, 2, v157
	ds_read_b32 v92, v2
.LBB0_1067:
	s_or_b64 exec, exec, s[46:47]
	v_or_b32_e32 v2, 0x210, v0
	v_sub_u32_e32 v2, v124, v2
	v_cmp_lt_i32_e32 vcc, -1, v2
	s_and_saveexec_b64 s[46:47], vcc
	s_cbranch_execz .LBB0_1069
	v_min_u32_e32 v2, 0x31f, v2
	v_lshl_add_u32 v2, v2, 2, v157
	ds_read_b32 v93, v2
.LBB0_1069:
	s_or_b64 exec, exec, s[46:47]
	v_or_b32_e32 v2, 0x220, v0
	v_sub_u32_e32 v2, v124, v2
	v_cmp_lt_i32_e32 vcc, -1, v2
	v_mov_b32_e32 v95, 0xf149f2ca
	v_mov_b32_e32 v94, 0xf149f2ca
	s_and_saveexec_b64 s[46:47], vcc
	s_cbranch_execz .LBB0_1071
	v_min_u32_e32 v2, 0x31f, v2
	v_lshl_add_u32 v2, v2, 2, v157
	ds_read_b32 v94, v2
.LBB0_1071:
	s_or_b64 exec, exec, s[46:47]
	v_or_b32_e32 v2, 0x230, v0
	v_sub_u32_e32 v2, v124, v2
	v_cmp_lt_i32_e32 vcc, -1, v2
	s_and_saveexec_b64 s[46:47], vcc
	s_cbranch_execz .LBB0_1073
	v_min_u32_e32 v2, 0x31f, v2
	v_lshl_add_u32 v2, v2, 2, v157
	ds_read_b32 v95, v2
.LBB0_1073:
	s_or_b64 exec, exec, s[46:47]
	v_or_b32_e32 v2, 0x300, v0
	v_sub_u32_e32 v2, v124, v2
	v_cmp_lt_i32_e32 vcc, -1, v2
	v_mov_b32_e32 v97, 0xf149f2ca
	v_mov_b32_e32 v96, 0xf149f2ca
	s_and_saveexec_b64 s[46:47], vcc
	s_cbranch_execz .LBB0_1075
	v_min_u32_e32 v2, 0x31f, v2
	v_lshl_add_u32 v2, v2, 2, v157
	ds_read_b32 v96, v2
.LBB0_1075:
	s_or_b64 exec, exec, s[46:47]
	v_or_b32_e32 v2, 0x310, v0
	v_sub_u32_e32 v2, v124, v2
	v_cmp_lt_i32_e32 vcc, -1, v2
	s_and_saveexec_b64 s[46:47], vcc
	s_cbranch_execz .LBB0_1077
	v_min_u32_e32 v2, 0x31f, v2
	v_lshl_add_u32 v2, v2, 2, v157
	ds_read_b32 v97, v2
.LBB0_1077:
	s_or_b64 exec, exec, s[46:47]
	v_or_b32_e32 v2, 0x320, v0
	v_sub_u32_e32 v2, v124, v2
	v_cmp_lt_i32_e32 vcc, -1, v2
	v_mov_b32_e32 v99, 0xf149f2ca
	v_mov_b32_e32 v98, 0xf149f2ca
	s_and_saveexec_b64 s[46:47], vcc
	s_cbranch_execz .LBB0_1079
	v_min_u32_e32 v2, 0x31f, v2
	v_lshl_add_u32 v2, v2, 2, v157
	ds_read_b32 v98, v2
.LBB0_1079:
	s_or_b64 exec, exec, s[46:47]
	v_or_b32_e32 v0, 0x330, v0
	v_sub_u32_e32 v0, v124, v0
	v_cmp_lt_i32_e32 vcc, -1, v0
	s_and_saveexec_b64 s[46:47], vcc
	s_cbranch_execz .LBB0_1081
	v_min_u32_e32 v0, 0x31f, v0
	v_lshl_add_u32 v0, v0, 2, v157
	ds_read_b32 v99, v0
.LBB0_1081:
	s_or_b64 exec, exec, s[46:47]
	s_waitcnt lgkmcnt(0)
	v_fmac_f32_e32 v84, 0x3e38aa3b, v68
	v_fmac_f32_e32 v85, 0x3e38aa3b, v69
	v_fmac_f32_e32 v86, 0x3e38aa3b, v70
	v_fmac_f32_e32 v87, 0x3e38aa3b, v71
	v_fmac_f32_e32 v88, 0x3e38aa3b, v72
	v_fmac_f32_e32 v89, 0x3e38aa3b, v73
	v_fmac_f32_e32 v90, 0x3e38aa3b, v74
	v_fmac_f32_e32 v91, 0x3e38aa3b, v75
	v_fmac_f32_e32 v92, 0x3e38aa3b, v64
	v_fmac_f32_e32 v93, 0x3e38aa3b, v65
	v_fmac_f32_e32 v94, 0x3e38aa3b, v66
	v_fmac_f32_e32 v95, 0x3e38aa3b, v67
	v_fmac_f32_e32 v96, 0x3e38aa3b, v60
	v_fmac_f32_e32 v97, 0x3e38aa3b, v61
	v_fmac_f32_e32 v98, 0x3e38aa3b, v62
	v_fmac_f32_e32 v99, 0x3e38aa3b, v63
	s_mov_b64 s[46:47], 0

; template <int MODE, int TM> ...
;     ...
;   for (int t = 0; t < 2; ++t) {
;     if (!(TM & (1 << t))) continue;
;     const h16* Ks = t ? Ks1 : Ks0;
; #pragma unroll
;     for (int kt = 0; kt < 4; ++kt) {
;       S[t][kt] = f32x4{0.f, 0.f, 0.f, 0.f};
; #pragma unroll
;       for (int ks = 0; ks < 2; ++ks) {
;         h16x8 Kf = *(const h16x8*)(Ks + (kt * 16 + col) * KP + ks * 32 + q4 * 8);
;         S[t][kt] = __builtin_amdgcn_mfma_f32_16x16x32_f16(Kf, Q[ks], S[t][kt], 0, 0, 0);
;       }
;     }
;   }
;   __builtin_amdgcn_s_setprio(0);
;   const float* bt = biasT + hd * 800;
;   float addc[2] = {0.f, 0.f}, sclc[2] = {1.f, 1.f};
; #pragma unroll
;   for (int t = 0; t < 2; ++t) {
;     if (!(TM & (1 << t))) continue;
;     const int kbase = kbase0 + 64 * t;
;     if (far[t]) {
;       const bool ok = (MODE == M_SEL) ? selbit[t] : true;
;       addc[t] = ok ? bt[799] : -1e30f;
;       sclc[t] = SCL2;
;     } else {
;       addc[t] = 0.f;
;       sclc[t] = 1.f;
;       const int kx0 = kbase + q4 * 4;
;       const int d0 = (DK == 16) ? tq - 31 - 16 * kx0 : tq - kx0;
; #pragma unroll
;       for (int kt = 0; kt < 4; ++kt)
; #pragma unroll
;         for (int j = 0; j < 4; ++j) {
;           const int dist = d0 - DK * (kt * 16 + j);
;           const int kx = kx0 + kt * 16 + j;
;           bool valid = dist >= 0;
;           if (MODE == M_WIN) valid = valid && dist < 512 && kx >= 0;
;           if (MODE == M_SEL) valid = valid && selbit[t];
;           if (DK == 16) valid = valid && kx < NCMP;
;           const int dc = dist < 0 ? 0 : (dist > 799 ? 799 : dist);
;           S[t][kt][j] = valid ? S[t][kt][j] * SCL2 + bt[dc] : -1e30f;
;         }
.LBB0_1086:
	s_and_b64 vcc, exec, s[46:47]
	s_cbranch_vccz .LBB0_1160
	s_waitcnt lgkmcnt(1)
	v_mfma_f32_16x16x32_f16 v[60:63], v[80:83], v[4:7], 0
	ds_read_b128 v[64:67], v155 offset:15360
	ds_read_b128 v[80:83], v155 offset:33280
	ds_read_b128 v[84:87], v155 offset:35840
	s_waitcnt lgkmcnt(3)
	v_mfma_f32_16x16x32_f16 v[68:71], v[76:79], v[8:11], v[60:63]
	ds_read_b128 v[76:79], v155 offset:17920
	ds_read_b128 v[88:91], v155 offset:38400
	ds_read_b128 v[92:95], v155 offset:40960
	ds_read_b128 v[60:63], v155 offset:15424
	s_waitcnt lgkmcnt(6)
	v_mfma_f32_16x16x32_f16 v[64:67], v[64:67], v[4:7], 0
	s_waitcnt lgkmcnt(0)
	v_mfma_f32_16x16x32_f16 v[72:75], v[60:63], v[8:11], v[64:67]
	ds_read_b128 v[60:63], v155 offset:17984
	v_mfma_f32_16x16x32_f16 v[64:67], v[76:79], v[4:7], 0
	ds_read_b128 v[76:79], v155 offset:20480
	s_waitcnt lgkmcnt(1)
	v_mfma_f32_16x16x32_f16 v[64:67], v[60:63], v[8:11], v[64:67]
	ds_read_b128 v[60:63], v155 offset:20544
	s_waitcnt lgkmcnt(1)
	v_mfma_f32_16x16x32_f16 v[76:79], v[76:79], v[4:7], 0
	s_waitcnt lgkmcnt(0)
	v_mfma_f32_16x16x32_f16 v[60:63], v[60:63], v[8:11], v[76:79]
	s_nop 5
	ds_read_b128 v[76:79], v155 offset:33344
	v_mfma_f32_16x16x32_f16 v[80:83], v[80:83], v[4:7], 0
	s_waitcnt lgkmcnt(0)
	v_mfma_f32_16x16x32_f16 v[76:79], v[76:79], v[8:11], v[80:83]
	s_nop 5
	ds_read_b128 v[80:83], v155 offset:35904
	v_mfma_f32_16x16x32_f16 v[84:87], v[84:87], v[4:7], 0
	s_waitcnt lgkmcnt(0)
	v_mfma_f32_16x16x32_f16 v[80:83], v[80:83], v[8:11], v[84:87]
	s_nop 5
	ds_read_b128 v[84:87], v155 offset:38464
	v_mfma_f32_16x16x32_f16 v[88:91], v[88:91], v[4:7], 0
	s_waitcnt lgkmcnt(0)
	v_mfma_f32_16x16x32_f16 v[84:87], v[84:87], v[8:11], v[88:91]
	s_nop 5
	ds_read_b128 v[88:91], v155 offset:41024
	v_mfma_f32_16x16x32_f16 v[92:95], v[92:95], v[4:7], 0
	s_waitcnt lgkmcnt(0)
	v_mfma_f32_16x16x32_f16 v[88:91], v[88:91], v[8:11], v[92:95]
	s_setprio 0
	v_or_b32_e32 v0, s3, v154
	s_mov_b64 s[46:47], -1
	s_and_b64 vcc, exec, s[44:45]
	v_lshlrev_b32_e32 v2, 4, v0
	s_cbranch_vccz .LBB0_1121
	v_sub_u32_e32 v0, v124, v2
	v_cmp_lt_i32_e32 vcc, -1, v0
	v_mov_b32_e32 v93, 0xf149f2ca
	v_mov_b32_e32 v92, 0xf149f2ca
	s_and_saveexec_b64 s[44:45], vcc
	s_cbranch_execz .LBB0_1090
	v_min_u32_e32 v0, 0x31f, v0
	v_lshl_add_u32 v0, v0, 2, v157
	ds_read_b32 v92, v0
.LBB0_1090:
	s_or_b64 exec, exec, s[44:45]
	v_or_b32_e32 v0, 16, v2
	v_sub_u32_e32 v0, v124, v0
	v_cmp_lt_i32_e32 vcc, -1, v0
	s_and_saveexec_b64 s[44:45], vcc
	s_cbranch_execz .LBB0_1092
	v_min_u32_e32 v0, 0x31f, v0
	v_lshl_add_u32 v0, v0, 2, v157
	ds_read_b32 v93, v0
.LBB0_1092:
	s_or_b64 exec, exec, s[44:45]
	v_or_b32_e32 v0, 32, v2
	v_sub_u32_e32 v0, v124, v0
	v_cmp_lt_i32_e32 vcc, -1, v0
	v_mov_b32_e32 v95, 0xf149f2ca
	v_mov_b32_e32 v94, 0xf149f2ca
	s_and_saveexec_b64 s[44:45], vcc
	s_cbranch_execz .LBB0_1094
	v_min_u32_e32 v0, 0x31f, v0
	v_lshl_add_u32 v0, v0, 2, v157
	ds_read_b32 v94, v0
.LBB0_1094:
	s_or_b64 exec, exec, s[44:45]
	v_or_b32_e32 v0, 48, v2
	v_sub_u32_e32 v0, v124, v0
	v_cmp_lt_i32_e32 vcc, -1, v0
	s_and_saveexec_b64 s[44:45], vcc
	s_cbranch_execz .LBB0_1096
	v_min_u32_e32 v0, 0x31f, v0
	v_lshl_add_u32 v0, v0, 2, v157
	ds_read_b32 v95, v0
.LBB0_1096:
	s_or_b64 exec, exec, s[44:45]
	v_or_b32_e32 v0, 0x100, v2
	v_sub_u32_e32 v0, v124, v0
	v_cmp_lt_i32_e32 vcc, -1, v0
	v_mov_b32_e32 v97, 0xf149f2ca
	v_mov_b32_e32 v96, 0xf149f2ca
	s_and_saveexec_b64 s[44:45], vcc
	s_cbranch_execz .LBB0_1098
	v_min_u32_e32 v0, 0x31f, v0
	v_lshl_add_u32 v0, v0, 2, v157
	ds_read_b32 v96, v0
.LBB0_1098:
	s_or_b64 exec, exec, s[44:45]
	v_or_b32_e32 v0, 0x110, v2
	v_sub_u32_e32 v0, v124, v0
	v_cmp_lt_i32_e32 vcc, -1, v0
	s_and_saveexec_b64 s[44:45], vcc
	s_cbranch_execz .LBB0_1100
	v_min_u32_e32 v0, 0x31f, v0
	v_lshl_add_u32 v0, v0, 2, v157
	ds_read_b32 v97, v0
; template <int MODE, int TM> ...
;     ...
;       const int kx0 = kbase + q4 * 4;
;       const int d0 = (DK == 16) ? tq - 31 - 16 * kx0 : tq - kx0;
; #pragma unroll
;       for (int kt = 0; kt < 4; ++kt)
; #pragma unroll
;         for (int j = 0; j < 4; ++j) {
;           const int dist = d0 - DK * (kt * 16 + j);
;           const int kx = kx0 + kt * 16 + j;
;           bool valid = dist >= 0;
;           if (MODE == M_WIN) valid = valid && dist < 512 && kx >= 0;
;           if (MODE == M_SEL) valid = valid && selbit[t];
;           if (DK == 16) valid = valid && kx < NCMP;
;           const int dc = dist < 0 ? 0 : (dist > 799 ? 799 : dist);
;           S[t][kt][j] = valid ? S[t][kt][j] * SCL2 + bt[dc] : -1e30f;
;         }
.LBB0_1100:
	s_or_b64 exec, exec, s[44:45]
	v_or_b32_e32 v0, 0x120, v2
	v_sub_u32_e32 v0, v124, v0
	v_cmp_lt_i32_e32 vcc, -1, v0
	v_mov_b32_e32 v99, 0xf149f2ca
	v_mov_b32_e32 v98, 0xf149f2ca
	s_and_saveexec_b64 s[44:45], vcc
	s_cbranch_execz .LBB0_1102
	v_min_u32_e32 v0, 0x31f, v0
	v_lshl_add_u32 v0, v0, 2, v157
	ds_read_b32 v98, v0
.LBB0_1102:
	s_or_b64 exec, exec, s[44:45]
	v_or_b32_e32 v0, 0x130, v2
	v_sub_u32_e32 v0, v124, v0
	v_cmp_lt_i32_e32 vcc, -1, v0
	s_and_saveexec_b64 s[44:45], vcc
	s_cbranch_execz .LBB0_1104
	v_min_u32_e32 v0, 0x31f, v0
	v_lshl_add_u32 v0, v0, 2, v157
	ds_read_b32 v99, v0
.LBB0_1104:
	s_or_b64 exec, exec, s[44:45]
	v_or_b32_e32 v0, 0x200, v2
	v_sub_u32_e32 v0, v124, v0
	v_cmp_lt_i32_e32 vcc, -1, v0
	v_mov_b32_e32 v101, 0xf149f2ca
	v_mov_b32_e32 v100, 0xf149f2ca
	s_and_saveexec_b64 s[44:45], vcc
	s_cbranch_execz .LBB0_1106
	v_min_u32_e32 v0, 0x31f, v0
	v_lshl_add_u32 v0, v0, 2, v157
	ds_read_b32 v100, v0
.LBB0_1106:
	s_or_b64 exec, exec, s[44:45]
	v_or_b32_e32 v0, 0x210, v2
	v_sub_u32_e32 v0, v124, v0
	v_cmp_lt_i32_e32 vcc, -1, v0
	s_and_saveexec_b64 s[44:45], vcc
	s_cbranch_execz .LBB0_1108
	v_min_u32_e32 v0, 0x31f, v0
	v_lshl_add_u32 v0, v0, 2, v157
	ds_read_b32 v101, v0
.LBB0_1108:
	s_or_b64 exec, exec, s[44:45]
	v_or_b32_e32 v0, 0x220, v2
	v_sub_u32_e32 v0, v124, v0
	v_cmp_lt_i32_e32 vcc, -1, v0
	v_mov_b32_e32 v103, 0xf149f2ca
	v_mov_b32_e32 v102, 0xf149f2ca
	s_and_saveexec_b64 s[44:45], vcc
	s_cbranch_execz .LBB0_1110
	v_min_u32_e32 v0, 0x31f, v0
	v_lshl_add_u32 v0, v0, 2, v157
	ds_read_b32 v102, v0
.LBB0_1110:
	s_or_b64 exec, exec, s[44:45]
	v_or_b32_e32 v0, 0x230, v2
	v_sub_u32_e32 v0, v124, v0
	v_cmp_lt_i32_e32 vcc, -1, v0
	s_and_saveexec_b64 s[44:45], vcc
	s_cbranch_execz .LBB0_1112
	v_min_u32_e32 v0, 0x31f, v0
	v_lshl_add_u32 v0, v0, 2, v157
	ds_read_b32 v103, v0
.LBB0_1112:
	s_or_b64 exec, exec, s[44:45]
	v_or_b32_e32 v0, 0x300, v2
	v_sub_u32_e32 v0, v124, v0
	v_cmp_lt_i32_e32 vcc, -1, v0
	v_mov_b32_e32 v105, 0xf149f2ca
	v_mov_b32_e32 v104, 0xf149f2ca
	s_and_saveexec_b64 s[44:45], vcc
	s_cbranch_execz .LBB0_1114
	v_min_u32_e32 v0, 0x31f, v0
	v_lshl_add_u32 v0, v0, 2, v157
	ds_read_b32 v104, v0
.LBB0_1114:
	s_or_b64 exec, exec, s[44:45]
	v_or_b32_e32 v0, 0x310, v2
	v_sub_u32_e32 v0, v124, v0
	v_cmp_lt_i32_e32 vcc, -1, v0
	s_and_saveexec_b64 s[44:45], vcc
	s_cbranch_execz .LBB0_1116
	v_min_u32_e32 v0, 0x31f, v0
	v_lshl_add_u32 v0, v0, 2, v157
	ds_read_b32 v105, v0
.LBB0_1116:
	s_or_b64 exec, exec, s[44:45]
	v_or_b32_e32 v0, 0x320, v2
	v_sub_u32_e32 v0, v124, v0
	v_cmp_lt_i32_e32 vcc, -1, v0
	v_mov_b32_e32 v107, 0xf149f2ca
	v_mov_b32_e32 v106, 0xf149f2ca
	s_and_saveexec_b64 s[44:45], vcc
	s_cbranch_execz .LBB0_1118
	v_min_u32_e32 v0, 0x31f, v0
	v_lshl_add_u32 v0, v0, 2, v157
	ds_read_b32 v106, v0
.LBB0_1118:
	s_or_b64 exec, exec, s[44:45]
	v_or_b32_e32 v0, 0x330, v2
	v_sub_u32_e32 v0, v124, v0
	v_cmp_lt_i32_e32 vcc, -1, v0
	s_and_saveexec_b64 s[44:45], vcc
	s_cbranch_execz .LBB0_1120
	v_min_u32_e32 v0, 0x31f, v0
	v_lshl_add_u32 v0, v0, 2, v157
	ds_read_b32 v107, v0
.LBB0_1120:
	s_or_b64 exec, exec, s[44:45]
	s_waitcnt lgkmcnt(0)
	v_fmac_f32_e32 v92, 0x3e38aa3b, v68
	v_fmac_f32_e32 v93, 0x3e38aa3b, v69
	v_fmac_f32_e32 v94, 0x3e38aa3b, v70
	v_fmac_f32_e32 v95, 0x3e38aa3b, v71
	v_fmac_f32_e32 v96, 0x3e38aa3b, v72
	v_fmac_f32_e32 v97, 0x3e38aa3b, v73
	v_fmac_f32_e32 v98, 0x3e38aa3b, v74
	v_fmac_f32_e32 v99, 0x3e38aa3b, v75
	v_fmac_f32_e32 v100, 0x3e38aa3b, v64
	v_fmac_f32_e32 v101, 0x3e38aa3b, v65
	v_fmac_f32_e32 v102, 0x3e38aa3b, v66
	v_fmac_f32_e32 v103, 0x3e38aa3b, v67
	v_fmac_f32_e32 v104, 0x3e38aa3b, v60
	v_fmac_f32_e32 v105, 0x3e38aa3b, v61
	v_fmac_f32_e32 v106, 0x3e38aa3b, v62
	v_fmac_f32_e32 v107, 0x3e38aa3b, v63
	s_mov_b64 s[46:47], 0

; template <int MODE, int TM> ...
;     ...
;       const int kx0 = kbase + q4 * 4;
;       const int d0 = (DK == 16) ? tq - 31 - 16 * kx0 : tq - kx0;
; #pragma unroll
;       for (int kt = 0; kt < 4; ++kt)
; #pragma unroll
;         for (int j = 0; j < 4; ++j) {
;           const int dist = d0 - DK * (kt * 16 + j);
;           const int kx = kx0 + kt * 16 + j;
;           bool valid = dist >= 0;
;           if (MODE == M_WIN) valid = valid && dist < 512 && kx >= 0;
;           if (MODE == M_SEL) valid = valid && selbit[t];
;           if (DK == 16) valid = valid && kx < NCMP;
;           const int dc = dist < 0 ? 0 : (dist > 799 ? 799 : dist);
;           S[t][kt][j] = valid ? S[t][kt][j] * SCL2 + bt[dc] : -1e30f;
;         }
.LBB0_1124:
	v_or_b32_e32 v3, 0x400, v2
	v_sub_u32_e32 v3, v124, v3
	v_cmp_lt_i32_e32 vcc, -1, v3
	v_mov_b32_e32 v93, 0xf149f2ca
	v_mov_b32_e32 v92, 0xf149f2ca
	s_and_saveexec_b64 s[44:45], vcc
	s_cbranch_execz .LBB0_1126
	v_min_u32_e32 v3, 0x31f, v3
	v_lshl_add_u32 v3, v3, 2, v157
	ds_read_b32 v92, v3
.LBB0_1126:
	s_or_b64 exec, exec, s[44:45]
	v_or_b32_e32 v3, 0x410, v2
	v_sub_u32_e32 v3, v124, v3
	v_cmp_lt_i32_e32 vcc, -1, v3
	s_and_saveexec_b64 s[44:45], vcc
	s_cbranch_execz .LBB0_1128
	v_min_u32_e32 v3, 0x31f, v3
	v_lshl_add_u32 v3, v3, 2, v157
	ds_read_b32 v93, v3
.LBB0_1128:
	s_or_b64 exec, exec, s[44:45]
	v_or_b32_e32 v3, 0x420, v2
	v_sub_u32_e32 v3, v124, v3
	v_cmp_lt_i32_e32 vcc, -1, v3
	v_mov_b32_e32 v95, 0xf149f2ca
	v_mov_b32_e32 v94, 0xf149f2ca
	s_and_saveexec_b64 s[44:45], vcc
	s_cbranch_execz .LBB0_1130
	v_min_u32_e32 v3, 0x31f, v3
	v_lshl_add_u32 v3, v3, 2, v157
	ds_read_b32 v94, v3
.LBB0_1130:
	s_or_b64 exec, exec, s[44:45]
	v_or_b32_e32 v3, 0x430, v2
	v_sub_u32_e32 v3, v124, v3
	v_cmp_lt_i32_e32 vcc, -1, v3
	s_and_saveexec_b64 s[44:45], vcc
	s_cbranch_execz .LBB0_1132
	v_min_u32_e32 v3, 0x31f, v3
	v_lshl_add_u32 v3, v3, 2, v157
	ds_read_b32 v95, v3
.LBB0_1132:
	s_or_b64 exec, exec, s[44:45]
	v_or_b32_e32 v3, 0x500, v2
	v_sub_u32_e32 v3, v124, v3
	v_cmp_lt_i32_e32 vcc, -1, v3
	v_mov_b32_e32 v97, 0xf149f2ca
	v_mov_b32_e32 v96, 0xf149f2ca
	s_and_saveexec_b64 s[44:45], vcc
	s_cbranch_execz .LBB0_1134
	v_min_u32_e32 v3, 0x31f, v3
	v_lshl_add_u32 v3, v3, 2, v157
	ds_read_b32 v96, v3
.LBB0_1134:
	s_or_b64 exec, exec, s[44:45]
	v_or_b32_e32 v3, 0x510, v2
	v_sub_u32_e32 v3, v124, v3
	v_cmp_lt_i32_e32 vcc, -1, v3
	s_and_saveexec_b64 s[44:45], vcc
	s_cbranch_execz .LBB0_1136
	v_min_u32_e32 v3, 0x31f, v3
	v_lshl_add_u32 v3, v3, 2, v157
	ds_read_b32 v97, v3
.LBB0_1136:
	s_or_b64 exec, exec, s[44:45]
	v_or_b32_e32 v3, 0x520, v2
	v_sub_u32_e32 v3, v124, v3
	v_cmp_lt_i32_e32 vcc, -1, v3
	v_mov_b32_e32 v99, 0xf149f2ca
	v_mov_b32_e32 v98, 0xf149f2ca
	s_and_saveexec_b64 s[44:45], vcc
	s_cbranch_execz .LBB0_1138
	v_min_u32_e32 v3, 0x31f, v3
	v_lshl_add_u32 v3, v3, 2, v157
	ds_read_b32 v98, v3
.LBB0_1138:
	s_or_b64 exec, exec, s[44:45]
	v_or_b32_e32 v3, 0x530, v2
	v_sub_u32_e32 v3, v124, v3
	v_cmp_lt_i32_e32 vcc, -1, v3
	s_and_saveexec_b64 s[44:45], vcc
	s_cbranch_execz .LBB0_1140
	v_min_u32_e32 v3, 0x31f, v3
	v_lshl_add_u32 v3, v3, 2, v157
	ds_read_b32 v99, v3
.LBB0_1140:
	s_or_b64 exec, exec, s[44:45]
	v_or_b32_e32 v3, 0x600, v2
	v_sub_u32_e32 v3, v124, v3
	v_cmp_lt_i32_e32 vcc, -1, v3
	v_mov_b32_e32 v101, 0xf149f2ca
	v_mov_b32_e32 v100, 0xf149f2ca
	s_and_saveexec_b64 s[44:45], vcc
	s_cbranch_execz .LBB0_1142
	v_min_u32_e32 v3, 0x31f, v3
	v_lshl_add_u32 v3, v3, 2, v157
	ds_read_b32 v100, v3
.LBB0_1142:
	s_or_b64 exec, exec, s[44:45]
	v_or_b32_e32 v3, 0x610, v2
	v_sub_u32_e32 v3, v124, v3
	v_cmp_lt_i32_e32 vcc, -1, v3
	s_and_saveexec_b64 s[44:45], vcc
	s_cbranch_execz .LBB0_1144
	v_min_u32_e32 v3, 0x31f, v3
	v_lshl_add_u32 v3, v3, 2, v157
	ds_read_b32 v101, v3
.LBB0_1144:
	s_or_b64 exec, exec, s[44:45]
	v_or_b32_e32 v3, 0x620, v2
	v_sub_u32_e32 v3, v124, v3
	v_cmp_lt_i32_e32 vcc, -1, v3
	v_mov_b32_e32 v103, 0xf149f2ca
	v_mov_b32_e32 v102, 0xf149f2ca
	s_and_saveexec_b64 s[44:45], vcc
	s_cbranch_execz .LBB0_1146
	v_min_u32_e32 v3, 0x31f, v3
	v_lshl_add_u32 v3, v3, 2, v157
	ds_read_b32 v102, v3
.LBB0_1146:
	s_or_b64 exec, exec, s[44:45]
	v_or_b32_e32 v3, 0x630, v2
	v_sub_u32_e32 v3, v124, v3
	v_cmp_lt_i32_e32 vcc, -1, v3
	s_and_saveexec_b64 s[44:45], vcc
	s_cbranch_execz .LBB0_1148
	v_min_u32_e32 v3, 0x31f, v3
	v_lshl_add_u32 v3, v3, 2, v157
	ds_read_b32 v103, v3
.LBB0_1148:
	s_or_b64 exec, exec, s[44:45]
	v_or_b32_e32 v3, 0x700, v2
	v_sub_u32_e32 v3, v124, v3
	v_cmp_lt_i32_e32 vcc, -1, v3
	v_mov_b32_e32 v105, 0xf149f2ca
	v_mov_b32_e32 v104, 0xf149f2ca
	s_and_saveexec_b64 s[44:45], vcc
	s_cbranch_execz .LBB0_1150
	v_min_u32_e32 v3, 0x31f, v3
	v_lshl_add_u32 v3, v3, 2, v157
	ds_read_b32 v104, v3
.LBB0_1150:
	s_or_b64 exec, exec, s[44:45]
	v_or_b32_e32 v3, 0x710, v2
	v_sub_u32_e32 v3, v124, v3
	v_cmp_lt_i32_e32 vcc, -1, v3
	s_and_saveexec_b64 s[44:45], vcc
	s_cbranch_execz .LBB0_1152
	v_min_u32_e32 v3, 0x31f, v3
	v_lshl_add_u32 v3, v3, 2, v157
	ds_read_b32 v105, v3
.LBB0_1152:
	s_or_b64 exec, exec, s[44:45]
	v_or_b32_e32 v3, 0x720, v2
	v_sub_u32_e32 v3, v124, v3
	v_cmp_lt_i32_e32 vcc, -1, v3
	v_mov_b32_e32 v107, 0xf149f2ca
	v_mov_b32_e32 v106, 0xf149f2ca
	s_and_saveexec_b64 s[44:45], vcc
	s_cbranch_execz .LBB0_1154
	v_min_u32_e32 v3, 0x31f, v3
	v_lshl_add_u32 v3, v3, 2, v157
	ds_read_b32 v106, v3
.LBB0_1154:
	s_or_b64 exec, exec, s[44:45]
	v_or_b32_e32 v2, 0x730, v2
	v_sub_u32_e32 v2, v124, v2
	v_cmp_lt_i32_e32 vcc, -1, v2
	s_and_saveexec_b64 s[44:45], vcc
	s_cbranch_execz .LBB0_1156
	v_min_u32_e32 v2, 0x31f, v2
	v_lshl_add_u32 v2, v2, 2, v157
	ds_read_b32 v107, v2
.LBB0_1156:
	s_or_b64 exec, exec, s[44:45]
	s_waitcnt lgkmcnt(0)
	v_fmac_f32_e32 v92, 0x3e38aa3b, v76
	v_fmac_f32_e32 v93, 0x3e38aa3b, v77
	v_fmac_f32_e32 v94, 0x3e38aa3b, v78
	v_fmac_f32_e32 v95, 0x3e38aa3b, v79
	v_fmac_f32_e32 v96, 0x3e38aa3b, v80
	v_fmac_f32_e32 v97, 0x3e38aa3b, v81
	v_fmac_f32_e32 v98, 0x3e38aa3b, v82
	v_fmac_f32_e32 v99, 0x3e38aa3b, v83
	v_fmac_f32_e32 v100, 0x3e38aa3b, v84
	v_fmac_f32_e32 v101, 0x3e38aa3b, v85
	v_fmac_f32_e32 v102, 0x3e38aa3b, v86
	v_fmac_f32_e32 v103, 0x3e38aa3b, v87
	v_fmac_f32_e32 v104, 0x3e38aa3b, v88
	v_fmac_f32_e32 v105, 0x3e38aa3b, v89
	v_fmac_f32_e32 v106, 0x3e38aa3b, v90
	v_fmac_f32_e32 v107, 0x3e38aa3b, v91
	s_mov_b64 s[44:45], 0
	s_waitcnt lgkmcnt(0)
	v_mov_b64_e32 v[120:121], v[0:1]

; template <int MODE, int TM> ...
;     ...
;   for (int t = 0; t < 2; ++t) {
;     if (!(TM & (1 << t))) continue;
;     const h16* Ks = t ? Ks1 : Ks0;
; #pragma unroll
;     for (int kt = 0; kt < 4; ++kt) {
;       S[t][kt] = f32x4{0.f, 0.f, 0.f, 0.f};
; #pragma unroll
;       for (int ks = 0; ks < 2; ++ks) {
;         h16x8 Kf = *(const h16x8*)(Ks + (kt * 16 + col) * KP + ks * 32 + q4 * 8);
;         S[t][kt] = __builtin_amdgcn_mfma_f32_16x16x32_f16(Kf, Q[ks], S[t][kt], 0, 0, 0);
;       }
;     }
;   }
;   __builtin_amdgcn_s_setprio(0);
;   const float* bt = biasT + hd * 800;
;   float addc[2] = {0.f, 0.f}, sclc[2] = {1.f, 1.f};
; #pragma unroll
;   for (int t = 0; t < 2; ++t) {
;     if (!(TM & (1 << t))) continue;
;     const int kbase = kbase0 + 64 * t;
;     if (far[t]) {
;       const bool ok = (MODE == M_SEL) ? selbit[t] : true;
;       addc[t] = ok ? bt[799] : -1e30f;
;       sclc[t] = SCL2;
;     } else {
;       addc[t] = 0.f;
;       sclc[t] = 1.f;
;       const int kx0 = kbase + q4 * 4;
;       const int d0 = (DK == 16) ? tq - 31 - 16 * kx0 : tq - kx0;
; #pragma unroll
;       for (int kt = 0; kt < 4; ++kt)
; #pragma unroll
;         for (int j = 0; j < 4; ++j) {
;           const int dist = d0 - DK * (kt * 16 + j);
;           const int kx = kx0 + kt * 16 + j;
;           bool valid = dist >= 0;
;           if (MODE == M_WIN) valid = valid && dist < 512 && kx >= 0;
;           if (MODE == M_SEL) valid = valid && selbit[t];
;           if (DK == 16) valid = valid && kx < NCMP;
;           const int dc = dist < 0 ? 0 : (dist > 799 ? 799 : dist);
;           S[t][kt][j] = valid ? S[t][kt][j] * SCL2 + bt[dc] : -1e30f;
;         }
.LBB0_1181:
	s_lshl_b32 s0, s49, 1
	s_lshl_b32 s3, s49, 7
	s_lshl_b32 s1, s49, 11
	s_cmp_ge_i32 s1, s31
	s_cselect_b64 s[42:43], -1, 0
	s_or_b32 s2, s0, 1
	s_cmp_lt_u32 s2, s28
	s_cselect_b64 s[44:45], -1, 0
	s_setprio 1
	ds_read_b128 v[80:83], v155 offset:53760
	ds_read_b128 v[76:79], v155 offset:53824
	v_cndmask_b32_e64 v0, 0, 1, s[42:43]
	s_mov_b64 s[0:1], -1
	s_and_b64 vcc, exec, s[44:45]
	v_cmp_ne_u32_e64 s[42:43], 1, v0
	s_cbranch_vccnz .LBB0_1221
	ds_read_b128 v[16:19], v155 offset:56320
	ds_read_b128 v[20:23], v155 offset:56384
	ds_read_b128 v[24:27], v155 offset:58880
	ds_read_b128 v[84:87], v155 offset:61440
	s_waitcnt lgkmcnt(5)
	v_mfma_f32_16x16x32_f16 v[12:15], v[80:83], v[4:7], 0
	s_waitcnt lgkmcnt(4)
	v_mfma_f32_16x16x32_f16 v[12:15], v[76:79], v[8:11], v[12:15]
	s_waitcnt lgkmcnt(3)
	v_mfma_f32_16x16x32_f16 v[16:19], v[16:19], v[4:7], 0
	s_waitcnt lgkmcnt(2)
	v_mfma_f32_16x16x32_f16 v[16:19], v[20:23], v[8:11], v[16:19]
	ds_read_b128 v[20:23], v155 offset:58944
	s_waitcnt lgkmcnt(2)
	v_mfma_f32_16x16x32_f16 v[24:27], v[24:27], v[4:7], 0
	s_waitcnt lgkmcnt(0)
	v_mfma_f32_16x16x32_f16 v[24:27], v[20:23], v[8:11], v[24:27]
	ds_read_b128 v[20:23], v155 offset:61504
	v_mfma_f32_16x16x32_f16 v[84:87], v[84:87], v[4:7], 0
	s_waitcnt lgkmcnt(0)
	v_mfma_f32_16x16x32_f16 v[84:87], v[20:23], v[8:11], v[84:87]
	s_setprio 0
	s_and_b64 vcc, exec, s[42:43]
	s_cbranch_vccnz .LBB0_1216
	v_or_b32_e32 v0, s3, v154
	v_lshlrev_b32_e32 v0, 4, v0
	v_sub_u32_e32 v2, v124, v0
	v_cmp_lt_i32_e32 vcc, -1, v2
	v_mov_b32_e32 v21, 0xf149f2ca
	v_mov_b32_e32 v20, 0xf149f2ca
	s_and_saveexec_b64 s[0:1], vcc
	s_cbranch_execz .LBB0_1185
	v_min_u32_e32 v2, 0x31f, v2
	v_lshl_add_u32 v2, v2, 2, v157
	ds_read_b32 v20, v2
.LBB0_1185:
	s_or_b64 exec, exec, s[0:1]
	v_or_b32_e32 v2, 16, v0
	v_sub_u32_e32 v2, v124, v2
	v_cmp_lt_i32_e32 vcc, -1, v2
	s_and_saveexec_b64 s[0:1], vcc
	s_cbranch_execz .LBB0_1187
	v_min_u32_e32 v2, 0x31f, v2
	v_lshl_add_u32 v2, v2, 2, v157
	ds_read_b32 v21, v2
.LBB0_1187:
	s_or_b64 exec, exec, s[0:1]
	v_or_b32_e32 v2, 32, v0
	v_sub_u32_e32 v2, v124, v2
	v_cmp_lt_i32_e32 vcc, -1, v2
	v_mov_b32_e32 v23, 0xf149f2ca
	v_mov_b32_e32 v22, 0xf149f2ca
	s_and_saveexec_b64 s[0:1], vcc
	s_cbranch_execz .LBB0_1189
	v_min_u32_e32 v2, 0x31f, v2
	v_lshl_add_u32 v2, v2, 2, v157
	ds_read_b32 v22, v2
.LBB0_1189:
	s_or_b64 exec, exec, s[0:1]
	v_or_b32_e32 v2, 48, v0
	v_sub_u32_e32 v2, v124, v2
	v_cmp_lt_i32_e32 vcc, -1, v2
	s_and_saveexec_b64 s[0:1], vcc
	s_cbranch_execz .LBB0_1191
	v_min_u32_e32 v2, 0x31f, v2
	v_lshl_add_u32 v2, v2, 2, v157
	ds_read_b32 v23, v2
.LBB0_1191:
	s_or_b64 exec, exec, s[0:1]
	v_or_b32_e32 v2, 0x100, v0
	v_sub_u32_e32 v2, v124, v2
	v_cmp_lt_i32_e32 vcc, -1, v2
	v_mov_b32_e32 v89, 0xf149f2ca
	v_mov_b32_e32 v88, 0xf149f2ca
	s_and_saveexec_b64 s[0:1], vcc
	s_cbranch_execz .LBB0_1193
	v_min_u32_e32 v2, 0x31f, v2
	v_lshl_add_u32 v2, v2, 2, v157
	ds_read_b32 v88, v2
.LBB0_1193:
	s_or_b64 exec, exec, s[0:1]
	v_or_b32_e32 v2, 0x110, v0
	v_sub_u32_e32 v2, v124, v2
	v_cmp_lt_i32_e32 vcc, -1, v2
	s_and_saveexec_b64 s[0:1], vcc
	s_cbranch_execz .LBB0_1195
	v_min_u32_e32 v2, 0x31f, v2
	v_lshl_add_u32 v2, v2, 2, v157
	ds_read_b32 v89, v2
.LBB0_1195:
	s_or_b64 exec, exec, s[0:1]
	v_or_b32_e32 v2, 0x120, v0
	v_sub_u32_e32 v2, v124, v2
	v_cmp_lt_i32_e32 vcc, -1, v2
	v_mov_b32_e32 v91, 0xf149f2ca
	v_mov_b32_e32 v90, 0xf149f2ca
	s_and_saveexec_b64 s[0:1], vcc
	s_cbranch_execz .LBB0_1197
	v_min_u32_e32 v2, 0x31f, v2
	v_lshl_add_u32 v2, v2, 2, v157
	ds_read_b32 v90, v2
.LBB0_1197:
	s_or_b64 exec, exec, s[0:1]
	v_or_b32_e32 v2, 0x130, v0
	v_sub_u32_e32 v2, v124, v2
	v_cmp_lt_i32_e32 vcc, -1, v2
	s_and_saveexec_b64 s[0:1], vcc
	s_cbranch_execz .LBB0_1199
	v_min_u32_e32 v2, 0x31f, v2
	v_lshl_add_u32 v2, v2, 2, v157
	ds_read_b32 v91, v2
.LBB0_1199:
	s_or_b64 exec, exec, s[0:1]
	v_or_b32_e32 v2, 0x200, v0
	v_sub_u32_e32 v2, v124, v2
	v_cmp_lt_i32_e32 vcc, -1, v2
	v_mov_b32_e32 v93, 0xf149f2ca
	v_mov_b32_e32 v92, 0xf149f2ca
	s_and_saveexec_b64 s[0:1], vcc
	s_cbranch_execz .LBB0_1201
	v_min_u32_e32 v2, 0x31f, v2
	v_lshl_add_u32 v2, v2, 2, v157
	ds_read_b32 v92, v2
.LBB0_1201:
	s_or_b64 exec, exec, s[0:1]
	v_or_b32_e32 v2, 0x210, v0
	v_sub_u32_e32 v2, v124, v2
	v_cmp_lt_i32_e32 vcc, -1, v2
	s_and_saveexec_b64 s[0:1], vcc
	s_cbranch_execz .LBB0_1203
	v_min_u32_e32 v2, 0x31f, v2
	v_lshl_add_u32 v2, v2, 2, v157
	ds_read_b32 v93, v2
.LBB0_1203:
	s_or_b64 exec, exec, s[0:1]
	v_or_b32_e32 v2, 0x220, v0
	v_sub_u32_e32 v2, v124, v2
	v_cmp_lt_i32_e32 vcc, -1, v2
	v_mov_b32_e32 v95, 0xf149f2ca
	v_mov_b32_e32 v94, 0xf149f2ca
	s_and_saveexec_b64 s[0:1], vcc
	s_cbranch_execz .LBB0_1205
	v_min_u32_e32 v2, 0x31f, v2
	v_lshl_add_u32 v2, v2, 2, v157
	ds_read_b32 v94, v2
.LBB0_1205:
	s_or_b64 exec, exec, s[0:1]
	v_or_b32_e32 v2, 0x230, v0
	v_sub_u32_e32 v2, v124, v2
	v_cmp_lt_i32_e32 vcc, -1, v2
	s_and_saveexec_b64 s[0:1], vcc
	s_cbranch_execz .LBB0_1207
	v_min_u32_e32 v2, 0x31f, v2
	v_lshl_add_u32 v2, v2, 2, v157
	ds_read_b32 v95, v2
.LBB0_1207:
	s_or_b64 exec, exec, s[0:1]
	v_or_b32_e32 v2, 0x300, v0
	v_sub_u32_e32 v2, v124, v2
	v_cmp_lt_i32_e32 vcc, -1, v2
	v_mov_b32_e32 v97, 0xf149f2ca
	v_mov_b32_e32 v96, 0xf149f2ca
	s_and_saveexec_b64 s[0:1], vcc
	s_cbranch_execz .LBB0_1209
	v_min_u32_e32 v2, 0x31f, v2
	v_lshl_add_u32 v2, v2, 2, v157
	ds_read_b32 v96, v2
.LBB0_1209:
	s_or_b64 exec, exec, s[0:1]
	v_or_b32_e32 v2, 0x310, v0
	v_sub_u32_e32 v2, v124, v2
	v_cmp_lt_i32_e32 vcc, -1, v2
	s_and_saveexec_b64 s[0:1], vcc
	s_cbranch_execz .LBB0_1211
	v_min_u32_e32 v2, 0x31f, v2
	v_lshl_add_u32 v2, v2, 2, v157
	ds_read_b32 v97, v2
.LBB0_1211:
	s_or_b64 exec, exec, s[0:1]
	v_or_b32_e32 v2, 0x320, v0
	v_sub_u32_e32 v2, v124, v2
	v_cmp_lt_i32_e32 vcc, -1, v2
	v_mov_b32_e32 v99, 0xf149f2ca
	v_mov_b32_e32 v98, 0xf149f2ca
	s_and_saveexec_b64 s[0:1], vcc
	s_cbranch_execz .LBB0_1213
	v_min_u32_e32 v2, 0x31f, v2
	v_lshl_add_u32 v2, v2, 2, v157
	ds_read_b32 v98, v2
.LBB0_1213:
	s_or_b64 exec, exec, s[0:1]
	v_or_b32_e32 v0, 0x330, v0
	v_sub_u32_e32 v0, v124, v0
	v_cmp_lt_i32_e32 vcc, -1, v0
	s_and_saveexec_b64 s[0:1], vcc
	s_cbranch_execz .LBB0_1215
	v_min_u32_e32 v0, 0x31f, v0
	v_lshl_add_u32 v0, v0, 2, v157
	ds_read_b32 v99, v0
.LBB0_1215:
	s_or_b64 exec, exec, s[0:1]
	s_waitcnt lgkmcnt(0)
	v_fmac_f32_e32 v20, 0x3e38aa3b, v12
	v_fmac_f32_e32 v21, 0x3e38aa3b, v13
	v_fmac_f32_e32 v22, 0x3e38aa3b, v14
	v_fmac_f32_e32 v23, 0x3e38aa3b, v15
	v_fmac_f32_e32 v88, 0x3e38aa3b, v16
	v_fmac_f32_e32 v89, 0x3e38aa3b, v17
	v_fmac_f32_e32 v90, 0x3e38aa3b, v18
	v_fmac_f32_e32 v91, 0x3e38aa3b, v19
	v_fmac_f32_e32 v92, 0x3e38aa3b, v24
	v_fmac_f32_e32 v93, 0x3e38aa3b, v25
	v_fmac_f32_e32 v94, 0x3e38aa3b, v26
	v_fmac_f32_e32 v95, 0x3e38aa3b, v27
	v_fmac_f32_e32 v96, 0x3e38aa3b, v84
	v_fmac_f32_e32 v97, 0x3e38aa3b, v85
	v_fmac_f32_e32 v98, 0x3e38aa3b, v86
	v_fmac_f32_e32 v99, 0x3e38aa3b, v87
	s_mov_b64 s[0:1], 0

; template <int MODE, int TM> ...
;     ...
;   for (int t = 0; t < 2; ++t) {
;     if (!(TM & (1 << t))) continue;
;     const h16* Ks = t ? Ks1 : Ks0;
; #pragma unroll
;     for (int kt = 0; kt < 4; ++kt) {
;       S[t][kt] = f32x4{0.f, 0.f, 0.f, 0.f};
; #pragma unroll
;       for (int ks = 0; ks < 2; ++ks) {
;         h16x8 Kf = *(const h16x8*)(Ks + (kt * 16 + col) * KP + ks * 32 + q4 * 8);
;         S[t][kt] = __builtin_amdgcn_mfma_f32_16x16x32_f16(Kf, Q[ks], S[t][kt], 0, 0, 0);
;       }
;     }
;   }
;   __builtin_amdgcn_s_setprio(0);
;   const float* bt = biasT + hd * 800;
;   float addc[2] = {0.f, 0.f}, sclc[2] = {1.f, 1.f};
; #pragma unroll
;   for (int t = 0; t < 2; ++t) {
;     if (!(TM & (1 << t))) continue;
;     const int kbase = kbase0 + 64 * t;
;     if (far[t]) {
;       const bool ok = (MODE == M_SEL) ? selbit[t] : true;
;       addc[t] = ok ? bt[799] : -1e30f;
;       sclc[t] = SCL2;
;     } else {
;       addc[t] = 0.f;
;       sclc[t] = 1.f;
;       const int kx0 = kbase + q4 * 4;
;       const int d0 = (DK == 16) ? tq - 31 - 16 * kx0 : tq - kx0;
; #pragma unroll
;       for (int kt = 0; kt < 4; ++kt)
; #pragma unroll
;         for (int j = 0; j < 4; ++j) {
;           const int dist = d0 - DK * (kt * 16 + j);
;           const int kx = kx0 + kt * 16 + j;
;           bool valid = dist >= 0;
;           if (MODE == M_WIN) valid = valid && dist < 512 && kx >= 0;
;           if (MODE == M_SEL) valid = valid && selbit[t];
;           if (DK == 16) valid = valid && kx < NCMP;
;           const int dc = dist < 0 ? 0 : (dist > 799 ? 799 : dist);
;           S[t][kt][j] = valid ? S[t][kt][j] * SCL2 + bt[dc] : -1e30f;
;         }
.LBB0_1221:
	s_and_b64 vcc, exec, s[0:1]
	s_cbranch_vccz .LBB0_1295
	s_waitcnt lgkmcnt(1)
	v_mfma_f32_16x16x32_f16 v[12:15], v[80:83], v[4:7], 0
	ds_read_b128 v[16:19], v155 offset:56320
	ds_read_b128 v[20:23], v155 offset:58880
	s_nop 1
	ds_read_b128 v[24:27], v202 offset:5120
	s_waitcnt lgkmcnt(3)
	v_mfma_f32_16x16x32_f16 v[92:95], v[76:79], v[8:11], v[12:15]
	ds_read_b128 v[76:79], v202 offset:7680
	s_nop 1
	ds_read_b128 v[12:15], v155 offset:56384
	s_waitcnt lgkmcnt(4)
	v_mfma_f32_16x16x32_f16 v[16:19], v[16:19], v[4:7], 0
	s_waitcnt lgkmcnt(0)
	v_mfma_f32_16x16x32_f16 v[96:99], v[12:15], v[8:11], v[16:19]
	ds_read_b128 v[12:15], v155 offset:58944
	v_mfma_f32_16x16x32_f16 v[16:19], v[20:23], v[4:7], 0
	ds_read_b128 v[20:23], v155 offset:61440
	s_waitcnt lgkmcnt(1)
	v_mfma_f32_16x16x32_f16 v[100:103], v[12:15], v[8:11], v[16:19]
	ds_read_b128 v[12:15], v155 offset:61504
	s_waitcnt lgkmcnt(1)
	v_mfma_f32_16x16x32_f16 v[16:19], v[20:23], v[4:7], 0
	ds_read_b128 v[20:23], v202
	s_waitcnt lgkmcnt(1)
	v_mfma_f32_16x16x32_f16 v[104:107], v[12:15], v[8:11], v[16:19]
	ds_read_b128 v[12:15], v202 offset:64
	s_waitcnt lgkmcnt(1)
	v_mfma_f32_16x16x32_f16 v[16:19], v[20:23], v[4:7], 0
	ds_read_b128 v[20:23], v202 offset:2560
	s_waitcnt lgkmcnt(1)
	v_mfma_f32_16x16x32_f16 v[12:15], v[12:15], v[8:11], v[16:19]
	s_nop 4
	ds_read_b128 v[16:19], v202 offset:2624
	s_waitcnt lgkmcnt(1)
	v_mfma_f32_16x16x32_f16 v[20:23], v[20:23], v[4:7], 0
	s_waitcnt lgkmcnt(0)
	v_mfma_f32_16x16x32_f16 v[16:19], v[16:19], v[8:11], v[20:23]
	s_nop 5
	ds_read_b128 v[20:23], v202 offset:5184
	v_mfma_f32_16x16x32_f16 v[24:27], v[24:27], v[4:7], 0
	s_waitcnt lgkmcnt(0)
	v_mfma_f32_16x16x32_f16 v[20:23], v[20:23], v[8:11], v[24:27]
	s_nop 5
	ds_read_b128 v[24:27], v202 offset:7744
	v_mfma_f32_16x16x32_f16 v[76:79], v[76:79], v[4:7], 0
	s_waitcnt lgkmcnt(0)
	v_mfma_f32_16x16x32_f16 v[76:79], v[24:27], v[8:11], v[76:79]
	s_setprio 0
	v_or_b32_e32 v2, s3, v154
	s_mov_b64 s[0:1], -1
	s_and_b64 vcc, exec, s[42:43]
	v_lshlrev_b32_e32 v3, 4, v2
	s_cbranch_vccnz .LBB0_1256
	v_sub_u32_e32 v0, v124, v3
	v_cmp_lt_i32_e32 vcc, -1, v0
	v_mov_b32_e32 v25, 0xf149f2ca
	v_mov_b32_e32 v24, 0xf149f2ca
	s_and_saveexec_b64 s[0:1], vcc
	s_cbranch_execz .LBB0_1225
	v_min_u32_e32 v0, 0x31f, v0
	v_lshl_add_u32 v0, v0, 2, v157
	ds_read_b32 v24, v0
.LBB0_1225:
	s_or_b64 exec, exec, s[0:1]
	v_or_b32_e32 v0, 16, v3
	v_sub_u32_e32 v0, v124, v0
	v_cmp_lt_i32_e32 vcc, -1, v0
	s_and_saveexec_b64 s[0:1], vcc
	s_cbranch_execz .LBB0_1227
	v_min_u32_e32 v0, 0x31f, v0
	v_lshl_add_u32 v0, v0, 2, v157
	ds_read_b32 v25, v0
.LBB0_1227:
	s_or_b64 exec, exec, s[0:1]
	v_or_b32_e32 v0, 32, v3
	v_sub_u32_e32 v0, v124, v0
	v_cmp_lt_i32_e32 vcc, -1, v0
	v_mov_b32_e32 v27, 0xf149f2ca
	v_mov_b32_e32 v26, 0xf149f2ca
	s_and_saveexec_b64 s[0:1], vcc
	s_cbranch_execz .LBB0_1229
	v_min_u32_e32 v0, 0x31f, v0
	v_lshl_add_u32 v0, v0, 2, v157
	ds_read_b32 v26, v0
.LBB0_1229:
	s_or_b64 exec, exec, s[0:1]
	v_or_b32_e32 v0, 48, v3
	v_sub_u32_e32 v0, v124, v0
	v_cmp_lt_i32_e32 vcc, -1, v0
	s_and_saveexec_b64 s[0:1], vcc
	s_cbranch_execz .LBB0_1231
	v_min_u32_e32 v0, 0x31f, v0
	v_lshl_add_u32 v0, v0, 2, v157
	ds_read_b32 v27, v0
.LBB0_1231:
	s_or_b64 exec, exec, s[0:1]
	v_or_b32_e32 v0, 0x100, v3
	v_sub_u32_e32 v0, v124, v0
	v_cmp_lt_i32_e32 vcc, -1, v0
	v_mov_b32_e32 v81, 0xf149f2ca
	v_mov_b32_e32 v80, 0xf149f2ca
	s_and_saveexec_b64 s[0:1], vcc
	s_cbranch_execz .LBB0_1233
	v_min_u32_e32 v0, 0x31f, v0
	v_lshl_add_u32 v0, v0, 2, v157
	ds_read_b32 v80, v0
.LBB0_1233:
	s_or_b64 exec, exec, s[0:1]
	v_or_b32_e32 v0, 0x110, v3
	v_sub_u32_e32 v0, v124, v0
	v_cmp_lt_i32_e32 vcc, -1, v0
	s_and_saveexec_b64 s[0:1], vcc
	s_cbranch_execz .LBB0_1235
	v_min_u32_e32 v0, 0x31f, v0
	v_lshl_add_u32 v0, v0, 2, v157
	ds_read_b32 v81, v0
; template <int MODE, int TM> ...
;     ...
;       const int kx0 = kbase + q4 * 4;
;       const int d0 = (DK == 16) ? tq - 31 - 16 * kx0 : tq - kx0;
; #pragma unroll
;       for (int kt = 0; kt < 4; ++kt)
; #pragma unroll
;         for (int j = 0; j < 4; ++j) {
;           const int dist = d0 - DK * (kt * 16 + j);
;           const int kx = kx0 + kt * 16 + j;
;           bool valid = dist >= 0;
;           if (MODE == M_WIN) valid = valid && dist < 512 && kx >= 0;
;           if (MODE == M_SEL) valid = valid && selbit[t];
;           if (DK == 16) valid = valid && kx < NCMP;
;           const int dc = dist < 0 ? 0 : (dist > 799 ? 799 : dist);
;           S[t][kt][j] = valid ? S[t][kt][j] * SCL2 + bt[dc] : -1e30f;
;         }
.LBB0_1235:
	s_or_b64 exec, exec, s[0:1]
	v_or_b32_e32 v0, 0x120, v3
	v_sub_u32_e32 v0, v124, v0
	v_cmp_lt_i32_e32 vcc, -1, v0
	v_mov_b32_e32 v83, 0xf149f2ca
	v_mov_b32_e32 v82, 0xf149f2ca
	s_and_saveexec_b64 s[0:1], vcc
	s_cbranch_execz .LBB0_1237
	v_min_u32_e32 v0, 0x31f, v0
	v_lshl_add_u32 v0, v0, 2, v157
	ds_read_b32 v82, v0
.LBB0_1237:
	s_or_b64 exec, exec, s[0:1]
	v_or_b32_e32 v0, 0x130, v3
	v_sub_u32_e32 v0, v124, v0
	v_cmp_lt_i32_e32 vcc, -1, v0
	s_and_saveexec_b64 s[0:1], vcc
	s_cbranch_execz .LBB0_1239
	v_min_u32_e32 v0, 0x31f, v0
	v_lshl_add_u32 v0, v0, 2, v157
	ds_read_b32 v83, v0
.LBB0_1239:
	s_or_b64 exec, exec, s[0:1]
	v_or_b32_e32 v0, 0x200, v3
	v_sub_u32_e32 v0, v124, v0
	v_cmp_lt_i32_e32 vcc, -1, v0
	v_mov_b32_e32 v85, 0xf149f2ca
	v_mov_b32_e32 v84, 0xf149f2ca
	s_and_saveexec_b64 s[0:1], vcc
	s_cbranch_execz .LBB0_1241
	v_min_u32_e32 v0, 0x31f, v0
	v_lshl_add_u32 v0, v0, 2, v157
	ds_read_b32 v84, v0
.LBB0_1241:
	s_or_b64 exec, exec, s[0:1]
	v_or_b32_e32 v0, 0x210, v3
	v_sub_u32_e32 v0, v124, v0
	v_cmp_lt_i32_e32 vcc, -1, v0
	s_and_saveexec_b64 s[0:1], vcc
	s_cbranch_execz .LBB0_1243
	v_min_u32_e32 v0, 0x31f, v0
	v_lshl_add_u32 v0, v0, 2, v157
	ds_read_b32 v85, v0
.LBB0_1243:
	s_or_b64 exec, exec, s[0:1]
	v_or_b32_e32 v0, 0x220, v3
	v_sub_u32_e32 v0, v124, v0
	v_cmp_lt_i32_e32 vcc, -1, v0
	v_mov_b32_e32 v87, 0xf149f2ca
	v_mov_b32_e32 v86, 0xf149f2ca
	s_and_saveexec_b64 s[0:1], vcc
	s_cbranch_execz .LBB0_1245
	v_min_u32_e32 v0, 0x31f, v0
	v_lshl_add_u32 v0, v0, 2, v157
	ds_read_b32 v86, v0
.LBB0_1245:
	s_or_b64 exec, exec, s[0:1]
	v_or_b32_e32 v0, 0x230, v3
	v_sub_u32_e32 v0, v124, v0
	v_cmp_lt_i32_e32 vcc, -1, v0
	s_and_saveexec_b64 s[0:1], vcc
	s_cbranch_execz .LBB0_1247
	v_min_u32_e32 v0, 0x31f, v0
	v_lshl_add_u32 v0, v0, 2, v157
	ds_read_b32 v87, v0
.LBB0_1247:
	s_or_b64 exec, exec, s[0:1]
	v_or_b32_e32 v0, 0x300, v3
	v_sub_u32_e32 v0, v124, v0
	v_cmp_lt_i32_e32 vcc, -1, v0
	v_mov_b32_e32 v89, 0xf149f2ca
	v_mov_b32_e32 v88, 0xf149f2ca
	s_and_saveexec_b64 s[0:1], vcc
	s_cbranch_execz .LBB0_1249
	v_min_u32_e32 v0, 0x31f, v0
	v_lshl_add_u32 v0, v0, 2, v157
	ds_read_b32 v88, v0
.LBB0_1249:
	s_or_b64 exec, exec, s[0:1]
	v_or_b32_e32 v0, 0x310, v3
	v_sub_u32_e32 v0, v124, v0
	v_cmp_lt_i32_e32 vcc, -1, v0
	s_and_saveexec_b64 s[0:1], vcc
	s_cbranch_execz .LBB0_1251
	v_min_u32_e32 v0, 0x31f, v0
	v_lshl_add_u32 v0, v0, 2, v157
	ds_read_b32 v89, v0
.LBB0_1251:
	s_or_b64 exec, exec, s[0:1]
	v_or_b32_e32 v0, 0x320, v3
	v_sub_u32_e32 v0, v124, v0
	v_cmp_lt_i32_e32 vcc, -1, v0
	v_mov_b32_e32 v91, 0xf149f2ca
	v_mov_b32_e32 v90, 0xf149f2ca
	s_and_saveexec_b64 s[0:1], vcc
	s_cbranch_execz .LBB0_1253
	v_min_u32_e32 v0, 0x31f, v0
	v_lshl_add_u32 v0, v0, 2, v157
	ds_read_b32 v90, v0
.LBB0_1253:
	s_or_b64 exec, exec, s[0:1]
	v_or_b32_e32 v0, 0x330, v3
	v_sub_u32_e32 v0, v124, v0
	v_cmp_lt_i32_e32 vcc, -1, v0
	s_and_saveexec_b64 s[0:1], vcc
	s_cbranch_execz .LBB0_1255
	v_min_u32_e32 v0, 0x31f, v0
	v_lshl_add_u32 v0, v0, 2, v157
	ds_read_b32 v91, v0
.LBB0_1255:
	s_or_b64 exec, exec, s[0:1]
	s_waitcnt lgkmcnt(0)
	v_fmac_f32_e32 v24, 0x3e38aa3b, v92
	v_fmac_f32_e32 v25, 0x3e38aa3b, v93
	v_fmac_f32_e32 v26, 0x3e38aa3b, v94
	v_fmac_f32_e32 v27, 0x3e38aa3b, v95
	v_fmac_f32_e32 v80, 0x3e38aa3b, v96
	v_fmac_f32_e32 v81, 0x3e38aa3b, v97
	v_fmac_f32_e32 v82, 0x3e38aa3b, v98
	v_fmac_f32_e32 v83, 0x3e38aa3b, v99
	v_fmac_f32_e32 v84, 0x3e38aa3b, v100
	v_fmac_f32_e32 v85, 0x3e38aa3b, v101
	v_fmac_f32_e32 v86, 0x3e38aa3b, v102
	v_fmac_f32_e32 v87, 0x3e38aa3b, v103
	v_fmac_f32_e32 v88, 0x3e38aa3b, v104
	v_fmac_f32_e32 v89, 0x3e38aa3b, v105
	v_fmac_f32_e32 v90, 0x3e38aa3b, v106
	v_fmac_f32_e32 v91, 0x3e38aa3b, v107
	s_mov_b64 s[0:1], 0

; template <int MODE, int TM> ...
;     ...
;       const int kx0 = kbase + q4 * 4;
;       const int d0 = (DK == 16) ? tq - 31 - 16 * kx0 : tq - kx0;
; #pragma unroll
;       for (int kt = 0; kt < 4; ++kt)
; #pragma unroll
;         for (int j = 0; j < 4; ++j) {
;           const int dist = d0 - DK * (kt * 16 + j);
;           const int kx = kx0 + kt * 16 + j;
;           bool valid = dist >= 0;
;           if (MODE == M_WIN) valid = valid && dist < 512 && kx >= 0;
;           if (MODE == M_SEL) valid = valid && selbit[t];
;           if (DK == 16) valid = valid && kx < NCMP;
;           const int dc = dist < 0 ? 0 : (dist > 799 ? 799 : dist);
;           S[t][kt][j] = valid ? S[t][kt][j] * SCL2 + bt[dc] : -1e30f;
;         }
.LBB0_1259:
	v_or_b32_e32 v92, 0x400, v3
	v_sub_u32_e32 v94, v124, v92
	v_cmp_lt_i32_e32 vcc, -1, v94
	v_mov_b32_e32 v93, 0xf149f2ca
	v_mov_b32_e32 v92, 0xf149f2ca
	s_and_saveexec_b64 s[0:1], vcc
	s_cbranch_execz .LBB0_1261
	v_min_u32_e32 v92, 0x31f, v94
	v_lshl_add_u32 v92, v92, 2, v157
	ds_read_b32 v92, v92
.LBB0_1261:
	s_or_b64 exec, exec, s[0:1]
	v_or_b32_e32 v94, 0x410, v3
	v_sub_u32_e32 v94, v124, v94
	v_cmp_lt_i32_e32 vcc, -1, v94
	s_and_saveexec_b64 s[0:1], vcc
	s_cbranch_execz .LBB0_1263
	v_min_u32_e32 v93, 0x31f, v94
	v_lshl_add_u32 v93, v93, 2, v157
	ds_read_b32 v93, v93
.LBB0_1263:
	s_or_b64 exec, exec, s[0:1]
	v_or_b32_e32 v94, 0x420, v3
	v_sub_u32_e32 v96, v124, v94
	v_cmp_lt_i32_e32 vcc, -1, v96
	v_mov_b32_e32 v95, 0xf149f2ca
	v_mov_b32_e32 v94, 0xf149f2ca
	s_and_saveexec_b64 s[0:1], vcc
	s_cbranch_execz .LBB0_1265
	v_min_u32_e32 v94, 0x31f, v96
	v_lshl_add_u32 v94, v94, 2, v157
	ds_read_b32 v94, v94
.LBB0_1265:
	s_or_b64 exec, exec, s[0:1]
	v_or_b32_e32 v96, 0x430, v3
	v_sub_u32_e32 v96, v124, v96
	v_cmp_lt_i32_e32 vcc, -1, v96
	s_and_saveexec_b64 s[0:1], vcc
	s_cbranch_execz .LBB0_1267
	v_min_u32_e32 v95, 0x31f, v96
	v_lshl_add_u32 v95, v95, 2, v157
	ds_read_b32 v95, v95
.LBB0_1267:
	s_or_b64 exec, exec, s[0:1]
	v_or_b32_e32 v96, 0x500, v3
	v_sub_u32_e32 v98, v124, v96
	v_cmp_lt_i32_e32 vcc, -1, v98
	v_mov_b32_e32 v97, 0xf149f2ca
	v_mov_b32_e32 v96, 0xf149f2ca
	s_and_saveexec_b64 s[0:1], vcc
	s_cbranch_execz .LBB0_1269
	v_min_u32_e32 v96, 0x31f, v98
	v_lshl_add_u32 v96, v96, 2, v157
	ds_read_b32 v96, v96
.LBB0_1269:
	s_or_b64 exec, exec, s[0:1]
	v_or_b32_e32 v98, 0x510, v3
	v_sub_u32_e32 v98, v124, v98
	v_cmp_lt_i32_e32 vcc, -1, v98
	s_and_saveexec_b64 s[0:1], vcc
	s_cbranch_execz .LBB0_1271
	v_min_u32_e32 v97, 0x31f, v98
	v_lshl_add_u32 v97, v97, 2, v157
	ds_read_b32 v97, v97
.LBB0_1271:
	s_or_b64 exec, exec, s[0:1]
	v_or_b32_e32 v98, 0x520, v3
	v_sub_u32_e32 v100, v124, v98
	v_cmp_lt_i32_e32 vcc, -1, v100
	v_mov_b32_e32 v99, 0xf149f2ca
	v_mov_b32_e32 v98, 0xf149f2ca
	s_and_saveexec_b64 s[0:1], vcc
	s_cbranch_execz .LBB0_1273
	v_min_u32_e32 v98, 0x31f, v100
	v_lshl_add_u32 v98, v98, 2, v157
	ds_read_b32 v98, v98
.LBB0_1273:
	s_or_b64 exec, exec, s[0:1]
	v_or_b32_e32 v100, 0x530, v3
	v_sub_u32_e32 v100, v124, v100
	v_cmp_lt_i32_e32 vcc, -1, v100
	s_and_saveexec_b64 s[0:1], vcc
	s_cbranch_execz .LBB0_1275
	v_min_u32_e32 v99, 0x31f, v100
	v_lshl_add_u32 v99, v99, 2, v157
	ds_read_b32 v99, v99
.LBB0_1275:
	s_or_b64 exec, exec, s[0:1]
	v_or_b32_e32 v100, 0x600, v3
	v_sub_u32_e32 v102, v124, v100
	v_cmp_lt_i32_e32 vcc, -1, v102
	v_mov_b32_e32 v101, 0xf149f2ca
	v_mov_b32_e32 v100, 0xf149f2ca
	s_and_saveexec_b64 s[0:1], vcc
	s_cbranch_execz .LBB0_1277
	v_min_u32_e32 v100, 0x31f, v102
	v_lshl_add_u32 v100, v100, 2, v157
	ds_read_b32 v100, v100
.LBB0_1277:
	s_or_b64 exec, exec, s[0:1]
	v_or_b32_e32 v102, 0x610, v3
	v_sub_u32_e32 v102, v124, v102
	v_cmp_lt_i32_e32 vcc, -1, v102
	s_and_saveexec_b64 s[0:1], vcc
	s_cbranch_execz .LBB0_1279
	v_min_u32_e32 v101, 0x31f, v102
	v_lshl_add_u32 v101, v101, 2, v157
	ds_read_b32 v101, v101
.LBB0_1279:
	s_or_b64 exec, exec, s[0:1]
	v_or_b32_e32 v102, 0x620, v3
	v_sub_u32_e32 v104, v124, v102
	v_cmp_lt_i32_e32 vcc, -1, v104
	v_mov_b32_e32 v103, 0xf149f2ca
	v_mov_b32_e32 v102, 0xf149f2ca
	s_and_saveexec_b64 s[0:1], vcc
	s_cbranch_execz .LBB0_1281
	v_min_u32_e32 v102, 0x31f, v104
	v_lshl_add_u32 v102, v102, 2, v157
	ds_read_b32 v102, v102
.LBB0_1281:
	s_or_b64 exec, exec, s[0:1]
	v_or_b32_e32 v104, 0x630, v3
	v_sub_u32_e32 v104, v124, v104
	v_cmp_lt_i32_e32 vcc, -1, v104
	s_and_saveexec_b64 s[0:1], vcc
	s_cbranch_execz .LBB0_1283
	v_min_u32_e32 v103, 0x31f, v104
	v_lshl_add_u32 v103, v103, 2, v157
	ds_read_b32 v103, v103
.LBB0_1283:
	s_or_b64 exec, exec, s[0:1]
	v_or_b32_e32 v104, 0x700, v3
	v_sub_u32_e32 v106, v124, v104
	v_cmp_lt_i32_e32 vcc, -1, v106
	v_mov_b32_e32 v105, 0xf149f2ca
	v_mov_b32_e32 v104, 0xf149f2ca
	s_and_saveexec_b64 s[0:1], vcc
	s_cbranch_execz .LBB0_1285
	v_min_u32_e32 v104, 0x31f, v106
	v_lshl_add_u32 v104, v104, 2, v157
	ds_read_b32 v104, v104
.LBB0_1285:
	s_or_b64 exec, exec, s[0:1]
	v_or_b32_e32 v106, 0x710, v3
	v_sub_u32_e32 v106, v124, v106
	v_cmp_lt_i32_e32 vcc, -1, v106
	s_and_saveexec_b64 s[0:1], vcc
	s_cbranch_execz .LBB0_1287
	v_min_u32_e32 v105, 0x31f, v106
	v_lshl_add_u32 v105, v105, 2, v157
	ds_read_b32 v105, v105
.LBB0_1287:
	s_or_b64 exec, exec, s[0:1]
	v_or_b32_e32 v3, 0x720, v3
	v_sub_u32_e32 v3, v124, v3
	v_cmp_lt_i32_e32 vcc, -1, v3
	v_mov_b32_e32 v107, 0xf149f2ca
	v_mov_b32_e32 v106, 0xf149f2ca
	s_and_saveexec_b64 s[0:1], vcc
	s_cbranch_execz .LBB0_1289
	v_min_u32_e32 v3, 0x31f, v3
	v_lshl_add_u32 v3, v3, 2, v157
	ds_read_b32 v106, v3
.LBB0_1289:
	s_or_b64 exec, exec, s[0:1]
	v_or_b32_e32 v3, 0x73, v2
	v_lshlrev_b32_e32 v2, 4, v3
	v_sub_u32_e32 v2, v124, v2
	v_cmp_lt_i32_e32 vcc, -1, v2
	v_cmp_gt_u32_e64 s[0:1], s60, v3
	s_and_b64 s[42:43], s[0:1], vcc
	s_and_saveexec_b64 s[0:1], s[42:43]
	s_cbranch_execz .LBB0_1291
	v_min_u32_e32 v2, 0x31f, v2
	v_lshl_add_u32 v2, v2, 2, v157
	ds_read_b32 v107, v2
.LBB0_1291:
	s_or_b64 exec, exec, s[0:1]
	s_waitcnt lgkmcnt(0)
	v_fmac_f32_e32 v92, 0x3e38aa3b, v12
	v_fmac_f32_e32 v93, 0x3e38aa3b, v13
	v_fmac_f32_e32 v94, 0x3e38aa3b, v14
	v_fmac_f32_e32 v95, 0x3e38aa3b, v15
	v_fmac_f32_e32 v96, 0x3e38aa3b, v16
	v_fmac_f32_e32 v97, 0x3e38aa3b, v17
	v_fmac_f32_e32 v98, 0x3e38aa3b, v18
	v_fmac_f32_e32 v99, 0x3e38aa3b, v19
	v_fmac_f32_e32 v100, 0x3e38aa3b, v20
	v_fmac_f32_e32 v101, 0x3e38aa3b, v21
	v_fmac_f32_e32 v102, 0x3e38aa3b, v22
	v_fmac_f32_e32 v103, 0x3e38aa3b, v23
	v_fmac_f32_e32 v104, 0x3e38aa3b, v76
	v_fmac_f32_e32 v105, 0x3e38aa3b, v77
	v_fmac_f32_e32 v106, 0x3e38aa3b, v78
	v_fmac_f32_e32 v107, 0x3e38aa3b, v79
	s_mov_b64 s[0:1], 0
	s_waitcnt lgkmcnt(0)
	v_mov_b64_e32 v[122:123], v[0:1]

; template <int MODE, int TM> ...
;     ...
;   for (int t = 0; t < 2; ++t) {
;     if (!(TM & (1 << t))) continue;
;     const h16* Ks = t ? Ks1 : Ks0;
; #pragma unroll
;     for (int kt = 0; kt < 4; ++kt) {
;       S[t][kt] = f32x4{0.f, 0.f, 0.f, 0.f};
; #pragma unroll
;       for (int ks = 0; ks < 2; ++ks) {
;         h16x8 Kf = *(const h16x8*)(Ks + (kt * 16 + col) * KP + ks * 32 + q4 * 8);
;         S[t][kt] = __builtin_amdgcn_mfma_f32_16x16x32_f16(Kf, Q[ks], S[t][kt], 0, 0, 0);
;       }
;     }
;   }
;   __builtin_amdgcn_s_setprio(0);
;   const float* bt = biasT + hd * 800;
;   float addc[2] = {0.f, 0.f}, sclc[2] = {1.f, 1.f};
; #pragma unroll
;   for (int t = 0; t < 2; ++t) {
;     if (!(TM & (1 << t))) continue;
;     const int kbase = kbase0 + 64 * t;
;     if (far[t]) {
;       const bool ok = (MODE == M_SEL) ? selbit[t] : true;
;       addc[t] = ok ? bt[799] : -1e30f;
;       sclc[t] = SCL2;
;     } else {
;       addc[t] = 0.f;
;       sclc[t] = 1.f;
;       const int kx0 = kbase + q4 * 4;
;       const int d0 = (DK == 16) ? tq - 31 - 16 * kx0 : tq - kx0;
; #pragma unroll
;       for (int kt = 0; kt < 4; ++kt)
; #pragma unroll
;         for (int j = 0; j < 4; ++j) {
;           const int dist = d0 - DK * (kt * 16 + j);
;           const int kx = kx0 + kt * 16 + j;
;           bool valid = dist >= 0;
;           if (MODE == M_WIN) valid = valid && dist < 512 && kx >= 0;
;           if (MODE == M_SEL) valid = valid && selbit[t];
;           if (DK == 16) valid = valid && kx < NCMP;
;     ...
;         const int jb = 2 * i;
;         bool sb[2];
;         sb[0] = ((jb < 64 ? (slo >> jb) : (shi >> (jb - 64))) & 1ull) != 0;
;         sb[1] = (jb + 1 <= cur) && (((jb + 1 < 64 ? (slo >> (jb + 1)) : (shi >> (jb + 1 - 64))) & 1ull) != 0);
;         const bool far[2] = {t0 - (jb * 64 + 63) >= 799, t0 - (jb * 64 + 127) >= 799};
;         const bool n0 = __any(sb[0]) != 0, n1 = __any(sb[1]) != 0;
;         if (n0 && n1) attn_tile2<M_SEL, 3>(Q, O, st, KSB(i, 0), VTB(i, 0), KSB(i, 1), VTB(i, 1), biasT, tq, hd, jb * 64, far, sb, hpd, hpe, lane);
;         else if (n0) attn_tile2<M_SEL, 1>(Q, O, st, KSB(i, 0), VTB(i, 0), KSB(i, 1), VTB(i, 1), biasT, tq, hd, jb * 64, far, sb, hpd, hpe, lane);
;         else if (n1) attn_tile2<M_SEL, 2>(Q, O, st, KSB(i, 0), VTB(i, 0), KSB(i, 1), VTB(i, 1), biasT, tq, hd, jb * 64, far, sb, hpd, hpe, lane);
.LBB0_1439:
	s_lshl_b32 s2, s30, 1
	s_cmp_lt_u32 s30, 32
	s_cselect_b64 s[42:43], -1, 0
	s_sub_i32 s3, s2, 64
	s_and_b64 s[0:1], s[42:43], exec
	v_cndmask_b32_e64 v3, v47, v45, s[42:43]
	s_cselect_b32 s0, s2, s3
	v_cndmask_b32_e64 v2, v46, v44, s[42:43]
	s_cmp_lt_u32 s2, s28
	v_lshrrev_b64 v[80:81], s0, v[2:3]
	s_cselect_b64 s[0:1], -1, 0
	s_or_b32 s46, s2, 1
	s_sub_i32 s47, s2, 63
	s_and_b64 s[2:3], s[42:43], exec
	s_cselect_b32 s2, s46, s47
	s_lshl_b64 s[2:3], 1, s2
	v_and_b32_e32 v83, s3, v3
	v_and_b32_e32 v82, s2, v2
	v_cmp_ne_u64_e32 vcc, 0, v[82:83]
	s_lshl_b32 s2, s30, 7
	s_and_b64 s[46:47], s[0:1], vcc
	s_sub_i32 s0, s20, s2
	s_cmpk_lt_i32 s0, 0x35e
	v_and_b32_e32 v0, 1, v80
	s_cselect_b64 s[50:51], -1, 0
	s_cmpk_lt_i32 s0, 0x39e
	v_cmp_ne_u32_e32 vcc, 0, v0
	s_cselect_b64 s[48:49], -1, 0
	s_cmp_eq_u64 vcc, 0
	v_cndmask_b32_e64 v80, 0, 1, s[46:47]
	s_cselect_b64 s[0:1], -1, 0
	s_cmp_lg_u64 vcc, 0
	v_cmp_ne_u32_e32 vcc, 0, v80
	s_cselect_b64 s[56:57], -1, 0
	s_cmp_lg_u64 vcc, 0
	s_cselect_b64 s[52:53], -1, 0
	s_and_b64 s[56:57], s[56:57], s[52:53]
	s_andn2_b64 vcc, exec, s[56:57]
	s_cbranch_vccz .LBB0_1480
	s_and_b64 vcc, exec, s[0:1]
	s_cbranch_vccz .LBB0_1481
	v_mov_b64_e32 v[82:83], v[30:31]
	v_mov_b64_e32 v[86:87], v[34:35]
	v_mov_b64_e32 v[90:91], v[38:39]
	v_mov_b64_e32 v[94:95], v[42:43]
	s_mov_b64 s[0:1], 0
	s_and_b64 vcc, exec, s[52:53]
	v_mov_b32_e32 v188, v243
	v_mov_b32_e32 v244, v173
	v_mov_b64_e32 v[80:81], v[28:29]
	v_mov_b64_e32 v[84:85], v[32:33]
	v_mov_b64_e32 v[88:89], v[36:37]
	v_mov_b64_e32 v[92:93], v[40:41]
	s_mov_b64 s[52:53], 0
	s_cbranch_vccz .LBB0_1482
	s_setprio 1
	ds_read_b128 v[80:83], v155 offset:33280
	ds_read_b128 v[84:87], v155 offset:33344
	ds_read_b128 v[88:91], v155 offset:35840
	ds_read_b128 v[92:95], v155 offset:35904
	ds_read_b128 v[96:99], v155 offset:38400
	s_waitcnt lgkmcnt(4)
	v_mfma_f32_16x16x32_f16 v[80:83], v[80:83], v[4:7], 0
	s_waitcnt lgkmcnt(2)
	v_mfma_f32_16x16x32_f16 v[88:91], v[88:91], v[4:7], 0
	v_mfma_f32_16x16x32_f16 v[84:87], v[84:87], v[8:11], v[80:83]
	s_waitcnt lgkmcnt(1)
	v_mfma_f32_16x16x32_f16 v[80:83], v[92:95], v[8:11], v[88:91]
	s_nop 4
	ds_read_b128 v[88:91], v155 offset:38464
	s_waitcnt lgkmcnt(1)
	v_mfma_f32_16x16x32_f16 v[92:95], v[96:99], v[4:7], 0
	ds_read_b128 v[96:99], v155 offset:40960
	s_waitcnt lgkmcnt(1)
	v_mfma_f32_16x16x32_f16 v[92:95], v[88:91], v[8:11], v[92:95]
	ds_read_b128 v[88:91], v155 offset:41024
	s_waitcnt lgkmcnt(1)
	v_mfma_f32_16x16x32_f16 v[96:99], v[96:99], v[4:7], 0
	s_waitcnt lgkmcnt(0)
	v_mfma_f32_16x16x32_f16 v[88:91], v[88:91], v[8:11], v[96:99]
	s_setprio 0
	s_andn2_b64 vcc, exec, s[48:49]
	s_mov_b64 s[52:53], -1
	s_cbranch_vccnz .LBB0_1476
	v_or_b32_e32 v112, s2, v154
	s_nop 0
	v_sub_u32_e32 v98, v175, v112
	v_cmp_lt_i32_e32 vcc, -1, v98
	s_and_b64 s[56:57], vcc, s[46:47]
	v_mov_b32_e32 v97, 0xf149f2ca
	v_mov_b32_e32 v96, 0xf149f2ca
	s_and_saveexec_b64 s[52:53], s[56:57]
	s_cbranch_execz .LBB0_1445
	v_min_u32_e32 v96, 0x31f, v98
	v_lshl_add_u32 v96, v96, 2, v157
	ds_read_b32 v96, v96
.LBB0_1445:
	s_or_b64 exec, exec, s[52:53]
	v_xad_u32 v98, v112, -1, v175
	v_cmp_lt_i32_e32 vcc, -1, v98
	s_and_b64 s[56:57], vcc, s[46:47]
	s_and_saveexec_b64 s[52:53], s[56:57]
	s_cbranch_execz .LBB0_1447
	v_min_u32_e32 v97, 0x31f, v98
	v_lshl_add_u32 v97, v97, 2, v157
	ds_read_b32 v97, v97
.LBB0_1447:
	s_or_b64 exec, exec, s[52:53]
	v_or_b32_e32 v98, 2, v112
	v_sub_u32_e32 v100, v175, v98
	v_cmp_lt_i32_e32 vcc, -1, v100
	s_and_b64 s[56:57], vcc, s[46:47]
	v_mov_b32_e32 v99, 0xf149f2ca
	v_mov_b32_e32 v98, 0xf149f2ca
	s_and_saveexec_b64 s[52:53], s[56:57]
	s_cbranch_execz .LBB0_1449
	v_min_u32_e32 v98, 0x31f, v100
	v_lshl_add_u32 v98, v98, 2, v157
	ds_read_b32 v98, v98
.LBB0_1449:
	s_or_b64 exec, exec, s[52:53]
	v_or_b32_e32 v100, 3, v112
	v_sub_u32_e32 v100, v175, v100
	v_cmp_lt_i32_e32 vcc, -1, v100
	s_and_b64 s[56:57], vcc, s[46:47]
	s_and_saveexec_b64 s[52:53], s[56:57]
	s_cbranch_execz .LBB0_1451
	v_min_u32_e32 v99, 0x31f, v100
	v_lshl_add_u32 v99, v99, 2, v157
	ds_read_b32 v99, v99
.LBB0_1451:
	s_or_b64 exec, exec, s[52:53]
	v_sub_u32_e32 v102, v177, v112
	v_cmp_lt_i32_e32 vcc, -1, v102
	s_and_b64 s[56:57], vcc, s[46:47]
	v_mov_b32_e32 v101, 0xf149f2ca
	v_mov_b32_e32 v100, 0xf149f2ca
	s_and_saveexec_b64 s[52:53], s[56:57]
	s_cbranch_execz .LBB0_1453
	v_min_u32_e32 v100, 0x31f, v102
	v_lshl_add_u32 v100, v100, 2, v157
	ds_read_b32 v100, v100
; template <int MODE, int TM> ...
;     ...
;       const int kx0 = kbase + q4 * 4;
;       const int d0 = (DK == 16) ? tq - 31 - 16 * kx0 : tq - kx0;
; #pragma unroll
;       for (int kt = 0; kt < 4; ++kt)
; #pragma unroll
;         for (int j = 0; j < 4; ++j) {
;           const int dist = d0 - DK * (kt * 16 + j);
;           const int kx = kx0 + kt * 16 + j;
;           bool valid = dist >= 0;
;           if (MODE == M_WIN) valid = valid && dist < 512 && kx >= 0;
;           if (MODE == M_SEL) valid = valid && selbit[t];
;           if (DK == 16) valid = valid && kx < NCMP;
;           const int dc = dist < 0 ? 0 : (dist > 799 ? 799 : dist);
;           S[t][kt][j] = valid ? S[t][kt][j] * SCL2 + bt[dc] : -1e30f;
;         }
.LBB0_1453:
	s_or_b64 exec, exec, s[52:53]
	v_sub_u32_e32 v102, v179, v112
	v_cmp_lt_i32_e32 vcc, -1, v102
	s_and_b64 s[56:57], vcc, s[46:47]
	s_and_saveexec_b64 s[52:53], s[56:57]
	s_cbranch_execz .LBB0_1455
	v_min_u32_e32 v101, 0x31f, v102
	v_lshl_add_u32 v101, v101, 2, v157
	ds_read_b32 v101, v101
.LBB0_1455:
	s_or_b64 exec, exec, s[52:53]
	v_sub_u32_e32 v104, v181, v112
	v_cmp_lt_i32_e32 vcc, -1, v104
	s_and_b64 s[56:57], vcc, s[46:47]
	v_mov_b32_e32 v103, 0xf149f2ca
	v_mov_b32_e32 v102, 0xf149f2ca
	s_and_saveexec_b64 s[52:53], s[56:57]
	s_cbranch_execz .LBB0_1457
	v_min_u32_e32 v102, 0x31f, v104
	v_lshl_add_u32 v102, v102, 2, v157
	ds_read_b32 v102, v102
.LBB0_1457:
	s_or_b64 exec, exec, s[52:53]
	v_sub_u32_e32 v104, v219, v112
	v_cmp_lt_i32_e32 vcc, -1, v104
	s_and_b64 s[56:57], vcc, s[46:47]
	s_and_saveexec_b64 s[52:53], s[56:57]
	s_cbranch_execz .LBB0_1459
	v_min_u32_e32 v103, 0x31f, v104
	v_lshl_add_u32 v103, v103, 2, v157
	ds_read_b32 v103, v103
.LBB0_1459:
	s_or_b64 exec, exec, s[52:53]
	v_sub_u32_e32 v106, v220, v112
	v_cmp_lt_i32_e32 vcc, -1, v106
	s_and_b64 s[56:57], vcc, s[46:47]
	v_mov_b32_e32 v105, 0xf149f2ca
	v_mov_b32_e32 v104, 0xf149f2ca
	s_and_saveexec_b64 s[52:53], s[56:57]
	s_cbranch_execz .LBB0_1461
	v_min_u32_e32 v104, 0x31f, v106
	v_lshl_add_u32 v104, v104, 2, v157
	ds_read_b32 v104, v104
.LBB0_1461:
	s_or_b64 exec, exec, s[52:53]
	v_sub_u32_e32 v106, v221, v112
	v_cmp_lt_i32_e32 vcc, -1, v106
	s_and_b64 s[56:57], vcc, s[46:47]
	s_and_saveexec_b64 s[52:53], s[56:57]
	s_cbranch_execz .LBB0_1463
	v_min_u32_e32 v105, 0x31f, v106
	v_lshl_add_u32 v105, v105, 2, v157
	ds_read_b32 v105, v105
.LBB0_1463:
	s_or_b64 exec, exec, s[52:53]
	v_sub_u32_e32 v108, v222, v112
	v_cmp_lt_i32_e32 vcc, -1, v108
	s_and_b64 s[56:57], vcc, s[46:47]
	v_mov_b32_e32 v107, 0xf149f2ca
	v_mov_b32_e32 v106, 0xf149f2ca
	s_and_saveexec_b64 s[52:53], s[56:57]
	s_cbranch_execz .LBB0_1465
	v_min_u32_e32 v106, 0x31f, v108
	v_lshl_add_u32 v106, v106, 2, v157
	ds_read_b32 v106, v106
.LBB0_1465:
	s_or_b64 exec, exec, s[52:53]
	v_sub_u32_e32 v108, v223, v112
	v_cmp_lt_i32_e32 vcc, -1, v108
	s_and_b64 s[56:57], vcc, s[46:47]
	s_and_saveexec_b64 s[52:53], s[56:57]
	s_cbranch_execz .LBB0_1467
	v_min_u32_e32 v107, 0x31f, v108
	v_lshl_add_u32 v107, v107, 2, v157
	ds_read_b32 v107, v107
.LBB0_1467:
	s_or_b64 exec, exec, s[52:53]
	v_sub_u32_e32 v110, v224, v112
	v_cmp_lt_i32_e32 vcc, -1, v110
	s_and_b64 s[56:57], vcc, s[46:47]
	v_mov_b32_e32 v109, 0xf149f2ca
	v_mov_b32_e32 v108, 0xf149f2ca
	s_and_saveexec_b64 s[52:53], s[56:57]
	s_cbranch_execz .LBB0_1469
	v_min_u32_e32 v108, 0x31f, v110
	v_lshl_add_u32 v108, v108, 2, v157
	ds_read_b32 v108, v108
.LBB0_1469:
	s_or_b64 exec, exec, s[52:53]
	v_sub_u32_e32 v110, v225, v112
	v_cmp_lt_i32_e32 vcc, -1, v110
	s_and_b64 s[56:57], vcc, s[46:47]
	s_and_saveexec_b64 s[52:53], s[56:57]
	s_cbranch_execz .LBB0_1471
	v_min_u32_e32 v109, 0x31f, v110
	v_lshl_add_u32 v109, v109, 2, v157
	ds_read_b32 v109, v109
.LBB0_1471:
	s_or_b64 exec, exec, s[52:53]
	v_sub_u32_e32 v113, v226, v112
	v_cmp_lt_i32_e32 vcc, -1, v113
	s_and_b64 s[56:57], vcc, s[46:47]
	v_mov_b32_e32 v111, 0xf149f2ca
	v_mov_b32_e32 v110, 0xf149f2ca
	s_and_saveexec_b64 s[52:53], s[56:57]
	s_cbranch_execz .LBB0_1473
	v_min_u32_e32 v110, 0x31f, v113
	v_lshl_add_u32 v110, v110, 2, v157
	ds_read_b32 v110, v110
.LBB0_1473:
	s_or_b64 exec, exec, s[52:53]
	v_sub_u32_e32 v112, v227, v112
	v_cmp_lt_i32_e32 vcc, -1, v112
	s_and_b64 s[56:57], vcc, s[46:47]
	s_and_saveexec_b64 s[52:53], s[56:57]
	s_cbranch_execz .LBB0_1475
	v_min_u32_e32 v111, 0x31f, v112
	v_lshl_add_u32 v111, v111, 2, v157
	ds_read_b32 v111, v111
.LBB0_1475:
	s_or_b64 exec, exec, s[52:53]
	s_waitcnt lgkmcnt(0)
	v_fmac_f32_e32 v96, 0x3e38aa3b, v84
	v_fmac_f32_e32 v97, 0x3e38aa3b, v85
	v_fmac_f32_e32 v98, 0x3e38aa3b, v86
	v_fmac_f32_e32 v99, 0x3e38aa3b, v87
	v_fmac_f32_e32 v100, 0x3e38aa3b, v80
	v_fmac_f32_e32 v101, 0x3e38aa3b, v81
	v_fmac_f32_e32 v102, 0x3e38aa3b, v82
	v_fmac_f32_e32 v103, 0x3e38aa3b, v83
	v_fmac_f32_e32 v104, 0x3e38aa3b, v92
	v_fmac_f32_e32 v105, 0x3e38aa3b, v93
	v_fmac_f32_e32 v106, 0x3e38aa3b, v94
	v_fmac_f32_e32 v107, 0x3e38aa3b, v95
	v_fmac_f32_e32 v108, 0x3e38aa3b, v88
	v_fmac_f32_e32 v109, 0x3e38aa3b, v89
	v_fmac_f32_e32 v110, 0x3e38aa3b, v90
	v_fmac_f32_e32 v111, 0x3e38aa3b, v91
	s_mov_b64 s[52:53], 0

; template <int MODE, int TM> ...
;     ...
;   for (int t = 0; t < 2; ++t) {
;     if (!(TM & (1 << t))) continue;
;     const h16* Ks = t ? Ks1 : Ks0;
; #pragma unroll
;     for (int kt = 0; kt < 4; ++kt) {
;       S[t][kt] = f32x4{0.f, 0.f, 0.f, 0.f};
; #pragma unroll
;       for (int ks = 0; ks < 2; ++ks) {
;         h16x8 Kf = *(const h16x8*)(Ks + (kt * 16 + col) * KP + ks * 32 + q4 * 8);
;         S[t][kt] = __builtin_amdgcn_mfma_f32_16x16x32_f16(Kf, Q[ks], S[t][kt], 0, 0, 0);
;       }
;     }
;   }
;   __builtin_amdgcn_s_setprio(0);
;   const float* bt = biasT + hd * 800;
;   float addc[2] = {0.f, 0.f}, sclc[2] = {1.f, 1.f};
; #pragma unroll
;   for (int t = 0; t < 2; ++t) {
;     if (!(TM & (1 << t))) continue;
;     const int kbase = kbase0 + 64 * t;
;     if (far[t]) {
;       const bool ok = (MODE == M_SEL) ? selbit[t] : true;
;       addc[t] = ok ? bt[799] : -1e30f;
;       sclc[t] = SCL2;
;     } else {
;       addc[t] = 0.f;
;       sclc[t] = 1.f;
;       const int kx0 = kbase + q4 * 4;
;       const int d0 = (DK == 16) ? tq - 31 - 16 * kx0 : tq - kx0;
; #pragma unroll
;       for (int kt = 0; kt < 4; ++kt)
; #pragma unroll
;         for (int j = 0; j < 4; ++j) {
;           const int dist = d0 - DK * (kt * 16 + j);
;           const int kx = kx0 + kt * 16 + j;
;           bool valid = dist >= 0;
;           if (MODE == M_WIN) valid = valid && dist < 512 && kx >= 0;
;           if (MODE == M_SEL) valid = valid && selbit[t];
;           if (DK == 16) valid = valid && kx < NCMP;
;           const int dc = dist < 0 ? 0 : (dist > 799 ? 799 : dist);
;           S[t][kt][j] = valid ? S[t][kt][j] * SCL2 + bt[dc] : -1e30f;
;         }
.LBB0_1483:
	s_setprio 1
	ds_read_b128 v[80:83], v155 offset:12800
	ds_read_b128 v[84:87], v155 offset:12864
	ds_read_b128 v[88:91], v155 offset:15360
	ds_read_b128 v[96:99], v155 offset:15424
	s_waitcnt lgkmcnt(3)
	v_mfma_f32_16x16x32_f16 v[80:83], v[80:83], v[4:7], 0
	s_waitcnt lgkmcnt(2)
	v_mfma_f32_16x16x32_f16 v[92:95], v[84:87], v[8:11], v[80:83]
	ds_read_b128 v[84:87], v155 offset:17984
	s_nop 4
	ds_read_b128 v[80:83], v155 offset:17920
	s_waitcnt lgkmcnt(3)
	v_mfma_f32_16x16x32_f16 v[88:91], v[88:91], v[4:7], 0
	s_waitcnt lgkmcnt(2)
	v_mfma_f32_16x16x32_f16 v[88:91], v[96:99], v[8:11], v[88:91]
	ds_read_b128 v[96:99], v155 offset:20480
	s_waitcnt lgkmcnt(1)
	v_mfma_f32_16x16x32_f16 v[80:83], v[80:83], v[4:7], 0
	v_mfma_f32_16x16x32_f16 v[84:87], v[84:87], v[8:11], v[80:83]
	s_nop 6
	ds_read_b128 v[80:83], v155 offset:20544
	s_waitcnt lgkmcnt(1)
	v_mfma_f32_16x16x32_f16 v[96:99], v[96:99], v[4:7], 0
	s_waitcnt lgkmcnt(0)
	v_mfma_f32_16x16x32_f16 v[80:83], v[80:83], v[8:11], v[96:99]
	s_setprio 0
	s_mov_b64 s[0:1], -1
	s_and_b64 vcc, exec, s[50:51]
	s_cbranch_vccz .LBB0_1517
	v_or_b32_e32 v112, s2, v154
	s_nop 0
	v_sub_u32_e32 v98, v182, v112
	v_cmp_lt_i32_e64 s[0:1], -1, v98
	v_cmp_eq_u32_e32 vcc, 1, v0
	s_and_b64 s[52:53], s[0:1], vcc
	v_mov_b32_e32 v97, 0xf149f2ca
	v_mov_b32_e32 v96, 0xf149f2ca
	s_and_saveexec_b64 s[0:1], s[52:53]
	s_cbranch_execz .LBB0_1486
	v_min_u32_e32 v96, 0x31f, v98
	v_lshl_add_u32 v96, v96, 2, v157
	ds_read_b32 v96, v96
.LBB0_1486:
	s_or_b64 exec, exec, s[0:1]
	v_xad_u32 v98, v112, -1, v182
	v_cmp_lt_i32_e64 s[0:1], -1, v98
	s_and_b64 s[52:53], s[0:1], vcc
	s_and_saveexec_b64 s[0:1], s[52:53]
	s_cbranch_execz .LBB0_1488
	v_min_u32_e32 v97, 0x31f, v98
	v_lshl_add_u32 v97, v97, 2, v157
	ds_read_b32 v97, v97
.LBB0_1488:
	s_or_b64 exec, exec, s[0:1]
	v_or_b32_e32 v98, 2, v112
	v_sub_u32_e32 v100, v182, v98
	v_cmp_lt_i32_e64 s[0:1], -1, v100
	s_and_b64 s[52:53], s[0:1], vcc
	v_mov_b32_e32 v99, 0xf149f2ca
	v_mov_b32_e32 v98, 0xf149f2ca
	s_and_saveexec_b64 s[0:1], s[52:53]
	s_cbranch_execz .LBB0_1490
	v_min_u32_e32 v98, 0x31f, v100
	v_lshl_add_u32 v98, v98, 2, v157
	ds_read_b32 v98, v98
.LBB0_1490:
	s_or_b64 exec, exec, s[0:1]
	v_or_b32_e32 v100, 3, v112
	v_sub_u32_e32 v100, v182, v100
	v_cmp_lt_i32_e64 s[0:1], -1, v100
	s_and_b64 s[52:53], s[0:1], vcc
	s_and_saveexec_b64 s[0:1], s[52:53]
	s_cbranch_execz .LBB0_1492
	v_min_u32_e32 v99, 0x31f, v100
	v_lshl_add_u32 v99, v99, 2, v157
	ds_read_b32 v99, v99
.LBB0_1492:
	s_or_b64 exec, exec, s[0:1]
	v_sub_u32_e32 v102, v228, v112
	v_cmp_lt_i32_e64 s[0:1], -1, v102
	s_and_b64 s[52:53], s[0:1], vcc
	v_mov_b32_e32 v101, 0xf149f2ca
	v_mov_b32_e32 v100, 0xf149f2ca
	s_and_saveexec_b64 s[0:1], s[52:53]
	s_cbranch_execz .LBB0_1494
	v_min_u32_e32 v100, 0x31f, v102
	v_lshl_add_u32 v100, v100, 2, v157
	ds_read_b32 v100, v100
.LBB0_1494:
	s_or_b64 exec, exec, s[0:1]
	v_sub_u32_e32 v102, v229, v112
	v_cmp_lt_i32_e64 s[0:1], -1, v102
	s_and_b64 s[52:53], s[0:1], vcc
	s_and_saveexec_b64 s[0:1], s[52:53]
	s_cbranch_execz .LBB0_1496
	v_min_u32_e32 v101, 0x31f, v102
	v_lshl_add_u32 v101, v101, 2, v157
	ds_read_b32 v101, v101
.LBB0_1496:
	s_or_b64 exec, exec, s[0:1]
	v_sub_u32_e32 v104, v230, v112
	v_cmp_lt_i32_e64 s[0:1], -1, v104
	s_and_b64 s[52:53], s[0:1], vcc
	v_mov_b32_e32 v103, 0xf149f2ca
	v_mov_b32_e32 v102, 0xf149f2ca
	s_and_saveexec_b64 s[0:1], s[52:53]
	s_cbranch_execz .LBB0_1498
	v_min_u32_e32 v102, 0x31f, v104
	v_lshl_add_u32 v102, v102, 2, v157
	ds_read_b32 v102, v102
; template <int MODE, int TM> ...
;     ...
;       const int kx0 = kbase + q4 * 4;
;       const int d0 = (DK == 16) ? tq - 31 - 16 * kx0 : tq - kx0;
; #pragma unroll
;       for (int kt = 0; kt < 4; ++kt)
; #pragma unroll
;         for (int j = 0; j < 4; ++j) {
;           const int dist = d0 - DK * (kt * 16 + j);
;           const int kx = kx0 + kt * 16 + j;
;           bool valid = dist >= 0;
;           if (MODE == M_WIN) valid = valid && dist < 512 && kx >= 0;
;           if (MODE == M_SEL) valid = valid && selbit[t];
;           if (DK == 16) valid = valid && kx < NCMP;
;           const int dc = dist < 0 ? 0 : (dist > 799 ? 799 : dist);
;           S[t][kt][j] = valid ? S[t][kt][j] * SCL2 + bt[dc] : -1e30f;
;         }
.LBB0_1498:
	s_or_b64 exec, exec, s[0:1]
	v_sub_u32_e32 v104, v231, v112
	v_cmp_lt_i32_e64 s[0:1], -1, v104
	s_and_b64 s[52:53], s[0:1], vcc
	s_and_saveexec_b64 s[0:1], s[52:53]
	s_cbranch_execz .LBB0_1500
	v_min_u32_e32 v103, 0x31f, v104
	v_lshl_add_u32 v103, v103, 2, v157
	ds_read_b32 v103, v103
.LBB0_1500:
	s_or_b64 exec, exec, s[0:1]
	v_sub_u32_e32 v106, v232, v112
	v_cmp_lt_i32_e64 s[0:1], -1, v106
	s_and_b64 s[52:53], s[0:1], vcc
	v_mov_b32_e32 v105, 0xf149f2ca
	v_mov_b32_e32 v104, 0xf149f2ca
	s_and_saveexec_b64 s[0:1], s[52:53]
	s_cbranch_execz .LBB0_1502
	v_min_u32_e32 v104, 0x31f, v106
	v_lshl_add_u32 v104, v104, 2, v157
	ds_read_b32 v104, v104
.LBB0_1502:
	s_or_b64 exec, exec, s[0:1]
	v_sub_u32_e32 v106, v233, v112
	v_cmp_lt_i32_e64 s[0:1], -1, v106
	s_and_b64 s[52:53], s[0:1], vcc
	s_and_saveexec_b64 s[0:1], s[52:53]
	s_cbranch_execz .LBB0_1504
	v_min_u32_e32 v105, 0x31f, v106
	v_lshl_add_u32 v105, v105, 2, v157
	ds_read_b32 v105, v105
.LBB0_1504:
	s_or_b64 exec, exec, s[0:1]
	v_sub_u32_e32 v108, v234, v112
	v_cmp_lt_i32_e64 s[0:1], -1, v108
	s_and_b64 s[52:53], s[0:1], vcc
	v_mov_b32_e32 v107, 0xf149f2ca
	v_mov_b32_e32 v106, 0xf149f2ca
	s_and_saveexec_b64 s[0:1], s[52:53]
	s_cbranch_execz .LBB0_1506
	v_min_u32_e32 v106, 0x31f, v108
	v_lshl_add_u32 v106, v106, 2, v157
	ds_read_b32 v106, v106
.LBB0_1506:
	s_or_b64 exec, exec, s[0:1]
	v_sub_u32_e32 v108, v235, v112
	v_cmp_lt_i32_e64 s[0:1], -1, v108
	s_and_b64 s[52:53], s[0:1], vcc
	s_and_saveexec_b64 s[0:1], s[52:53]
	s_cbranch_execz .LBB0_1508
	v_min_u32_e32 v107, 0x31f, v108
	v_lshl_add_u32 v107, v107, 2, v157
	ds_read_b32 v107, v107
.LBB0_1508:
	s_or_b64 exec, exec, s[0:1]
	v_sub_u32_e32 v110, v236, v112
	v_cmp_lt_i32_e64 s[0:1], -1, v110
	s_and_b64 s[52:53], s[0:1], vcc
	v_mov_b32_e32 v109, 0xf149f2ca
	v_mov_b32_e32 v108, 0xf149f2ca
	s_and_saveexec_b64 s[0:1], s[52:53]
	s_cbranch_execz .LBB0_1510
	v_min_u32_e32 v108, 0x31f, v110
	v_lshl_add_u32 v108, v108, 2, v157
	ds_read_b32 v108, v108
.LBB0_1510:
	s_or_b64 exec, exec, s[0:1]
	v_sub_u32_e32 v110, v237, v112
	v_cmp_lt_i32_e64 s[0:1], -1, v110
	s_and_b64 s[52:53], s[0:1], vcc
	s_and_saveexec_b64 s[0:1], s[52:53]
	s_cbranch_execz .LBB0_1512
	v_min_u32_e32 v109, 0x31f, v110
	v_lshl_add_u32 v109, v109, 2, v157
	ds_read_b32 v109, v109
.LBB0_1512:
	s_or_b64 exec, exec, s[0:1]
	v_sub_u32_e32 v113, v238, v112
	v_cmp_lt_i32_e64 s[0:1], -1, v113
	s_and_b64 s[52:53], s[0:1], vcc
	v_mov_b32_e32 v111, 0xf149f2ca
	v_mov_b32_e32 v110, 0xf149f2ca
	s_and_saveexec_b64 s[0:1], s[52:53]
	s_cbranch_execz .LBB0_1514
	v_min_u32_e32 v110, 0x31f, v113
	v_lshl_add_u32 v110, v110, 2, v157
	ds_read_b32 v110, v110
.LBB0_1514:
	s_or_b64 exec, exec, s[0:1]
	v_sub_u32_e32 v112, v239, v112
	v_cmp_lt_i32_e64 s[0:1], -1, v112
	s_and_b64 s[52:53], s[0:1], vcc
	s_and_saveexec_b64 s[0:1], s[52:53]
	s_cbranch_execz .LBB0_1516
	v_min_u32_e32 v111, 0x31f, v112
	v_lshl_add_u32 v111, v111, 2, v157
	ds_read_b32 v111, v111
.LBB0_1516:
	s_or_b64 exec, exec, s[0:1]
	s_waitcnt lgkmcnt(0)
	v_fmac_f32_e32 v96, 0x3e38aa3b, v92
	v_fmac_f32_e32 v97, 0x3e38aa3b, v93
	v_fmac_f32_e32 v98, 0x3e38aa3b, v94
	v_fmac_f32_e32 v99, 0x3e38aa3b, v95
	v_fmac_f32_e32 v100, 0x3e38aa3b, v88
	v_fmac_f32_e32 v101, 0x3e38aa3b, v89
	v_fmac_f32_e32 v102, 0x3e38aa3b, v90
	v_fmac_f32_e32 v103, 0x3e38aa3b, v91
	v_fmac_f32_e32 v104, 0x3e38aa3b, v84
	v_fmac_f32_e32 v105, 0x3e38aa3b, v85
	v_fmac_f32_e32 v106, 0x3e38aa3b, v86
	v_fmac_f32_e32 v107, 0x3e38aa3b, v87
	v_fmac_f32_e32 v108, 0x3e38aa3b, v80
	v_fmac_f32_e32 v109, 0x3e38aa3b, v81
	v_fmac_f32_e32 v110, 0x3e38aa3b, v82
	v_fmac_f32_e32 v111, 0x3e38aa3b, v83
	s_mov_b64 s[0:1], 0

; template <int MODE, int TM> ...
;     ...
;   for (int t = 0; t < 2; ++t) {
;     if (!(TM & (1 << t))) continue;
;     const h16* Ks = t ? Ks1 : Ks0;
; #pragma unroll
;     for (int kt = 0; kt < 4; ++kt) {
;       S[t][kt] = f32x4{0.f, 0.f, 0.f, 0.f};
; #pragma unroll
;       for (int ks = 0; ks < 2; ++ks) {
;         h16x8 Kf = *(const h16x8*)(Ks + (kt * 16 + col) * KP + ks * 32 + q4 * 8);
;         S[t][kt] = __builtin_amdgcn_mfma_f32_16x16x32_f16(Kf, Q[ks], S[t][kt], 0, 0, 0);
;       }
;     }
;   }
;   __builtin_amdgcn_s_setprio(0);
;   const float* bt = biasT + hd * 800;
;   float addc[2] = {0.f, 0.f}, sclc[2] = {1.f, 1.f};
; #pragma unroll
;   for (int t = 0; t < 2; ++t) {
;     if (!(TM & (1 << t))) continue;
;     const int kbase = kbase0 + 64 * t;
;     if (far[t]) {
;       const bool ok = (MODE == M_SEL) ? selbit[t] : true;
;       addc[t] = ok ? bt[799] : -1e30f;
;       sclc[t] = SCL2;
;     } else {
;       addc[t] = 0.f;
;       sclc[t] = 1.f;
;       const int kx0 = kbase + q4 * 4;
;       const int d0 = (DK == 16) ? tq - 31 - 16 * kx0 : tq - kx0;
; #pragma unroll
;       for (int kt = 0; kt < 4; ++kt)
; #pragma unroll
;         for (int j = 0; j < 4; ++j) {
;           const int dist = d0 - DK * (kt * 16 + j);
;           const int kx = kx0 + kt * 16 + j;
;           bool valid = dist >= 0;
;           if (MODE == M_WIN) valid = valid && dist < 512 && kx >= 0;
;           if (MODE == M_SEL) valid = valid && selbit[t];
;           if (DK == 16) valid = valid && kx < NCMP;
;           const int dc = dist < 0 ? 0 : (dist > 799 ? 799 : dist);
;           S[t][kt][j] = valid ? S[t][kt][j] * SCL2 + bt[dc] : -1e30f;
;         }
.LBB0_1526:
	s_setprio 1
	ds_read_b128 v[80:83], v155 offset:12800
	ds_read_b128 v[84:87], v155 offset:12864
	ds_read_b128 v[88:91], v155 offset:15360
	ds_read_b128 v[96:99], v155 offset:15424
	ds_read_b128 v[100:103], v155 offset:33280
	ds_read_b128 v[104:107], v155 offset:35840
	s_waitcnt lgkmcnt(5)
	v_mfma_f32_16x16x32_f16 v[80:83], v[80:83], v[4:7], 0
	ds_read_b128 v[108:111], v155 offset:38400
	ds_read_b128 v[112:115], v155 offset:40960
	s_waitcnt lgkmcnt(6)
	v_mfma_f32_16x16x32_f16 v[92:95], v[84:87], v[8:11], v[80:83]
	ds_read_b128 v[84:87], v155 offset:17984
	s_nop 2
	ds_read_b128 v[80:83], v155 offset:17920
	s_waitcnt lgkmcnt(7)
	v_mfma_f32_16x16x32_f16 v[88:91], v[88:91], v[4:7], 0
	s_waitcnt lgkmcnt(6)
	v_mfma_f32_16x16x32_f16 v[88:91], v[96:99], v[8:11], v[88:91]
	ds_read_b128 v[96:99], v155 offset:20480
	s_waitcnt lgkmcnt(1)
	v_mfma_f32_16x16x32_f16 v[80:83], v[80:83], v[4:7], 0
	v_mfma_f32_16x16x32_f16 v[84:87], v[84:87], v[8:11], v[80:83]
	s_nop 6
	ds_read_b128 v[80:83], v155 offset:20544
	s_waitcnt lgkmcnt(1)
	v_mfma_f32_16x16x32_f16 v[96:99], v[96:99], v[4:7], 0
	s_waitcnt lgkmcnt(0)
	v_mfma_f32_16x16x32_f16 v[80:83], v[80:83], v[8:11], v[96:99]
	s_nop 5
	ds_read_b128 v[96:99], v155 offset:33344
	v_mfma_f32_16x16x32_f16 v[100:103], v[100:103], v[4:7], 0
	s_waitcnt lgkmcnt(0)
	v_mfma_f32_16x16x32_f16 v[96:99], v[96:99], v[8:11], v[100:103]
	s_nop 5
	ds_read_b128 v[100:103], v155 offset:35904
	v_mfma_f32_16x16x32_f16 v[104:107], v[104:107], v[4:7], 0
	s_waitcnt lgkmcnt(0)
	v_mfma_f32_16x16x32_f16 v[100:103], v[100:103], v[8:11], v[104:107]
	s_nop 5
	ds_read_b128 v[104:107], v155 offset:38464
	v_mfma_f32_16x16x32_f16 v[108:111], v[108:111], v[4:7], 0
	s_waitcnt lgkmcnt(0)
	v_mfma_f32_16x16x32_f16 v[104:107], v[104:107], v[8:11], v[108:111]
	s_nop 5
	ds_read_b128 v[108:111], v155 offset:41024
	v_mfma_f32_16x16x32_f16 v[112:115], v[112:115], v[4:7], 0
	s_waitcnt lgkmcnt(0)
	v_mfma_f32_16x16x32_f16 v[108:111], v[108:111], v[8:11], v[112:115]
	s_setprio 0
	v_or_b32_e32 v244, s2, v154
	s_mov_b64 s[0:1], -1
	s_and_b64 vcc, exec, s[50:51]
	s_cbranch_vccz .LBB0_1560
	s_nop 0
	v_sub_u32_e32 v114, v182, v244
	v_cmp_lt_i32_e64 s[0:1], -1, v114
	v_cmp_eq_u32_e32 vcc, 1, v0
	s_and_b64 s[2:3], s[0:1], vcc
	v_mov_b32_e32 v113, 0xf149f2ca
	v_mov_b32_e32 v112, 0xf149f2ca
	s_and_saveexec_b64 s[0:1], s[2:3]
	s_cbranch_execz .LBB0_1529
	v_min_u32_e32 v112, 0x31f, v114
	v_lshl_add_u32 v112, v112, 2, v157
	ds_read_b32 v112, v112
.LBB0_1529:
	s_or_b64 exec, exec, s[0:1]
	v_xad_u32 v114, v244, -1, v182
	v_cmp_lt_i32_e64 s[0:1], -1, v114
	s_and_b64 s[2:3], s[0:1], vcc
	s_and_saveexec_b64 s[0:1], s[2:3]
	s_cbranch_execz .LBB0_1531
	v_min_u32_e32 v113, 0x31f, v114
	v_lshl_add_u32 v113, v113, 2, v157
	ds_read_b32 v113, v113
.LBB0_1531:
	s_or_b64 exec, exec, s[0:1]
	v_or_b32_e32 v114, 2, v244
	v_sub_u32_e32 v116, v182, v114
	v_cmp_lt_i32_e64 s[0:1], -1, v116
	s_and_b64 s[2:3], s[0:1], vcc
	v_mov_b32_e32 v115, 0xf149f2ca
	v_mov_b32_e32 v114, 0xf149f2ca
	s_and_saveexec_b64 s[0:1], s[2:3]
	s_cbranch_execz .LBB0_1533
	v_min_u32_e32 v114, 0x31f, v116
	v_lshl_add_u32 v114, v114, 2, v157
	ds_read_b32 v114, v114
.LBB0_1533:
	s_or_b64 exec, exec, s[0:1]
	v_or_b32_e32 v116, 3, v244
	v_sub_u32_e32 v116, v182, v116
	v_cmp_lt_i32_e64 s[0:1], -1, v116
	s_and_b64 s[2:3], s[0:1], vcc
	s_and_saveexec_b64 s[0:1], s[2:3]
	s_cbranch_execz .LBB0_1535
	v_min_u32_e32 v115, 0x31f, v116
	v_lshl_add_u32 v115, v115, 2, v157
	ds_read_b32 v115, v115
.LBB0_1535:
	s_or_b64 exec, exec, s[0:1]
	v_sub_u32_e32 v118, v228, v244
	v_cmp_lt_i32_e64 s[0:1], -1, v118
	s_and_b64 s[2:3], s[0:1], vcc
	v_mov_b32_e32 v117, 0xf149f2ca
	v_mov_b32_e32 v116, 0xf149f2ca
	s_and_saveexec_b64 s[0:1], s[2:3]
	s_cbranch_execz .LBB0_1537
	v_min_u32_e32 v116, 0x31f, v118
	v_lshl_add_u32 v116, v116, 2, v157
	ds_read_b32 v116, v116
.LBB0_1537:
	s_or_b64 exec, exec, s[0:1]
	v_sub_u32_e32 v118, v229, v244
	v_cmp_lt_i32_e64 s[0:1], -1, v118
	s_and_b64 s[2:3], s[0:1], vcc
	s_and_saveexec_b64 s[0:1], s[2:3]
	s_cbranch_execz .LBB0_1539
	v_min_u32_e32 v117, 0x31f, v118
	v_lshl_add_u32 v117, v117, 2, v157
	ds_read_b32 v117, v117
; template <int MODE, int TM> ...
;     ...
;       const int kx0 = kbase + q4 * 4;
;       const int d0 = (DK == 16) ? tq - 31 - 16 * kx0 : tq - kx0;
; #pragma unroll
;       for (int kt = 0; kt < 4; ++kt)
; #pragma unroll
;         for (int j = 0; j < 4; ++j) {
;           const int dist = d0 - DK * (kt * 16 + j);
;           const int kx = kx0 + kt * 16 + j;
;           bool valid = dist >= 0;
;           if (MODE == M_WIN) valid = valid && dist < 512 && kx >= 0;
;           if (MODE == M_SEL) valid = valid && selbit[t];
;           if (DK == 16) valid = valid && kx < NCMP;
;           const int dc = dist < 0 ? 0 : (dist > 799 ? 799 : dist);
;           S[t][kt][j] = valid ? S[t][kt][j] * SCL2 + bt[dc] : -1e30f;
;         }
.LBB0_1539:
	s_or_b64 exec, exec, s[0:1]
	v_sub_u32_e32 v120, v230, v244
	v_cmp_lt_i32_e64 s[0:1], -1, v120
	s_and_b64 s[2:3], s[0:1], vcc
	v_mov_b32_e32 v119, 0xf149f2ca
	v_mov_b32_e32 v118, 0xf149f2ca
	s_and_saveexec_b64 s[0:1], s[2:3]
	s_cbranch_execz .LBB0_1541
	v_min_u32_e32 v118, 0x31f, v120
	v_lshl_add_u32 v118, v118, 2, v157
	ds_read_b32 v118, v118
.LBB0_1541:
	s_or_b64 exec, exec, s[0:1]
	v_sub_u32_e32 v120, v231, v244
	v_cmp_lt_i32_e64 s[0:1], -1, v120
	s_and_b64 s[2:3], s[0:1], vcc
	s_and_saveexec_b64 s[0:1], s[2:3]
	s_cbranch_execz .LBB0_1543
	v_min_u32_e32 v119, 0x31f, v120
	v_lshl_add_u32 v119, v119, 2, v157
	ds_read_b32 v119, v119
.LBB0_1543:
	s_or_b64 exec, exec, s[0:1]
	v_sub_u32_e32 v122, v232, v244
	v_cmp_lt_i32_e64 s[0:1], -1, v122
	s_and_b64 s[2:3], s[0:1], vcc
	v_mov_b32_e32 v121, 0xf149f2ca
	v_mov_b32_e32 v120, 0xf149f2ca
	s_and_saveexec_b64 s[0:1], s[2:3]
	s_cbranch_execz .LBB0_1545
	v_min_u32_e32 v120, 0x31f, v122
	v_lshl_add_u32 v120, v120, 2, v157
	ds_read_b32 v120, v120
.LBB0_1545:
	s_or_b64 exec, exec, s[0:1]
	v_sub_u32_e32 v122, v233, v244
	v_cmp_lt_i32_e64 s[0:1], -1, v122
	s_and_b64 s[2:3], s[0:1], vcc
	s_and_saveexec_b64 s[0:1], s[2:3]
	s_cbranch_execz .LBB0_1547
	v_min_u32_e32 v121, 0x31f, v122
	v_lshl_add_u32 v121, v121, 2, v157
	ds_read_b32 v121, v121
.LBB0_1547:
	s_or_b64 exec, exec, s[0:1]
	v_sub_u32_e32 v124, v234, v244
	v_cmp_lt_i32_e64 s[0:1], -1, v124
	s_and_b64 s[2:3], s[0:1], vcc
	v_mov_b32_e32 v123, 0xf149f2ca
	v_mov_b32_e32 v122, 0xf149f2ca
	s_and_saveexec_b64 s[0:1], s[2:3]
	s_cbranch_execz .LBB0_1549
	v_min_u32_e32 v122, 0x31f, v124
	v_lshl_add_u32 v122, v122, 2, v157
	ds_read_b32 v122, v122
.LBB0_1549:
	s_or_b64 exec, exec, s[0:1]
	v_sub_u32_e32 v124, v235, v244
	v_cmp_lt_i32_e64 s[0:1], -1, v124
	s_and_b64 s[2:3], s[0:1], vcc
	s_and_saveexec_b64 s[0:1], s[2:3]
	s_cbranch_execz .LBB0_1551
	v_min_u32_e32 v123, 0x31f, v124
	v_lshl_add_u32 v123, v123, 2, v157
	ds_read_b32 v123, v123
.LBB0_1551:
	s_or_b64 exec, exec, s[0:1]
	v_sub_u32_e32 v126, v236, v244
	v_cmp_lt_i32_e64 s[0:1], -1, v126
	s_and_b64 s[2:3], s[0:1], vcc
	v_mov_b32_e32 v125, 0xf149f2ca
	v_mov_b32_e32 v124, 0xf149f2ca
	s_and_saveexec_b64 s[0:1], s[2:3]
	s_cbranch_execz .LBB0_1553
	v_min_u32_e32 v124, 0x31f, v126
	v_lshl_add_u32 v124, v124, 2, v157
	ds_read_b32 v124, v124
.LBB0_1553:
	s_or_b64 exec, exec, s[0:1]
	v_sub_u32_e32 v126, v237, v244
	v_cmp_lt_i32_e64 s[0:1], -1, v126
	s_and_b64 s[2:3], s[0:1], vcc
	s_and_saveexec_b64 s[0:1], s[2:3]
	s_cbranch_execz .LBB0_1555
	v_min_u32_e32 v125, 0x31f, v126
	v_lshl_add_u32 v125, v125, 2, v157
	ds_read_b32 v125, v125
.LBB0_1555:
	s_or_b64 exec, exec, s[0:1]
	v_sub_u32_e32 v188, v238, v244
	v_cmp_lt_i32_e64 s[0:1], -1, v188
	s_and_b64 s[2:3], s[0:1], vcc
	v_mov_b32_e32 v127, 0xf149f2ca
	v_mov_b32_e32 v126, 0xf149f2ca
	s_and_saveexec_b64 s[0:1], s[2:3]
	s_cbranch_execz .LBB0_1557
	v_min_u32_e32 v126, 0x31f, v188
	v_lshl_add_u32 v126, v126, 2, v157
	ds_read_b32 v126, v126
.LBB0_1557:
	s_or_b64 exec, exec, s[0:1]
	v_sub_u32_e32 v188, v239, v244
	v_cmp_lt_i32_e64 s[0:1], -1, v188
	s_and_b64 s[2:3], s[0:1], vcc
	s_and_saveexec_b64 s[0:1], s[2:3]
	s_cbranch_execz .LBB0_1559
	v_min_u32_e32 v127, 0x31f, v188
	v_lshl_add_u32 v127, v127, 2, v157
	ds_read_b32 v127, v127
.LBB0_1559:
	s_or_b64 exec, exec, s[0:1]
	s_waitcnt lgkmcnt(0)
	v_fmac_f32_e32 v112, 0x3e38aa3b, v92
	v_fmac_f32_e32 v113, 0x3e38aa3b, v93
	v_fmac_f32_e32 v114, 0x3e38aa3b, v94
	v_fmac_f32_e32 v115, 0x3e38aa3b, v95
	v_fmac_f32_e32 v116, 0x3e38aa3b, v88
	v_fmac_f32_e32 v117, 0x3e38aa3b, v89
	v_fmac_f32_e32 v118, 0x3e38aa3b, v90
	v_fmac_f32_e32 v119, 0x3e38aa3b, v91
	v_fmac_f32_e32 v120, 0x3e38aa3b, v84
	v_fmac_f32_e32 v121, 0x3e38aa3b, v85
	v_fmac_f32_e32 v122, 0x3e38aa3b, v86
	v_fmac_f32_e32 v123, 0x3e38aa3b, v87
	v_fmac_f32_e32 v124, 0x3e38aa3b, v80
	v_fmac_f32_e32 v125, 0x3e38aa3b, v81
	v_fmac_f32_e32 v126, 0x3e38aa3b, v82
	v_fmac_f32_e32 v127, 0x3e38aa3b, v83
	s_mov_b64 s[0:1], 0

; template <int MODE, int TM> ...
;     ...
;       const int kx0 = kbase + q4 * 4;
;       const int d0 = (DK == 16) ? tq - 31 - 16 * kx0 : tq - kx0;
; #pragma unroll
;       for (int kt = 0; kt < 4; ++kt)
; #pragma unroll
;         for (int j = 0; j < 4; ++j) {
;           const int dist = d0 - DK * (kt * 16 + j);
;           const int kx = kx0 + kt * 16 + j;
;           bool valid = dist >= 0;
;           if (MODE == M_WIN) valid = valid && dist < 512 && kx >= 0;
;           if (MODE == M_SEL) valid = valid && selbit[t];
;           if (DK == 16) valid = valid && kx < NCMP;
;           const int dc = dist < 0 ? 0 : (dist > 799 ? 799 : dist);
;           S[t][kt][j] = valid ? S[t][kt][j] * SCL2 + bt[dc] : -1e30f;
;         }
.LBB0_1565:
	v_sub_u32_e32 v114, v175, v244
	v_cmp_lt_i32_e32 vcc, -1, v114
	s_and_b64 s[48:49], vcc, s[46:47]
	v_mov_b32_e32 v113, 0xf149f2ca
	v_mov_b32_e32 v112, 0xf149f2ca
	s_and_saveexec_b64 s[0:1], s[48:49]
	s_cbranch_execz .LBB0_1567
	v_min_u32_e32 v112, 0x31f, v114
	v_lshl_add_u32 v112, v112, 2, v157
	ds_read_b32 v112, v112
.LBB0_1567:
	s_or_b64 exec, exec, s[0:1]
	v_sub_u32_e32 v114, v240, v244
	v_cmp_lt_i32_e32 vcc, -1, v114
	s_and_b64 s[48:49], vcc, s[46:47]
	s_and_saveexec_b64 s[0:1], s[48:49]
	s_cbranch_execz .LBB0_1569
	v_min_u32_e32 v113, 0x31f, v114
	v_lshl_add_u32 v113, v113, 2, v157
	ds_read_b32 v113, v113
.LBB0_1569:
	s_or_b64 exec, exec, s[0:1]
	v_sub_u32_e32 v116, v241, v244
	v_cmp_lt_i32_e32 vcc, -1, v116
	s_and_b64 s[48:49], vcc, s[46:47]
	v_mov_b32_e32 v115, 0xf149f2ca
	v_mov_b32_e32 v114, 0xf149f2ca
	s_and_saveexec_b64 s[0:1], s[48:49]
	s_cbranch_execz .LBB0_1571
	v_min_u32_e32 v114, 0x31f, v116
	v_lshl_add_u32 v114, v114, 2, v157
	ds_read_b32 v114, v114
.LBB0_1571:
	s_or_b64 exec, exec, s[0:1]
	v_sub_u32_e32 v116, v242, v244
	v_cmp_lt_i32_e32 vcc, -1, v116
	s_and_b64 s[48:49], vcc, s[46:47]
	s_and_saveexec_b64 s[0:1], s[48:49]
	s_cbranch_execz .LBB0_1573
	v_min_u32_e32 v115, 0x31f, v116
	v_lshl_add_u32 v115, v115, 2, v157
	ds_read_b32 v115, v115
.LBB0_1573:
	s_or_b64 exec, exec, s[0:1]
	v_sub_u32_e32 v118, v177, v244
	v_cmp_lt_i32_e32 vcc, -1, v118
	s_and_b64 s[48:49], vcc, s[46:47]
	v_mov_b32_e32 v117, 0xf149f2ca
	v_mov_b32_e32 v116, 0xf149f2ca
	s_and_saveexec_b64 s[0:1], s[48:49]
	s_cbranch_execz .LBB0_1575
	v_min_u32_e32 v116, 0x31f, v118
	v_lshl_add_u32 v116, v116, 2, v157
	ds_read_b32 v116, v116
.LBB0_1575:
	s_or_b64 exec, exec, s[0:1]
	v_sub_u32_e32 v118, v179, v244
	v_cmp_lt_i32_e32 vcc, -1, v118
	s_and_b64 s[48:49], vcc, s[46:47]
	s_and_saveexec_b64 s[0:1], s[48:49]
	s_cbranch_execz .LBB0_1577
	v_min_u32_e32 v117, 0x31f, v118
	v_lshl_add_u32 v117, v117, 2, v157
	ds_read_b32 v117, v117
.LBB0_1577:
	s_or_b64 exec, exec, s[0:1]
	v_sub_u32_e32 v120, v181, v244
	v_cmp_lt_i32_e32 vcc, -1, v120
	s_and_b64 s[48:49], vcc, s[46:47]
	v_mov_b32_e32 v119, 0xf149f2ca
	v_mov_b32_e32 v118, 0xf149f2ca
	s_and_saveexec_b64 s[0:1], s[48:49]
	s_cbranch_execz .LBB0_1579
	v_min_u32_e32 v118, 0x31f, v120
	v_lshl_add_u32 v118, v118, 2, v157
	ds_read_b32 v118, v118
.LBB0_1579:
	s_or_b64 exec, exec, s[0:1]
	v_sub_u32_e32 v120, v219, v244
	v_cmp_lt_i32_e32 vcc, -1, v120
	s_and_b64 s[48:49], vcc, s[46:47]
	s_and_saveexec_b64 s[0:1], s[48:49]
	s_cbranch_execz .LBB0_1581
	v_min_u32_e32 v119, 0x31f, v120
	v_lshl_add_u32 v119, v119, 2, v157
	ds_read_b32 v119, v119
.LBB0_1581:
	s_or_b64 exec, exec, s[0:1]
	v_sub_u32_e32 v122, v220, v244
	v_cmp_lt_i32_e32 vcc, -1, v122
	s_and_b64 s[48:49], vcc, s[46:47]
	v_mov_b32_e32 v121, 0xf149f2ca
	v_mov_b32_e32 v120, 0xf149f2ca
	s_and_saveexec_b64 s[0:1], s[48:49]
	s_cbranch_execz .LBB0_1583
	v_min_u32_e32 v120, 0x31f, v122
	v_lshl_add_u32 v120, v120, 2, v157
	ds_read_b32 v120, v120
.LBB0_1583:
	s_or_b64 exec, exec, s[0:1]
	v_sub_u32_e32 v122, v221, v244
	v_cmp_lt_i32_e32 vcc, -1, v122
	s_and_b64 s[48:49], vcc, s[46:47]
	s_and_saveexec_b64 s[0:1], s[48:49]
	s_cbranch_execz .LBB0_1585
	v_min_u32_e32 v121, 0x31f, v122
	v_lshl_add_u32 v121, v121, 2, v157
	ds_read_b32 v121, v121
.LBB0_1585:
	s_or_b64 exec, exec, s[0:1]
	v_sub_u32_e32 v124, v222, v244
	v_cmp_lt_i32_e32 vcc, -1, v124
	s_and_b64 s[48:49], vcc, s[46:47]
	v_mov_b32_e32 v123, 0xf149f2ca
	v_mov_b32_e32 v122, 0xf149f2ca
	s_and_saveexec_b64 s[0:1], s[48:49]
	s_cbranch_execz .LBB0_1587
	v_min_u32_e32 v122, 0x31f, v124
	v_lshl_add_u32 v122, v122, 2, v157
	ds_read_b32 v122, v122
.LBB0_1587:
	s_or_b64 exec, exec, s[0:1]
	v_sub_u32_e32 v124, v223, v244
	v_cmp_lt_i32_e32 vcc, -1, v124
	s_and_b64 s[48:49], vcc, s[46:47]
	s_and_saveexec_b64 s[0:1], s[48:49]
	s_cbranch_execz .LBB0_1589
	v_min_u32_e32 v123, 0x31f, v124
	v_lshl_add_u32 v123, v123, 2, v157
	ds_read_b32 v123, v123
.LBB0_1589:
	s_or_b64 exec, exec, s[0:1]
	v_sub_u32_e32 v126, v224, v244
	v_cmp_lt_i32_e32 vcc, -1, v126
	s_and_b64 s[48:49], vcc, s[46:47]
	v_mov_b32_e32 v125, 0xf149f2ca
	v_mov_b32_e32 v124, 0xf149f2ca
	s_and_saveexec_b64 s[0:1], s[48:49]
	s_cbranch_execz .LBB0_1591
	v_min_u32_e32 v124, 0x31f, v126
	v_lshl_add_u32 v124, v124, 2, v157
	ds_read_b32 v124, v124
.LBB0_1591:
	s_or_b64 exec, exec, s[0:1]
	v_sub_u32_e32 v126, v225, v244
	v_cmp_lt_i32_e32 vcc, -1, v126
	s_and_b64 s[48:49], vcc, s[46:47]
	s_and_saveexec_b64 s[0:1], s[48:49]
	s_cbranch_execz .LBB0_1593
	v_min_u32_e32 v125, 0x31f, v126
	v_lshl_add_u32 v125, v125, 2, v157
	ds_read_b32 v125, v125
.LBB0_1593:
	s_or_b64 exec, exec, s[0:1]
	v_sub_u32_e32 v188, v226, v244
	v_cmp_lt_i32_e32 vcc, -1, v188
	s_and_b64 s[48:49], vcc, s[46:47]
	v_mov_b32_e32 v127, 0xf149f2ca
	v_mov_b32_e32 v126, 0xf149f2ca
	s_and_saveexec_b64 s[0:1], s[48:49]
	s_cbranch_execz .LBB0_1595
	v_min_u32_e32 v126, 0x31f, v188
	v_lshl_add_u32 v126, v126, 2, v157
	ds_read_b32 v126, v126
.LBB0_1595:
	s_or_b64 exec, exec, s[0:1]
	v_sub_u32_e32 v188, v227, v244
	v_cmp_lt_i32_e32 vcc, -1, v188
	s_and_b64 s[48:49], vcc, s[46:47]
	s_and_saveexec_b64 s[0:1], s[48:49]
	s_cbranch_execz .LBB0_1597
	v_min_u32_e32 v127, 0x31f, v188
	v_lshl_add_u32 v127, v127, 2, v157
	ds_read_b32 v127, v127
.LBB0_1597:
	s_or_b64 exec, exec, s[0:1]
	s_waitcnt lgkmcnt(0)
	v_fmac_f32_e32 v112, 0x3e38aa3b, v96
	v_fmac_f32_e32 v113, 0x3e38aa3b, v97
	v_fmac_f32_e32 v114, 0x3e38aa3b, v98
	v_fmac_f32_e32 v115, 0x3e38aa3b, v99
	v_fmac_f32_e32 v116, 0x3e38aa3b, v100
	v_fmac_f32_e32 v117, 0x3e38aa3b, v101
	v_fmac_f32_e32 v118, 0x3e38aa3b, v102
	v_fmac_f32_e32 v119, 0x3e38aa3b, v103
	v_fmac_f32_e32 v120, 0x3e38aa3b, v104
	v_fmac_f32_e32 v121, 0x3e38aa3b, v105
	v_fmac_f32_e32 v122, 0x3e38aa3b, v106
	v_fmac_f32_e32 v123, 0x3e38aa3b, v107
	v_fmac_f32_e32 v124, 0x3e38aa3b, v108
	v_fmac_f32_e32 v125, 0x3e38aa3b, v109
	v_fmac_f32_e32 v126, 0x3e38aa3b, v110
	v_fmac_f32_e32 v127, 0x3e38aa3b, v111
	s_mov_b64 s[0:1], 0
	s_waitcnt lgkmcnt(0)
	v_mov_b64_e32 v[188:189], v[0:1]

; template <int MODE, int TM> ...
;     ...
;   for (int t = 0; t < 2; ++t) {
;     if (!(TM & (1 << t))) continue;
;     const h16* Ks = t ? Ks1 : Ks0;
; #pragma unroll
;     for (int kt = 0; kt < 4; ++kt) {
;       S[t][kt] = f32x4{0.f, 0.f, 0.f, 0.f};
; #pragma unroll
;       for (int ks = 0; ks < 2; ++ks) {
;         h16x8 Kf = *(const h16x8*)(Ks + (kt * 16 + col) * KP + ks * 32 + q4 * 8);
;         S[t][kt] = __builtin_amdgcn_mfma_f32_16x16x32_f16(Kf, Q[ks], S[t][kt], 0, 0, 0);
;       }
;     }
;   }
;   __builtin_amdgcn_s_setprio(0);
;   const float* bt = biasT + hd * 800;
;   float addc[2] = {0.f, 0.f}, sclc[2] = {1.f, 1.f};
; #pragma unroll
;   for (int t = 0; t < 2; ++t) {
;     if (!(TM & (1 << t))) continue;
;     const int kbase = kbase0 + 64 * t;
;     if (far[t]) {
;       const bool ok = (MODE == M_SEL) ? selbit[t] : true;
;       addc[t] = ok ? bt[799] : -1e30f;
;       sclc[t] = SCL2;
;     } else {
;       addc[t] = 0.f;
;       sclc[t] = 1.f;
;       const int kx0 = kbase + q4 * 4;
;       const int d0 = (DK == 16) ? tq - 31 - 16 * kx0 : tq - kx0;
; #pragma unroll
;       for (int kt = 0; kt < 4; ++kt)
; #pragma unroll
;         for (int j = 0; j < 4; ++j) {
;           const int dist = d0 - DK * (kt * 16 + j);
;           const int kx = kx0 + kt * 16 + j;
;           bool valid = dist >= 0;
;           if (MODE == M_WIN) valid = valid && dist < 512 && kx >= 0;
;           if (MODE == M_SEL) valid = valid && selbit[t];
;           if (DK == 16) valid = valid && kx < NCMP;
;     ...
;         const int jb = 2 * i;
;         bool sb[2];
;         sb[0] = ((jb < 64 ? (slo >> jb) : (shi >> (jb - 64))) & 1ull) != 0;
;         sb[1] = (jb + 1 <= cur) && (((jb + 1 < 64 ? (slo >> (jb + 1)) : (shi >> (jb + 1 - 64))) & 1ull) != 0);
;         const bool far[2] = {t0 - (jb * 64 + 63) >= 799, t0 - (jb * 64 + 127) >= 799};
;         const bool n0 = __any(sb[0]) != 0, n1 = __any(sb[1]) != 0;
;         if (n0 && n1) attn_tile2<M_SEL, 3>(Q, O, st, KSB(i, 0), VTB(i, 0), KSB(i, 1), VTB(i, 1), biasT, tq, hd, jb * 64, far, sb, hpd, hpe, lane);
;         else if (n0) attn_tile2<M_SEL, 1>(Q, O, st, KSB(i, 0), VTB(i, 0), KSB(i, 1), VTB(i, 1), biasT, tq, hd, jb * 64, far, sb, hpd, hpe, lane);
;         else if (n1) attn_tile2<M_SEL, 2>(Q, O, st, KSB(i, 0), VTB(i, 0), KSB(i, 1), VTB(i, 1), biasT, tq, hd, jb * 64, far, sb, hpd, hpe, lane);
.LBB0_1618:
	s_lshl_b32 s2, s31, 1
	s_sub_i32 s3, s2, 64
	s_and_b64 s[0:1], s[42:43], exec
	s_cselect_b32 s0, s2, s3
	s_cmp_lt_u32 s2, s28
	v_lshrrev_b64 v[28:29], s0, v[2:3]
	s_cselect_b64 s[0:1], -1, 0
	s_or_b32 s44, s2, 1
	s_sub_i32 s45, s2, 63
	s_and_b64 s[2:3], s[42:43], exec
	s_cselect_b32 s2, s44, s45
	s_lshl_b64 s[2:3], 1, s2
	v_and_b32_e32 v3, s3, v3
	v_and_b32_e32 v2, s2, v2
	v_cmp_ne_u64_e32 vcc, 0, v[2:3]
	s_lshl_b32 s2, s31, 7
	s_and_b64 s[42:43], s[0:1], vcc
	s_sub_i32 s0, s20, s2
	s_cmpk_lt_i32 s0, 0x35e
	v_and_b32_e32 v0, 1, v28
	s_cselect_b64 s[46:47], -1, 0
	s_cmpk_lt_i32 s0, 0x39e
	v_cmp_ne_u32_e32 vcc, 0, v0
	s_cselect_b64 s[44:45], -1, 0
	s_cmp_eq_u64 vcc, 0
	v_cndmask_b32_e64 v2, 0, 1, s[42:43]
	s_cselect_b64 s[0:1], -1, 0
	s_cmp_lg_u64 vcc, 0
	v_cmp_ne_u32_e32 vcc, 0, v2
	s_cselect_b64 s[50:51], -1, 0
	s_cmp_lg_u64 vcc, 0
	s_cselect_b64 s[48:49], -1, 0
	s_and_b64 s[50:51], s[50:51], s[48:49]
	s_and_b64 vcc, exec, s[50:51]
	s_cbranch_vccnz .LBB0_1660
	s_and_b64 vcc, exec, s[0:1]
	s_cbranch_vccz .LBB0_1661
	v_mov_b64_e32 v[28:29], v[80:81]
	v_mov_b64_e32 v[32:33], v[84:85]
	v_mov_b64_e32 v[36:37], v[88:89]
	v_mov_b64_e32 v[40:41], v[92:93]
	s_mov_b64 s[0:1], 0
	s_and_b64 vcc, exec, s[48:49]
	v_mov_b32_e32 v243, v188
	v_mov_b32_e32 v173, v244
	v_mov_b64_e32 v[30:31], v[82:83]
	v_mov_b64_e32 v[34:35], v[86:87]
	v_mov_b64_e32 v[38:39], v[90:91]
	v_mov_b64_e32 v[42:43], v[94:95]
	s_mov_b64 s[48:49], 0
	s_cbranch_vccz .LBB0_1662
	s_setprio 1
	ds_read_b128 v[28:31], v202
	ds_read_b128 v[32:35], v202 offset:64
	ds_read_b128 v[36:39], v202 offset:2560
	ds_read_b128 v[40:43], v202 offset:2624
	ds_read_b128 v[96:99], v202 offset:5120
	s_waitcnt lgkmcnt(4)
	v_mfma_f32_16x16x32_f16 v[28:31], v[28:31], v[4:7], 0
	s_waitcnt lgkmcnt(2)
	v_mfma_f32_16x16x32_f16 v[36:39], v[36:39], v[4:7], 0
	v_mfma_f32_16x16x32_f16 v[32:35], v[32:35], v[8:11], v[28:31]
	s_waitcnt lgkmcnt(1)
	v_mfma_f32_16x16x32_f16 v[28:31], v[40:43], v[8:11], v[36:39]
	s_nop 4
	ds_read_b128 v[36:39], v202 offset:5184
	s_waitcnt lgkmcnt(1)
	v_mfma_f32_16x16x32_f16 v[40:43], v[96:99], v[4:7], 0
	ds_read_b128 v[96:99], v202 offset:7680
	s_waitcnt lgkmcnt(1)
	v_mfma_f32_16x16x32_f16 v[40:43], v[36:39], v[8:11], v[40:43]
	ds_read_b128 v[36:39], v202 offset:7744
	s_waitcnt lgkmcnt(1)
	v_mfma_f32_16x16x32_f16 v[96:99], v[96:99], v[4:7], 0
	s_waitcnt lgkmcnt(0)
	v_mfma_f32_16x16x32_f16 v[36:39], v[36:39], v[8:11], v[96:99]
	s_setprio 0
	s_andn2_b64 vcc, exec, s[44:45]
	s_mov_b64 s[48:49], -1
	s_cbranch_vccnz .LBB0_1655
	v_or_b32_e32 v2, s2, v154
	v_sub_u32_e32 v3, v175, v2
	v_cmp_lt_i32_e32 vcc, -1, v3
	s_and_b64 s[50:51], vcc, s[42:43]
	v_mov_b32_e32 v97, 0xf149f2ca
	v_mov_b32_e32 v96, 0xf149f2ca
	s_and_saveexec_b64 s[48:49], s[50:51]
	s_cbranch_execz .LBB0_1624
	v_min_u32_e32 v3, 0x31f, v3
	v_lshl_add_u32 v3, v3, 2, v157
	ds_read_b32 v96, v3
.LBB0_1624:
	s_or_b64 exec, exec, s[48:49]
	v_xad_u32 v3, v2, -1, v175
	v_cmp_lt_i32_e32 vcc, -1, v3
	s_and_b64 s[50:51], vcc, s[42:43]
	s_and_saveexec_b64 s[48:49], s[50:51]
	s_cbranch_execz .LBB0_1626
	v_min_u32_e32 v3, 0x31f, v3
	v_lshl_add_u32 v3, v3, 2, v157
	ds_read_b32 v97, v3
.LBB0_1626:
	s_or_b64 exec, exec, s[48:49]
	v_or_b32_e32 v3, 2, v2
	v_sub_u32_e32 v3, v175, v3
	v_cmp_lt_i32_e32 vcc, -1, v3
	s_and_b64 s[50:51], vcc, s[42:43]
	v_mov_b32_e32 v99, 0xf149f2ca
	v_mov_b32_e32 v98, 0xf149f2ca
	s_and_saveexec_b64 s[48:49], s[50:51]
	s_cbranch_execz .LBB0_1628
	v_min_u32_e32 v3, 0x31f, v3
	v_lshl_add_u32 v3, v3, 2, v157
	ds_read_b32 v98, v3
.LBB0_1628:
	s_or_b64 exec, exec, s[48:49]
	v_or_b32_e32 v3, 3, v2
	v_sub_u32_e32 v3, v175, v3
	v_cmp_lt_i32_e32 vcc, -1, v3
	s_and_b64 s[50:51], vcc, s[42:43]
	s_and_saveexec_b64 s[48:49], s[50:51]
	s_cbranch_execz .LBB0_1630
	v_min_u32_e32 v3, 0x31f, v3
	v_lshl_add_u32 v3, v3, 2, v157
	ds_read_b32 v99, v3
.LBB0_1630:
	s_or_b64 exec, exec, s[48:49]
	v_sub_u32_e32 v3, v177, v2
	v_cmp_lt_i32_e32 vcc, -1, v3
	s_and_b64 s[50:51], vcc, s[42:43]
	v_mov_b32_e32 v101, 0xf149f2ca
	v_mov_b32_e32 v100, 0xf149f2ca
	s_and_saveexec_b64 s[48:49], s[50:51]
	s_cbranch_execz .LBB0_1632
	v_min_u32_e32 v3, 0x31f, v3
	v_lshl_add_u32 v3, v3, 2, v157
	ds_read_b32 v100, v3
; template <int MODE, int TM> ...
;     ...
;       const int kx0 = kbase + q4 * 4;
;       const int d0 = (DK == 16) ? tq - 31 - 16 * kx0 : tq - kx0;
; #pragma unroll
;       for (int kt = 0; kt < 4; ++kt)
; #pragma unroll
;         for (int j = 0; j < 4; ++j) {
;           const int dist = d0 - DK * (kt * 16 + j);
;           const int kx = kx0 + kt * 16 + j;
;           bool valid = dist >= 0;
;           if (MODE == M_WIN) valid = valid && dist < 512 && kx >= 0;
;           if (MODE == M_SEL) valid = valid && selbit[t];
;           if (DK == 16) valid = valid && kx < NCMP;
;           const int dc = dist < 0 ? 0 : (dist > 799 ? 799 : dist);
;           S[t][kt][j] = valid ? S[t][kt][j] * SCL2 + bt[dc] : -1e30f;
;         }
.LBB0_1632:
	s_or_b64 exec, exec, s[48:49]
	v_sub_u32_e32 v3, v179, v2
	v_cmp_lt_i32_e32 vcc, -1, v3
	s_and_b64 s[50:51], vcc, s[42:43]
	s_and_saveexec_b64 s[48:49], s[50:51]
	s_cbranch_execz .LBB0_1634
	v_min_u32_e32 v3, 0x31f, v3
	v_lshl_add_u32 v3, v3, 2, v157
	ds_read_b32 v101, v3
.LBB0_1634:
	s_or_b64 exec, exec, s[48:49]
	v_sub_u32_e32 v3, v181, v2
	v_cmp_lt_i32_e32 vcc, -1, v3
	s_and_b64 s[50:51], vcc, s[42:43]
	v_mov_b32_e32 v103, 0xf149f2ca
	v_mov_b32_e32 v102, 0xf149f2ca
	s_and_saveexec_b64 s[48:49], s[50:51]
	s_cbranch_execz .LBB0_1636
	v_min_u32_e32 v3, 0x31f, v3
	v_lshl_add_u32 v3, v3, 2, v157
	ds_read_b32 v102, v3
.LBB0_1636:
	s_or_b64 exec, exec, s[48:49]
	v_sub_u32_e32 v3, v219, v2
	v_cmp_lt_i32_e32 vcc, -1, v3
	s_and_b64 s[50:51], vcc, s[42:43]
	s_and_saveexec_b64 s[48:49], s[50:51]
	s_cbranch_execz .LBB0_1638
	v_min_u32_e32 v3, 0x31f, v3
	v_lshl_add_u32 v3, v3, 2, v157
	ds_read_b32 v103, v3
.LBB0_1638:
	s_or_b64 exec, exec, s[48:49]
	v_sub_u32_e32 v3, v220, v2
	v_cmp_lt_i32_e32 vcc, -1, v3
	s_and_b64 s[50:51], vcc, s[42:43]
	v_mov_b32_e32 v105, 0xf149f2ca
	v_mov_b32_e32 v104, 0xf149f2ca
	s_and_saveexec_b64 s[48:49], s[50:51]
	s_cbranch_execz .LBB0_1640
	v_min_u32_e32 v3, 0x31f, v3
	v_lshl_add_u32 v3, v3, 2, v157
	ds_read_b32 v104, v3
.LBB0_1640:
	s_or_b64 exec, exec, s[48:49]
	v_sub_u32_e32 v3, v221, v2
	v_cmp_lt_i32_e32 vcc, -1, v3
	s_and_b64 s[50:51], vcc, s[42:43]
	s_and_saveexec_b64 s[48:49], s[50:51]
	s_cbranch_execz .LBB0_1642
	v_min_u32_e32 v3, 0x31f, v3
	v_lshl_add_u32 v3, v3, 2, v157
	ds_read_b32 v105, v3
.LBB0_1642:
	s_or_b64 exec, exec, s[48:49]
	v_sub_u32_e32 v3, v222, v2
	v_cmp_lt_i32_e32 vcc, -1, v3
	s_and_b64 s[50:51], vcc, s[42:43]
	v_mov_b32_e32 v107, 0xf149f2ca
	v_mov_b32_e32 v106, 0xf149f2ca
	s_and_saveexec_b64 s[48:49], s[50:51]
	s_cbranch_execz .LBB0_1644
	v_min_u32_e32 v3, 0x31f, v3
	v_lshl_add_u32 v3, v3, 2, v157
	ds_read_b32 v106, v3
.LBB0_1644:
	s_or_b64 exec, exec, s[48:49]
	v_sub_u32_e32 v3, v223, v2
	v_cmp_lt_i32_e32 vcc, -1, v3
	s_and_b64 s[50:51], vcc, s[42:43]
	s_and_saveexec_b64 s[48:49], s[50:51]
	s_cbranch_execz .LBB0_1646
	v_min_u32_e32 v3, 0x31f, v3
	v_lshl_add_u32 v3, v3, 2, v157
	ds_read_b32 v107, v3
.LBB0_1646:
	s_or_b64 exec, exec, s[48:49]
	v_sub_u32_e32 v3, v224, v2
	v_cmp_lt_i32_e32 vcc, -1, v3
	s_and_b64 s[50:51], vcc, s[42:43]
	v_mov_b32_e32 v109, 0xf149f2ca
	v_mov_b32_e32 v108, 0xf149f2ca
	s_and_saveexec_b64 s[48:49], s[50:51]
	s_cbranch_execz .LBB0_1648
	v_min_u32_e32 v3, 0x31f, v3
	v_lshl_add_u32 v3, v3, 2, v157
	ds_read_b32 v108, v3
.LBB0_1648:
	s_or_b64 exec, exec, s[48:49]
	v_sub_u32_e32 v3, v225, v2
	v_cmp_lt_i32_e32 vcc, -1, v3
	s_and_b64 s[50:51], vcc, s[42:43]
	s_and_saveexec_b64 s[48:49], s[50:51]
	s_cbranch_execz .LBB0_1650
	v_min_u32_e32 v3, 0x31f, v3
	v_lshl_add_u32 v3, v3, 2, v157
	ds_read_b32 v109, v3
.LBB0_1650:
	s_or_b64 exec, exec, s[48:49]
	v_sub_u32_e32 v3, v226, v2
	v_cmp_lt_i32_e32 vcc, -1, v3
	s_and_b64 s[50:51], vcc, s[42:43]
	v_mov_b32_e32 v111, 0xf149f2ca
	v_mov_b32_e32 v110, 0xf149f2ca
	s_and_saveexec_b64 s[48:49], s[50:51]
	s_cbranch_execz .LBB0_1652
	v_min_u32_e32 v3, 0x31f, v3
	v_lshl_add_u32 v3, v3, 2, v157
	ds_read_b32 v110, v3
.LBB0_1652:
	s_or_b64 exec, exec, s[48:49]
	v_sub_u32_e32 v2, v227, v2
	v_cmp_lt_i32_e32 vcc, -1, v2
	s_and_b64 s[50:51], vcc, s[42:43]
	s_and_saveexec_b64 s[48:49], s[50:51]
	s_cbranch_execz .LBB0_1654
	v_min_u32_e32 v2, 0x31f, v2
	v_lshl_add_u32 v2, v2, 2, v157
	ds_read_b32 v111, v2
.LBB0_1654:
	s_or_b64 exec, exec, s[48:49]
	s_waitcnt lgkmcnt(0)
	v_fmac_f32_e32 v96, 0x3e38aa3b, v32
	v_fmac_f32_e32 v97, 0x3e38aa3b, v33
	v_fmac_f32_e32 v98, 0x3e38aa3b, v34
	v_fmac_f32_e32 v99, 0x3e38aa3b, v35
	v_fmac_f32_e32 v100, 0x3e38aa3b, v28
	v_fmac_f32_e32 v101, 0x3e38aa3b, v29
	v_fmac_f32_e32 v102, 0x3e38aa3b, v30
	v_fmac_f32_e32 v103, 0x3e38aa3b, v31
	v_fmac_f32_e32 v104, 0x3e38aa3b, v40
	v_fmac_f32_e32 v105, 0x3e38aa3b, v41
	v_fmac_f32_e32 v106, 0x3e38aa3b, v42
	v_fmac_f32_e32 v107, 0x3e38aa3b, v43
	v_fmac_f32_e32 v108, 0x3e38aa3b, v36
	v_fmac_f32_e32 v109, 0x3e38aa3b, v37
	v_fmac_f32_e32 v110, 0x3e38aa3b, v38
	v_fmac_f32_e32 v111, 0x3e38aa3b, v39
	s_mov_b64 s[48:49], 0

; template <int MODE, int TM> ...
;     ...
;   for (int t = 0; t < 2; ++t) {
;     if (!(TM & (1 << t))) continue;
;     const h16* Ks = t ? Ks1 : Ks0;
; #pragma unroll
;     for (int kt = 0; kt < 4; ++kt) {
;       S[t][kt] = f32x4{0.f, 0.f, 0.f, 0.f};
; #pragma unroll
;       for (int ks = 0; ks < 2; ++ks) {
;         h16x8 Kf = *(const h16x8*)(Ks + (kt * 16 + col) * KP + ks * 32 + q4 * 8);
;         S[t][kt] = __builtin_amdgcn_mfma_f32_16x16x32_f16(Kf, Q[ks], S[t][kt], 0, 0, 0);
;       }
;     }
;   }
;   __builtin_amdgcn_s_setprio(0);
;   const float* bt = biasT + hd * 800;
;   float addc[2] = {0.f, 0.f}, sclc[2] = {1.f, 1.f};
; #pragma unroll
;   for (int t = 0; t < 2; ++t) {
;     if (!(TM & (1 << t))) continue;
;     const int kbase = kbase0 + 64 * t;
;     if (far[t]) {
;       const bool ok = (MODE == M_SEL) ? selbit[t] : true;
;       addc[t] = ok ? bt[799] : -1e30f;
;       sclc[t] = SCL2;
;     } else {
;       addc[t] = 0.f;
;       sclc[t] = 1.f;
;       const int kx0 = kbase + q4 * 4;
;       const int d0 = (DK == 16) ? tq - 31 - 16 * kx0 : tq - kx0;
; #pragma unroll
;       for (int kt = 0; kt < 4; ++kt)
; #pragma unroll
;         for (int j = 0; j < 4; ++j) {
;           const int dist = d0 - DK * (kt * 16 + j);
;           const int kx = kx0 + kt * 16 + j;
;           bool valid = dist >= 0;
;           if (MODE == M_WIN) valid = valid && dist < 512 && kx >= 0;
;           if (MODE == M_SEL) valid = valid && selbit[t];
;           if (DK == 16) valid = valid && kx < NCMP;
;           const int dc = dist < 0 ? 0 : (dist > 799 ? 799 : dist);
;           S[t][kt][j] = valid ? S[t][kt][j] * SCL2 + bt[dc] : -1e30f;
;         }
.LBB0_1663:
	s_setprio 1
	ds_read_b128 v[28:31], v155 offset:53760
	ds_read_b128 v[32:35], v155 offset:53824
	ds_read_b128 v[36:39], v155 offset:56320
	ds_read_b128 v[96:99], v155 offset:56384
	s_waitcnt lgkmcnt(3)
	v_mfma_f32_16x16x32_f16 v[28:31], v[28:31], v[4:7], 0
	s_waitcnt lgkmcnt(2)
	v_mfma_f32_16x16x32_f16 v[40:43], v[32:35], v[8:11], v[28:31]
	ds_read_b128 v[32:35], v155 offset:58944
	s_nop 4
	ds_read_b128 v[28:31], v155 offset:58880
	s_waitcnt lgkmcnt(3)
	v_mfma_f32_16x16x32_f16 v[36:39], v[36:39], v[4:7], 0
	s_waitcnt lgkmcnt(2)
	v_mfma_f32_16x16x32_f16 v[36:39], v[96:99], v[8:11], v[36:39]
	ds_read_b128 v[96:99], v155 offset:61440
	s_waitcnt lgkmcnt(1)
	v_mfma_f32_16x16x32_f16 v[28:31], v[28:31], v[4:7], 0
	v_mfma_f32_16x16x32_f16 v[32:35], v[32:35], v[8:11], v[28:31]
	s_nop 6
	ds_read_b128 v[28:31], v155 offset:61504
	s_waitcnt lgkmcnt(1)
	v_mfma_f32_16x16x32_f16 v[96:99], v[96:99], v[4:7], 0
	s_waitcnt lgkmcnt(0)
	v_mfma_f32_16x16x32_f16 v[28:31], v[28:31], v[8:11], v[96:99]
	s_setprio 0
	s_andn2_b64 vcc, exec, s[46:47]
	s_mov_b64 s[0:1], -1
	s_cbranch_vccnz .LBB0_1697
	v_or_b32_e32 v2, s2, v154
	v_sub_u32_e32 v3, v182, v2
	v_cmp_lt_i32_e64 s[0:1], -1, v3
	v_cmp_eq_u32_e32 vcc, 1, v0
	s_and_b64 s[48:49], s[0:1], vcc
	v_mov_b32_e32 v97, 0xf149f2ca
	v_mov_b32_e32 v96, 0xf149f2ca
	s_and_saveexec_b64 s[0:1], s[48:49]
	s_cbranch_execz .LBB0_1666
	v_min_u32_e32 v3, 0x31f, v3
	v_lshl_add_u32 v3, v3, 2, v157
	ds_read_b32 v96, v3
.LBB0_1666:
	s_or_b64 exec, exec, s[0:1]
	v_xad_u32 v3, v2, -1, v182
	v_cmp_lt_i32_e64 s[0:1], -1, v3
	s_and_b64 s[48:49], s[0:1], vcc
	s_and_saveexec_b64 s[0:1], s[48:49]
	s_cbranch_execz .LBB0_1668
	v_min_u32_e32 v3, 0x31f, v3
	v_lshl_add_u32 v3, v3, 2, v157
	ds_read_b32 v97, v3
.LBB0_1668:
	s_or_b64 exec, exec, s[0:1]
	v_or_b32_e32 v3, 2, v2
	v_sub_u32_e32 v3, v182, v3
	v_cmp_lt_i32_e64 s[0:1], -1, v3
	s_and_b64 s[48:49], s[0:1], vcc
	v_mov_b32_e32 v99, 0xf149f2ca
	v_mov_b32_e32 v98, 0xf149f2ca
	s_and_saveexec_b64 s[0:1], s[48:49]
	s_cbranch_execz .LBB0_1670
	v_min_u32_e32 v3, 0x31f, v3
	v_lshl_add_u32 v3, v3, 2, v157
	ds_read_b32 v98, v3
.LBB0_1670:
	s_or_b64 exec, exec, s[0:1]
	v_or_b32_e32 v3, 3, v2
	v_sub_u32_e32 v3, v182, v3
	v_cmp_lt_i32_e64 s[0:1], -1, v3
	s_and_b64 s[48:49], s[0:1], vcc
	s_and_saveexec_b64 s[0:1], s[48:49]
	s_cbranch_execz .LBB0_1672
	v_min_u32_e32 v3, 0x31f, v3
	v_lshl_add_u32 v3, v3, 2, v157
	ds_read_b32 v99, v3
.LBB0_1672:
	s_or_b64 exec, exec, s[0:1]
	v_sub_u32_e32 v3, v228, v2
	v_cmp_lt_i32_e64 s[0:1], -1, v3
	s_and_b64 s[48:49], s[0:1], vcc
	v_mov_b32_e32 v101, 0xf149f2ca
	v_mov_b32_e32 v100, 0xf149f2ca
	s_and_saveexec_b64 s[0:1], s[48:49]
	s_cbranch_execz .LBB0_1674
	v_min_u32_e32 v3, 0x31f, v3
	v_lshl_add_u32 v3, v3, 2, v157
	ds_read_b32 v100, v3
.LBB0_1674:
	s_or_b64 exec, exec, s[0:1]
	v_sub_u32_e32 v3, v229, v2
	v_cmp_lt_i32_e64 s[0:1], -1, v3
	s_and_b64 s[48:49], s[0:1], vcc
	s_and_saveexec_b64 s[0:1], s[48:49]
	s_cbranch_execz .LBB0_1676
	v_min_u32_e32 v3, 0x31f, v3
	v_lshl_add_u32 v3, v3, 2, v157
	ds_read_b32 v101, v3
.LBB0_1676:
	s_or_b64 exec, exec, s[0:1]
	v_sub_u32_e32 v3, v230, v2
	v_cmp_lt_i32_e64 s[0:1], -1, v3
	s_and_b64 s[48:49], s[0:1], vcc
	v_mov_b32_e32 v103, 0xf149f2ca
	v_mov_b32_e32 v102, 0xf149f2ca
	s_and_saveexec_b64 s[0:1], s[48:49]
	s_cbranch_execz .LBB0_1678
	v_min_u32_e32 v3, 0x31f, v3
	v_lshl_add_u32 v3, v3, 2, v157
	ds_read_b32 v102, v3
.LBB0_1678:
	s_or_b64 exec, exec, s[0:1]
	v_sub_u32_e32 v3, v231, v2
	v_cmp_lt_i32_e64 s[0:1], -1, v3
	s_and_b64 s[48:49], s[0:1], vcc
	s_and_saveexec_b64 s[0:1], s[48:49]
	s_cbranch_execz .LBB0_1680
	v_min_u32_e32 v3, 0x31f, v3
	v_lshl_add_u32 v3, v3, 2, v157
	ds_read_b32 v103, v3
.LBB0_1680:
	s_or_b64 exec, exec, s[0:1]
	v_sub_u32_e32 v3, v232, v2
	v_cmp_lt_i32_e64 s[0:1], -1, v3
	s_and_b64 s[48:49], s[0:1], vcc
	v_mov_b32_e32 v105, 0xf149f2ca
	v_mov_b32_e32 v104, 0xf149f2ca
	s_and_saveexec_b64 s[0:1], s[48:49]
	s_cbranch_execz .LBB0_1682
	v_min_u32_e32 v3, 0x31f, v3
	v_lshl_add_u32 v3, v3, 2, v157
	ds_read_b32 v104, v3
.LBB0_1682:
	s_or_b64 exec, exec, s[0:1]
	v_sub_u32_e32 v3, v233, v2
	v_cmp_lt_i32_e64 s[0:1], -1, v3
	s_and_b64 s[48:49], s[0:1], vcc
	s_and_saveexec_b64 s[0:1], s[48:49]
	s_cbranch_execz .LBB0_1684
	v_min_u32_e32 v3, 0x31f, v3
	v_lshl_add_u32 v3, v3, 2, v157
	ds_read_b32 v105, v3
.LBB0_1684:
	s_or_b64 exec, exec, s[0:1]
	v_sub_u32_e32 v3, v234, v2
	v_cmp_lt_i32_e64 s[0:1], -1, v3
	s_and_b64 s[48:49], s[0:1], vcc
	v_mov_b32_e32 v107, 0xf149f2ca
	v_mov_b32_e32 v106, 0xf149f2ca
	s_and_saveexec_b64 s[0:1], s[48:49]
	s_cbranch_execz .LBB0_1686
	v_min_u32_e32 v3, 0x31f, v3
	v_lshl_add_u32 v3, v3, 2, v157
	ds_read_b32 v106, v3
.LBB0_1686:
	s_or_b64 exec, exec, s[0:1]
	v_sub_u32_e32 v3, v235, v2
	v_cmp_lt_i32_e64 s[0:1], -1, v3
	s_and_b64 s[48:49], s[0:1], vcc
	s_and_saveexec_b64 s[0:1], s[48:49]
	s_cbranch_execz .LBB0_1688
	v_min_u32_e32 v3, 0x31f, v3
	v_lshl_add_u32 v3, v3, 2, v157
	ds_read_b32 v107, v3
.LBB0_1688:
	s_or_b64 exec, exec, s[0:1]
	v_sub_u32_e32 v3, v236, v2
	v_cmp_lt_i32_e64 s[0:1], -1, v3
	s_and_b64 s[48:49], s[0:1], vcc
	v_mov_b32_e32 v109, 0xf149f2ca
	v_mov_b32_e32 v108, 0xf149f2ca
	s_and_saveexec_b64 s[0:1], s[48:49]
	s_cbranch_execz .LBB0_1690
	v_min_u32_e32 v3, 0x31f, v3
	v_lshl_add_u32 v3, v3, 2, v157
	ds_read_b32 v108, v3
.LBB0_1690:
	s_or_b64 exec, exec, s[0:1]
	v_sub_u32_e32 v3, v237, v2
	v_cmp_lt_i32_e64 s[0:1], -1, v3
	s_and_b64 s[48:49], s[0:1], vcc
	s_and_saveexec_b64 s[0:1], s[48:49]
	s_cbranch_execz .LBB0_1692
	v_min_u32_e32 v3, 0x31f, v3
	v_lshl_add_u32 v3, v3, 2, v157
	ds_read_b32 v109, v3
.LBB0_1692:
	s_or_b64 exec, exec, s[0:1]
	v_sub_u32_e32 v3, v238, v2
	v_cmp_lt_i32_e64 s[0:1], -1, v3
	s_and_b64 s[48:49], s[0:1], vcc
	v_mov_b32_e32 v111, 0xf149f2ca
	v_mov_b32_e32 v110, 0xf149f2ca
	s_and_saveexec_b64 s[0:1], s[48:49]
	s_cbranch_execz .LBB0_1694
	v_min_u32_e32 v3, 0x31f, v3
	v_lshl_add_u32 v3, v3, 2, v157
	ds_read_b32 v110, v3
.LBB0_1694:
	s_or_b64 exec, exec, s[0:1]
	v_sub_u32_e32 v2, v239, v2
	v_cmp_lt_i32_e64 s[0:1], -1, v2
	s_and_b64 s[48:49], s[0:1], vcc
	s_and_saveexec_b64 s[0:1], s[48:49]
	s_cbranch_execz .LBB0_1696
	v_min_u32_e32 v2, 0x31f, v2
	v_lshl_add_u32 v2, v2, 2, v157
	ds_read_b32 v111, v2
.LBB0_1696:
	s_or_b64 exec, exec, s[0:1]
	s_waitcnt lgkmcnt(0)
	v_fmac_f32_e32 v96, 0x3e38aa3b, v40
	v_fmac_f32_e32 v97, 0x3e38aa3b, v41
	v_fmac_f32_e32 v98, 0x3e38aa3b, v42
	v_fmac_f32_e32 v99, 0x3e38aa3b, v43
	v_fmac_f32_e32 v100, 0x3e38aa3b, v36
	v_fmac_f32_e32 v101, 0x3e38aa3b, v37
	v_fmac_f32_e32 v102, 0x3e38aa3b, v38
	v_fmac_f32_e32 v103, 0x3e38aa3b, v39
	v_fmac_f32_e32 v104, 0x3e38aa3b, v32
	v_fmac_f32_e32 v105, 0x3e38aa3b, v33
	v_fmac_f32_e32 v106, 0x3e38aa3b, v34
	v_fmac_f32_e32 v107, 0x3e38aa3b, v35
	v_fmac_f32_e32 v108, 0x3e38aa3b, v28
	v_fmac_f32_e32 v109, 0x3e38aa3b, v29
	v_fmac_f32_e32 v110, 0x3e38aa3b, v30
	v_fmac_f32_e32 v111, 0x3e38aa3b, v31
	s_mov_b64 s[0:1], 0

; template <int MODE, int TM> ...
;     ...
;     const h16* Ks = t ? Ks1 : Ks0;
; #pragma unroll
;     for (int kt = 0; kt < 4; ++kt) {
;       S[t][kt] = f32x4{0.f, 0.f, 0.f, 0.f};
; #pragma unroll
;       for (int ks = 0; ks < 2; ++ks) {
;         h16x8 Kf = *(const h16x8*)(Ks + (kt * 16 + col) * KP + ks * 32 + q4 * 8);
;         S[t][kt] = __builtin_amdgcn_mfma_f32_16x16x32_f16(Kf, Q[ks], S[t][kt], 0, 0, 0);
;       }
;     }
;   }
;   __builtin_amdgcn_s_setprio(0);
;   const float* bt = biasT + hd * 800;
;   float addc[2] = {0.f, 0.f}, sclc[2] = {1.f, 1.f};
; #pragma unroll
;   for (int t = 0; t < 2; ++t) {
;     if (!(TM & (1 << t))) continue;
;     const int kbase = kbase0 + 64 * t;
;     if (far[t]) {
;       const bool ok = (MODE == M_SEL) ? selbit[t] : true;
;       addc[t] = ok ? bt[799] : -1e30f;
;       sclc[t] = SCL2;
;     } else {
;       addc[t] = 0.f;
;       sclc[t] = 1.f;
;       const int kx0 = kbase + q4 * 4;
;       const int d0 = (DK == 16) ? tq - 31 - 16 * kx0 : tq - kx0;
; #pragma unroll
;       for (int kt = 0; kt < 4; ++kt)
; #pragma unroll
;         for (int j = 0; j < 4; ++j) {
;           const int dist = d0 - DK * (kt * 16 + j);
;           const int kx = kx0 + kt * 16 + j;
;           bool valid = dist >= 0;
;           if (MODE == M_WIN) valid = valid && dist < 512 && kx >= 0;
;           if (MODE == M_SEL) valid = valid && selbit[t];
;           if (DK == 16) valid = valid && kx < NCMP;
;           const int dc = dist < 0 ? 0 : (dist > 799 ? 799 : dist);
;           S[t][kt][j] = valid ? S[t][kt][j] * SCL2 + bt[dc] : -1e30f;
;         }
.LBB0_1706:
	s_setprio 1
	ds_read_b128 v[28:31], v155 offset:53760
	ds_read_b128 v[32:35], v155 offset:53824
	ds_read_b128 v[36:39], v155 offset:56320
	ds_read_b128 v[96:99], v155 offset:56384
	ds_read_b128 v[100:103], v202
	ds_read_b128 v[104:107], v202 offset:2560
	s_waitcnt lgkmcnt(5)
	v_mfma_f32_16x16x32_f16 v[28:31], v[28:31], v[4:7], 0
	ds_read_b128 v[108:111], v202 offset:5120
	ds_read_b128 v[112:115], v202 offset:7680
	s_waitcnt lgkmcnt(6)
	v_mfma_f32_16x16x32_f16 v[40:43], v[32:35], v[8:11], v[28:31]
	ds_read_b128 v[32:35], v155 offset:58944
	s_nop 2
	ds_read_b128 v[28:31], v155 offset:58880
	s_waitcnt lgkmcnt(7)
	v_mfma_f32_16x16x32_f16 v[36:39], v[36:39], v[4:7], 0
	s_waitcnt lgkmcnt(6)
	v_mfma_f32_16x16x32_f16 v[36:39], v[96:99], v[8:11], v[36:39]
	ds_read_b128 v[96:99], v155 offset:61440
	s_waitcnt lgkmcnt(1)
	v_mfma_f32_16x16x32_f16 v[28:31], v[28:31], v[4:7], 0
	v_mfma_f32_16x16x32_f16 v[32:35], v[32:35], v[8:11], v[28:31]
	s_nop 6
	ds_read_b128 v[28:31], v155 offset:61504
	s_waitcnt lgkmcnt(1)
	v_mfma_f32_16x16x32_f16 v[96:99], v[96:99], v[4:7], 0
	s_waitcnt lgkmcnt(0)
	v_mfma_f32_16x16x32_f16 v[28:31], v[28:31], v[8:11], v[96:99]
	s_nop 5
	ds_read_b128 v[96:99], v202 offset:64
	v_mfma_f32_16x16x32_f16 v[100:103], v[100:103], v[4:7], 0
	s_waitcnt lgkmcnt(0)
	v_mfma_f32_16x16x32_f16 v[96:99], v[96:99], v[8:11], v[100:103]
	s_nop 5
	ds_read_b128 v[100:103], v202 offset:2624
	v_mfma_f32_16x16x32_f16 v[104:107], v[104:107], v[4:7], 0
	s_waitcnt lgkmcnt(0)
	v_mfma_f32_16x16x32_f16 v[100:103], v[100:103], v[8:11], v[104:107]
	s_nop 5
	ds_read_b128 v[104:107], v202 offset:5184
	v_mfma_f32_16x16x32_f16 v[108:111], v[108:111], v[4:7], 0
	s_waitcnt lgkmcnt(0)
	v_mfma_f32_16x16x32_f16 v[104:107], v[104:107], v[8:11], v[108:111]
	s_nop 5
	ds_read_b128 v[108:111], v202 offset:7744
	v_mfma_f32_16x16x32_f16 v[112:115], v[112:115], v[4:7], 0
	s_waitcnt lgkmcnt(0)
	v_mfma_f32_16x16x32_f16 v[108:111], v[108:111], v[8:11], v[112:115]
	s_setprio 0
	v_or_b32_e32 v173, s2, v154
	s_andn2_b64 vcc, exec, s[46:47]
	s_mov_b64 s[0:1], -1
	s_cbranch_vccnz .LBB0_1740
	v_sub_u32_e32 v2, v182, v173
	v_cmp_lt_i32_e64 s[0:1], -1, v2
	v_cmp_eq_u32_e32 vcc, 1, v0
	s_and_b64 s[2:3], s[0:1], vcc
	v_mov_b32_e32 v113, 0xf149f2ca
	v_mov_b32_e32 v112, 0xf149f2ca
	s_and_saveexec_b64 s[0:1], s[2:3]
	s_cbranch_execz .LBB0_1709
	v_min_u32_e32 v2, 0x31f, v2
	v_lshl_add_u32 v2, v2, 2, v157
	ds_read_b32 v112, v2
.LBB0_1709:
	s_or_b64 exec, exec, s[0:1]
	v_xad_u32 v2, v173, -1, v182
	v_cmp_lt_i32_e64 s[0:1], -1, v2
	s_and_b64 s[2:3], s[0:1], vcc
	s_and_saveexec_b64 s[0:1], s[2:3]
	s_cbranch_execz .LBB0_1711
	v_min_u32_e32 v2, 0x31f, v2
	v_lshl_add_u32 v2, v2, 2, v157
	ds_read_b32 v113, v2
.LBB0_1711:
	s_or_b64 exec, exec, s[0:1]
	v_or_b32_e32 v2, 2, v173
	v_sub_u32_e32 v2, v182, v2
	v_cmp_lt_i32_e64 s[0:1], -1, v2
	s_and_b64 s[2:3], s[0:1], vcc
	v_mov_b32_e32 v115, 0xf149f2ca
	v_mov_b32_e32 v114, 0xf149f2ca
	s_and_saveexec_b64 s[0:1], s[2:3]
	s_cbranch_execz .LBB0_1713
	v_min_u32_e32 v2, 0x31f, v2
	v_lshl_add_u32 v2, v2, 2, v157
	ds_read_b32 v114, v2
.LBB0_1713:
	s_or_b64 exec, exec, s[0:1]
	v_or_b32_e32 v2, 3, v173
	v_sub_u32_e32 v2, v182, v2
	v_cmp_lt_i32_e64 s[0:1], -1, v2
	s_and_b64 s[2:3], s[0:1], vcc
	s_and_saveexec_b64 s[0:1], s[2:3]
	s_cbranch_execz .LBB0_1715
	v_min_u32_e32 v2, 0x31f, v2
	v_lshl_add_u32 v2, v2, 2, v157
	ds_read_b32 v115, v2
.LBB0_1715:
	s_or_b64 exec, exec, s[0:1]
	v_sub_u32_e32 v2, v228, v173
	v_cmp_lt_i32_e64 s[0:1], -1, v2
	s_and_b64 s[2:3], s[0:1], vcc
	v_mov_b32_e32 v117, 0xf149f2ca
	v_mov_b32_e32 v116, 0xf149f2ca
	s_and_saveexec_b64 s[0:1], s[2:3]
	s_cbranch_execz .LBB0_1717
	v_min_u32_e32 v2, 0x31f, v2
	v_lshl_add_u32 v2, v2, 2, v157
	ds_read_b32 v116, v2
.LBB0_1717:
	s_or_b64 exec, exec, s[0:1]
	v_sub_u32_e32 v2, v229, v173
	v_cmp_lt_i32_e64 s[0:1], -1, v2
	s_and_b64 s[2:3], s[0:1], vcc
	s_and_saveexec_b64 s[0:1], s[2:3]
	s_cbranch_execz .LBB0_1719
	v_min_u32_e32 v2, 0x31f, v2
	v_lshl_add_u32 v2, v2, 2, v157
	ds_read_b32 v117, v2
; template <int MODE, int TM> ...
;     ...
;       const int kx0 = kbase + q4 * 4;
;       const int d0 = (DK == 16) ? tq - 31 - 16 * kx0 : tq - kx0;
; #pragma unroll
;       for (int kt = 0; kt < 4; ++kt)
; #pragma unroll
;         for (int j = 0; j < 4; ++j) {
;           const int dist = d0 - DK * (kt * 16 + j);
;           const int kx = kx0 + kt * 16 + j;
;           bool valid = dist >= 0;
;           if (MODE == M_WIN) valid = valid && dist < 512 && kx >= 0;
;           if (MODE == M_SEL) valid = valid && selbit[t];
;           if (DK == 16) valid = valid && kx < NCMP;
;           const int dc = dist < 0 ? 0 : (dist > 799 ? 799 : dist);
;           S[t][kt][j] = valid ? S[t][kt][j] * SCL2 + bt[dc] : -1e30f;
;         }
.LBB0_1719:
	s_or_b64 exec, exec, s[0:1]
	v_sub_u32_e32 v2, v230, v173
	v_cmp_lt_i32_e64 s[0:1], -1, v2
	s_and_b64 s[2:3], s[0:1], vcc
	v_mov_b32_e32 v119, 0xf149f2ca
	v_mov_b32_e32 v118, 0xf149f2ca
	s_and_saveexec_b64 s[0:1], s[2:3]
	s_cbranch_execz .LBB0_1721
	v_min_u32_e32 v2, 0x31f, v2
	v_lshl_add_u32 v2, v2, 2, v157
	ds_read_b32 v118, v2
.LBB0_1721:
	s_or_b64 exec, exec, s[0:1]
	v_sub_u32_e32 v2, v231, v173
	v_cmp_lt_i32_e64 s[0:1], -1, v2
	s_and_b64 s[2:3], s[0:1], vcc
	s_and_saveexec_b64 s[0:1], s[2:3]
	s_cbranch_execz .LBB0_1723
	v_min_u32_e32 v2, 0x31f, v2
	v_lshl_add_u32 v2, v2, 2, v157
	ds_read_b32 v119, v2
.LBB0_1723:
	s_or_b64 exec, exec, s[0:1]
	v_sub_u32_e32 v2, v232, v173
	v_cmp_lt_i32_e64 s[0:1], -1, v2
	s_and_b64 s[2:3], s[0:1], vcc
	v_mov_b32_e32 v121, 0xf149f2ca
	v_mov_b32_e32 v120, 0xf149f2ca
	s_and_saveexec_b64 s[0:1], s[2:3]
	s_cbranch_execz .LBB0_1725
	v_min_u32_e32 v2, 0x31f, v2
	v_lshl_add_u32 v2, v2, 2, v157
	ds_read_b32 v120, v2
.LBB0_1725:
	s_or_b64 exec, exec, s[0:1]
	v_sub_u32_e32 v2, v233, v173
	v_cmp_lt_i32_e64 s[0:1], -1, v2
	s_and_b64 s[2:3], s[0:1], vcc
	s_and_saveexec_b64 s[0:1], s[2:3]
	s_cbranch_execz .LBB0_1727
	v_min_u32_e32 v2, 0x31f, v2
	v_lshl_add_u32 v2, v2, 2, v157
	ds_read_b32 v121, v2
.LBB0_1727:
	s_or_b64 exec, exec, s[0:1]
	v_sub_u32_e32 v2, v234, v173
	v_cmp_lt_i32_e64 s[0:1], -1, v2
	s_and_b64 s[2:3], s[0:1], vcc
	v_mov_b32_e32 v123, 0xf149f2ca
	v_mov_b32_e32 v122, 0xf149f2ca
	s_and_saveexec_b64 s[0:1], s[2:3]
	s_cbranch_execz .LBB0_1729
	v_min_u32_e32 v2, 0x31f, v2
	v_lshl_add_u32 v2, v2, 2, v157
	ds_read_b32 v122, v2
.LBB0_1729:
	s_or_b64 exec, exec, s[0:1]
	v_sub_u32_e32 v2, v235, v173
	v_cmp_lt_i32_e64 s[0:1], -1, v2
	s_and_b64 s[2:3], s[0:1], vcc
	s_and_saveexec_b64 s[0:1], s[2:3]
	s_cbranch_execz .LBB0_1731
	v_min_u32_e32 v2, 0x31f, v2
	v_lshl_add_u32 v2, v2, 2, v157
	ds_read_b32 v123, v2
.LBB0_1731:
	s_or_b64 exec, exec, s[0:1]
	v_sub_u32_e32 v2, v236, v173
	v_cmp_lt_i32_e64 s[0:1], -1, v2
	s_and_b64 s[2:3], s[0:1], vcc
	v_mov_b32_e32 v125, 0xf149f2ca
	v_mov_b32_e32 v124, 0xf149f2ca
	s_and_saveexec_b64 s[0:1], s[2:3]
	s_cbranch_execz .LBB0_1733
	v_min_u32_e32 v2, 0x31f, v2
	v_lshl_add_u32 v2, v2, 2, v157
	ds_read_b32 v124, v2
.LBB0_1733:
	s_or_b64 exec, exec, s[0:1]
	v_sub_u32_e32 v2, v237, v173
	v_cmp_lt_i32_e64 s[0:1], -1, v2
	s_and_b64 s[2:3], s[0:1], vcc
	s_and_saveexec_b64 s[0:1], s[2:3]
	s_cbranch_execz .LBB0_1735
	v_min_u32_e32 v2, 0x31f, v2
	v_lshl_add_u32 v2, v2, 2, v157
	ds_read_b32 v125, v2
.LBB0_1735:
	s_or_b64 exec, exec, s[0:1]
	v_sub_u32_e32 v2, v238, v173
	v_cmp_lt_i32_e64 s[0:1], -1, v2
	s_and_b64 s[2:3], s[0:1], vcc
	v_mov_b32_e32 v127, 0xf149f2ca
	v_mov_b32_e32 v126, 0xf149f2ca
	s_and_saveexec_b64 s[0:1], s[2:3]
	s_cbranch_execz .LBB0_1737
	v_min_u32_e32 v2, 0x31f, v2
	v_lshl_add_u32 v2, v2, 2, v157
	ds_read_b32 v126, v2
.LBB0_1737:
	s_or_b64 exec, exec, s[0:1]
	v_sub_u32_e32 v2, v239, v173
	v_cmp_lt_i32_e64 s[0:1], -1, v2
	s_and_b64 s[2:3], s[0:1], vcc
	s_and_saveexec_b64 s[0:1], s[2:3]
	s_cbranch_execz .LBB0_1739
	v_min_u32_e32 v2, 0x31f, v2
	v_lshl_add_u32 v2, v2, 2, v157
	ds_read_b32 v127, v2
.LBB0_1739:
	s_or_b64 exec, exec, s[0:1]
	s_waitcnt lgkmcnt(0)
	v_fmac_f32_e32 v112, 0x3e38aa3b, v40
	v_fmac_f32_e32 v113, 0x3e38aa3b, v41
	v_fmac_f32_e32 v114, 0x3e38aa3b, v42
	v_fmac_f32_e32 v115, 0x3e38aa3b, v43
	v_fmac_f32_e32 v116, 0x3e38aa3b, v36
	v_fmac_f32_e32 v117, 0x3e38aa3b, v37
	v_fmac_f32_e32 v118, 0x3e38aa3b, v38
	v_fmac_f32_e32 v119, 0x3e38aa3b, v39
	v_fmac_f32_e32 v120, 0x3e38aa3b, v32
	v_fmac_f32_e32 v121, 0x3e38aa3b, v33
	v_fmac_f32_e32 v122, 0x3e38aa3b, v34
	v_fmac_f32_e32 v123, 0x3e38aa3b, v35
	v_fmac_f32_e32 v124, 0x3e38aa3b, v28
	v_fmac_f32_e32 v125, 0x3e38aa3b, v29
	v_fmac_f32_e32 v126, 0x3e38aa3b, v30
	v_fmac_f32_e32 v127, 0x3e38aa3b, v31
	s_mov_b64 s[0:1], 0

; template <int MODE, int TM> ...
;     ...
;       const int kx0 = kbase + q4 * 4;
;       const int d0 = (DK == 16) ? tq - 31 - 16 * kx0 : tq - kx0;
; #pragma unroll
;       for (int kt = 0; kt < 4; ++kt)
; #pragma unroll
;         for (int j = 0; j < 4; ++j) {
;           const int dist = d0 - DK * (kt * 16 + j);
;           const int kx = kx0 + kt * 16 + j;
;           bool valid = dist >= 0;
;           if (MODE == M_WIN) valid = valid && dist < 512 && kx >= 0;
;           if (MODE == M_SEL) valid = valid && selbit[t];
;           if (DK == 16) valid = valid && kx < NCMP;
;           const int dc = dist < 0 ? 0 : (dist > 799 ? 799 : dist);
;           S[t][kt][j] = valid ? S[t][kt][j] * SCL2 + bt[dc] : -1e30f;
;         }
.LBB0_1745:
	v_sub_u32_e32 v2, v175, v173
	v_cmp_lt_i32_e32 vcc, -1, v2
	s_and_b64 s[44:45], vcc, s[42:43]
	v_mov_b32_e32 v113, 0xf149f2ca
	v_mov_b32_e32 v112, 0xf149f2ca
	s_and_saveexec_b64 s[0:1], s[44:45]
	s_cbranch_execz .LBB0_1747
	v_min_u32_e32 v2, 0x31f, v2
	v_lshl_add_u32 v2, v2, 2, v157
	ds_read_b32 v112, v2
.LBB0_1747:
	s_or_b64 exec, exec, s[0:1]
	v_sub_u32_e32 v2, v240, v173
	v_cmp_lt_i32_e32 vcc, -1, v2
	s_and_b64 s[44:45], vcc, s[42:43]
	s_and_saveexec_b64 s[0:1], s[44:45]
	s_cbranch_execz .LBB0_1749
	v_min_u32_e32 v2, 0x31f, v2
	v_lshl_add_u32 v2, v2, 2, v157
	ds_read_b32 v113, v2
.LBB0_1749:
	s_or_b64 exec, exec, s[0:1]
	v_sub_u32_e32 v2, v241, v173
	v_cmp_lt_i32_e32 vcc, -1, v2
	s_and_b64 s[44:45], vcc, s[42:43]
	v_mov_b32_e32 v115, 0xf149f2ca
	v_mov_b32_e32 v114, 0xf149f2ca
	s_and_saveexec_b64 s[0:1], s[44:45]
	s_cbranch_execz .LBB0_1751
	v_min_u32_e32 v2, 0x31f, v2
	v_lshl_add_u32 v2, v2, 2, v157
	ds_read_b32 v114, v2
.LBB0_1751:
	s_or_b64 exec, exec, s[0:1]
	v_sub_u32_e32 v2, v242, v173
	v_cmp_lt_i32_e32 vcc, -1, v2
	s_and_b64 s[44:45], vcc, s[42:43]
	s_and_saveexec_b64 s[0:1], s[44:45]
	s_cbranch_execz .LBB0_1753
	v_min_u32_e32 v2, 0x31f, v2
	v_lshl_add_u32 v2, v2, 2, v157
	ds_read_b32 v115, v2
.LBB0_1753:
	s_or_b64 exec, exec, s[0:1]
	v_sub_u32_e32 v2, v177, v173
	v_cmp_lt_i32_e32 vcc, -1, v2
	s_and_b64 s[44:45], vcc, s[42:43]
	v_mov_b32_e32 v117, 0xf149f2ca
	v_mov_b32_e32 v116, 0xf149f2ca
	s_and_saveexec_b64 s[0:1], s[44:45]
	s_cbranch_execz .LBB0_1755
	v_min_u32_e32 v2, 0x31f, v2
	v_lshl_add_u32 v2, v2, 2, v157
	ds_read_b32 v116, v2
.LBB0_1755:
	s_or_b64 exec, exec, s[0:1]
	v_sub_u32_e32 v2, v179, v173
	v_cmp_lt_i32_e32 vcc, -1, v2
	s_and_b64 s[44:45], vcc, s[42:43]
	s_and_saveexec_b64 s[0:1], s[44:45]
	s_cbranch_execz .LBB0_1757
	v_min_u32_e32 v2, 0x31f, v2
	v_lshl_add_u32 v2, v2, 2, v157
	ds_read_b32 v117, v2
.LBB0_1757:
	s_or_b64 exec, exec, s[0:1]
	v_sub_u32_e32 v2, v181, v173
	v_cmp_lt_i32_e32 vcc, -1, v2
	s_and_b64 s[44:45], vcc, s[42:43]
	v_mov_b32_e32 v119, 0xf149f2ca
	v_mov_b32_e32 v118, 0xf149f2ca
	s_and_saveexec_b64 s[0:1], s[44:45]
	s_cbranch_execz .LBB0_1759
	v_min_u32_e32 v2, 0x31f, v2
	v_lshl_add_u32 v2, v2, 2, v157
	ds_read_b32 v118, v2
.LBB0_1759:
	s_or_b64 exec, exec, s[0:1]
	v_sub_u32_e32 v2, v219, v173
	v_cmp_lt_i32_e32 vcc, -1, v2
	s_and_b64 s[44:45], vcc, s[42:43]
	s_and_saveexec_b64 s[0:1], s[44:45]
	s_cbranch_execz .LBB0_1761
	v_min_u32_e32 v2, 0x31f, v2
	v_lshl_add_u32 v2, v2, 2, v157
	ds_read_b32 v119, v2
.LBB0_1761:
	s_or_b64 exec, exec, s[0:1]
	v_sub_u32_e32 v2, v220, v173
	v_cmp_lt_i32_e32 vcc, -1, v2
	s_and_b64 s[44:45], vcc, s[42:43]
	v_mov_b32_e32 v121, 0xf149f2ca
	v_mov_b32_e32 v120, 0xf149f2ca
	s_and_saveexec_b64 s[0:1], s[44:45]
	s_cbranch_execz .LBB0_1763
	v_min_u32_e32 v2, 0x31f, v2
	v_lshl_add_u32 v2, v2, 2, v157
	ds_read_b32 v120, v2
.LBB0_1763:
	s_or_b64 exec, exec, s[0:1]
	v_sub_u32_e32 v2, v221, v173
	v_cmp_lt_i32_e32 vcc, -1, v2
	s_and_b64 s[44:45], vcc, s[42:43]
	s_and_saveexec_b64 s[0:1], s[44:45]
	s_cbranch_execz .LBB0_1765
	v_min_u32_e32 v2, 0x31f, v2
	v_lshl_add_u32 v2, v2, 2, v157
	ds_read_b32 v121, v2
.LBB0_1765:
	s_or_b64 exec, exec, s[0:1]
	v_sub_u32_e32 v2, v222, v173
	v_cmp_lt_i32_e32 vcc, -1, v2
	s_and_b64 s[44:45], vcc, s[42:43]
	v_mov_b32_e32 v123, 0xf149f2ca
	v_mov_b32_e32 v122, 0xf149f2ca
	s_and_saveexec_b64 s[0:1], s[44:45]
	s_cbranch_execz .LBB0_1767
	v_min_u32_e32 v2, 0x31f, v2
	v_lshl_add_u32 v2, v2, 2, v157
	ds_read_b32 v122, v2
.LBB0_1767:
	s_or_b64 exec, exec, s[0:1]
	v_sub_u32_e32 v2, v223, v173
	v_cmp_lt_i32_e32 vcc, -1, v2
	s_and_b64 s[44:45], vcc, s[42:43]
	s_and_saveexec_b64 s[0:1], s[44:45]
	s_cbranch_execz .LBB0_1769
	v_min_u32_e32 v2, 0x31f, v2
	v_lshl_add_u32 v2, v2, 2, v157
	ds_read_b32 v123, v2
.LBB0_1769:
	s_or_b64 exec, exec, s[0:1]
	v_sub_u32_e32 v2, v224, v173
	v_cmp_lt_i32_e32 vcc, -1, v2
	s_and_b64 s[44:45], vcc, s[42:43]
	v_mov_b32_e32 v125, 0xf149f2ca
	v_mov_b32_e32 v124, 0xf149f2ca
	s_and_saveexec_b64 s[0:1], s[44:45]
	s_cbranch_execz .LBB0_1771
	v_min_u32_e32 v2, 0x31f, v2
	v_lshl_add_u32 v2, v2, 2, v157
	ds_read_b32 v124, v2
.LBB0_1771:
	s_or_b64 exec, exec, s[0:1]
	v_sub_u32_e32 v2, v225, v173
	v_cmp_lt_i32_e32 vcc, -1, v2
	s_and_b64 s[44:45], vcc, s[42:43]
	s_and_saveexec_b64 s[0:1], s[44:45]
	s_cbranch_execz .LBB0_1773
	v_min_u32_e32 v2, 0x31f, v2
	v_lshl_add_u32 v2, v2, 2, v157
	ds_read_b32 v125, v2
.LBB0_1773:
	s_or_b64 exec, exec, s[0:1]
	v_sub_u32_e32 v2, v226, v173
	v_cmp_lt_i32_e32 vcc, -1, v2
	s_and_b64 s[44:45], vcc, s[42:43]
	v_mov_b32_e32 v127, 0xf149f2ca
	v_mov_b32_e32 v126, 0xf149f2ca
	s_and_saveexec_b64 s[0:1], s[44:45]
	s_cbranch_execz .LBB0_1775
	v_min_u32_e32 v2, 0x31f, v2
	v_lshl_add_u32 v2, v2, 2, v157
	ds_read_b32 v126, v2
.LBB0_1775:
	s_or_b64 exec, exec, s[0:1]
	v_sub_u32_e32 v2, v227, v173
	v_cmp_lt_i32_e32 vcc, -1, v2
	s_and_b64 s[44:45], vcc, s[42:43]
	s_and_saveexec_b64 s[0:1], s[44:45]
	s_cbranch_execz .LBB0_1777
	v_min_u32_e32 v2, 0x31f, v2
	v_lshl_add_u32 v2, v2, 2, v157
	ds_read_b32 v127, v2
.LBB0_1777:
	s_or_b64 exec, exec, s[0:1]
	s_waitcnt lgkmcnt(0)
	v_fmac_f32_e32 v112, 0x3e38aa3b, v96
	v_fmac_f32_e32 v113, 0x3e38aa3b, v97
	v_fmac_f32_e32 v114, 0x3e38aa3b, v98
	v_fmac_f32_e32 v115, 0x3e38aa3b, v99
	v_fmac_f32_e32 v116, 0x3e38aa3b, v100
	v_fmac_f32_e32 v117, 0x3e38aa3b, v101
	v_fmac_f32_e32 v118, 0x3e38aa3b, v102
	v_fmac_f32_e32 v119, 0x3e38aa3b, v103
	v_fmac_f32_e32 v120, 0x3e38aa3b, v104
	v_fmac_f32_e32 v121, 0x3e38aa3b, v105
	v_fmac_f32_e32 v122, 0x3e38aa3b, v106
	v_fmac_f32_e32 v123, 0x3e38aa3b, v107
	v_fmac_f32_e32 v124, 0x3e38aa3b, v108
	v_fmac_f32_e32 v125, 0x3e38aa3b, v109
	v_fmac_f32_e32 v126, 0x3e38aa3b, v110
	v_fmac_f32_e32 v127, 0x3e38aa3b, v111
	s_mov_b64 s[0:1], 0
	s_waitcnt lgkmcnt(0)
	v_mov_b64_e32 v[2:3], v[0:1]
